# all 16-byte epilogue stores write-through sc1 (8-byte attention stores plain), plus phase-B rewrites
# baseline (speedup 1.0000x reference)
.LBB0_449:
	v_lshl_or_b32 v158, s90, 8, v192
	v_lshl_add_u32 v188, s91, 8, v190
	v_ashrrev_i32_e32 v159, 31, v158
	v_lshlrev_b64 v[202:203], 1, v[158:159]
	v_ashrrev_i32_e32 v189, 31, v188
	v_lshl_add_u64 v[160:161], s[94:95], 0, v[202:203]
	v_lshlrev_b64 v[162:163], 11, v[188:189]
	v_lshl_add_u64 v[114:115], v[160:161], 0, v[162:163]
	global_load_dwordx4 v[194:197], v[114:115], off
	global_load_dwordx4 v[198:201], v[114:115], off offset:256
	v_or_b32_e32 v114, 16, v188
	v_ashrrev_i32_e32 v115, 31, v114
	v_lshlrev_b64 v[186:187], 11, v[114:115]
	v_lshl_add_u64 v[114:115], v[160:161], 0, v[186:187]
	global_load_dwordx4 v[150:153], v[114:115], off
	global_load_dwordx4 v[146:149], v[114:115], off offset:256
	v_or_b32_e32 v114, 32, v188
	v_ashrrev_i32_e32 v115, 31, v114
	v_lshlrev_b64 v[184:185], 11, v[114:115]
	v_lshl_add_u64 v[114:115], v[160:161], 0, v[184:185]
	global_load_dwordx4 v[134:137], v[114:115], off
	global_load_dwordx4 v[130:133], v[114:115], off offset:256
	v_or_b32_e32 v114, 48, v188
	v_ashrrev_i32_e32 v115, 31, v114
	v_lshlrev_b64 v[182:183], 11, v[114:115]
	v_lshl_add_u64 v[114:115], v[160:161], 0, v[182:183]
	global_load_dwordx4 v[126:129], v[114:115], off
	s_nop 0
	global_load_dwordx4 v[114:117], v[114:115], off offset:256
	s_waitcnt vmcnt(0)
	v_lshlrev_b32_e32 v214, 16, v194
	v_add_f32_e32 v214, v142, v214
	v_and_b32_e32 v142, 0xffff0000, v194
	v_add_f32_e32 v194, v143, v142
	v_lshlrev_b32_e32 v142, 16, v195
	v_add_f32_e32 v144, v144, v142
	v_and_b32_e32 v142, 0xffff0000, v195
	v_add_f32_e32 v145, v145, v142
	v_lshlrev_b32_e32 v142, 16, v196
	v_add_f32_e32 v195, v138, v142
	v_and_b32_e32 v138, 0xffff0000, v196
	v_add_f32_e32 v196, v139, v138
	v_lshlrev_b32_e32 v138, 16, v197
	v_add_f32_e32 v215, v140, v138
	v_and_b32_e32 v138, 0xffff0000, v197
	v_lshl_add_u64 v[142:143], s[94:95], 0, v[162:163]
	v_add_f32_e32 v197, v141, v138
	v_cvt_pk_bf16_f32 v138, v214, v194
	v_lshl_add_u64 v[142:143], v[142:143], 0, v[202:203]
	v_cvt_pk_bf16_f32 v139, v144, v145
	v_cvt_pk_bf16_f32 v140, v195, v196
	v_cvt_pk_bf16_f32 v141, v215, v197
	global_store_dwordx4 v[142:143], v[138:141], off sc1
	s_nop 1
	v_mul_f32_e32 v138, v194, v194
	v_fmac_f32_e32 v138, v214, v214
	v_fmac_f32_e32 v138, v144, v144
	v_lshlrev_b32_e32 v139, 16, v198
	v_fmac_f32_e32 v138, v145, v145
	v_add_f32_e32 v122, v122, v139
	v_and_b32_e32 v139, 0xffff0000, v198
	v_fmac_f32_e32 v138, v195, v195
	v_add_f32_e32 v123, v123, v139
	v_lshlrev_b32_e32 v139, 16, v199
	v_fmac_f32_e32 v138, v196, v196
	v_add_f32_e32 v124, v124, v139
	v_and_b32_e32 v139, 0xffff0000, v199
	v_fmac_f32_e32 v138, v215, v215
	v_add_f32_e32 v125, v125, v139
	v_lshlrev_b32_e32 v139, 16, v200
	v_fmac_f32_e32 v138, v197, v197
	v_add_f32_e32 v139, v118, v139
	v_and_b32_e32 v118, 0xffff0000, v200
	v_add_f32_e32 v140, v119, v118
	v_lshlrev_b32_e32 v118, 16, v201
	v_fmac_f32_e32 v138, v122, v122
	v_add_f32_e32 v141, v120, v118
	v_and_b32_e32 v118, 0xffff0000, v201
	v_fmac_f32_e32 v138, v123, v123
	v_add_f32_e32 v144, v121, v118
	v_cvt_pk_bf16_f32 v118, v122, v123
	v_cvt_pk_bf16_f32 v119, v124, v125
	v_fmac_f32_e32 v138, v124, v124
	v_cvt_pk_bf16_f32 v120, v139, v140
	v_cvt_pk_bf16_f32 v121, v141, v144
	global_store_dwordx4 v[142:143], v[118:121], off offset:256 sc1
	v_fmac_f32_e32 v138, v125, v125
	v_fmac_f32_e32 v138, v139, v139
	v_and_b32_e32 v119, 64, v206
	v_xor_b32_e32 v118, 16, v206
	v_add_u32_e32 v119, 64, v119
	v_fmac_f32_e32 v138, v140, v140
	v_cmp_lt_i32_e32 vcc, v118, v119
	v_fmac_f32_e32 v138, v141, v141
	v_fmac_f32_e32 v138, v144, v144
	v_cndmask_b32_e32 v118, v206, v118, vcc
	v_lshlrev_b32_e32 v120, 2, v118
	ds_bpermute_b32 v118, v120, v138
	s_waitcnt lgkmcnt(0)
	v_add_f32_e32 v122, v138, v118
	v_xor_b32_e32 v118, 32, v206
	v_cmp_lt_i32_e32 vcc, v118, v119
	s_nop 1
	v_cndmask_b32_e32 v118, v206, v118, vcc
	v_lshlrev_b32_e32 v121, 2, v118
	ds_bpermute_b32 v123, v121, v122
	v_lshl_add_u64 v[118:119], v[188:189], 3, s[6:7]
	s_and_saveexec_b64 s[56:57], s[52:53]
	s_mov_b64 s[86:87], 0x30080
	s_cbranch_execz .LBB0_451
	s_waitcnt lgkmcnt(0)
	v_add_f32_e32 v122, v122, v123
	v_mul_f32_e32 v122, 0x4d800000, v122
	v_trunc_f32_e32 v122, v122
	v_mul_f32_e32 v123, 0x2f800000, v122
	v_floor_f32_e32 v123, v123
	v_fmac_f32_e32 v122, 0xcf800000, v123
	v_cvt_u32_f32_e32 v122, v122
	v_cvt_u32_f32_e32 v123, v123
	global_atomic_add_x2 v[118:119], v[122:123], off
.LBB0_451:
	s_or_b64 exec, exec, s[56:57]
	v_lshlrev_b32_e32 v122, 16, v150
	v_add_f32_e32 v110, v110, v122
	v_and_b32_e32 v122, 0xffff0000, v150
	v_add_f32_e32 v111, v111, v122
	v_lshlrev_b32_e32 v122, 16, v151
	v_add_f32_e32 v112, v112, v122
	v_and_b32_e32 v122, 0xffff0000, v151
	v_add_f32_e32 v113, v113, v122
	v_lshlrev_b32_e32 v122, 16, v152
	v_add_f32_e32 v122, v106, v122
	v_and_b32_e32 v106, 0xffff0000, v152
	s_waitcnt lgkmcnt(0)
	v_add_f32_e32 v123, v107, v106
	v_lshlrev_b32_e32 v106, 16, v153
	v_add_f32_e32 v124, v108, v106
	v_and_b32_e32 v106, 0xffff0000, v153
	v_add_f32_e32 v125, v109, v106
	v_cvt_pk_bf16_f32 v106, v110, v111
	v_mul_f32_e32 v111, v111, v111
	v_fmac_f32_e32 v111, v110, v110
	v_fmac_f32_e32 v111, v112, v112
	v_fmac_f32_e32 v111, v113, v113
	v_fmac_f32_e32 v111, v122, v122
	v_fmac_f32_e32 v111, v123, v123
	v_fmac_f32_e32 v111, v124, v124
	v_lshlrev_b32_e32 v110, 16, v146
	v_fmac_f32_e32 v111, v125, v125
	v_add_f32_e32 v102, v102, v110
	v_and_b32_e32 v110, 0xffff0000, v146
	v_add_f32_e32 v103, v103, v110
	v_lshlrev_b32_e32 v110, 16, v147
	v_fmac_f32_e32 v111, v102, v102
	v_add_f32_e32 v110, v104, v110
	v_and_b32_e32 v104, 0xffff0000, v147
	v_fmac_f32_e32 v111, v103, v103
	v_cvt_pk_bf16_f32 v107, v112, v113
	v_add_f32_e32 v112, v105, v104
	v_lshlrev_b32_e32 v104, 16, v148
	v_fmac_f32_e32 v111, v110, v110
	v_add_f32_e32 v113, v98, v104
	v_and_b32_e32 v98, 0xffff0000, v148
	v_fmac_f32_e32 v111, v112, v112
	v_cvt_pk_bf16_f32 v108, v122, v123
	v_add_f32_e32 v122, v99, v98
	v_lshlrev_b32_e32 v98, 16, v149
	v_fmac_f32_e32 v111, v113, v113
	v_add_f32_e32 v123, v100, v98
	v_and_b32_e32 v98, 0xffff0000, v149
	v_fmac_f32_e32 v111, v122, v122
	v_cvt_pk_bf16_f32 v109, v124, v125
	v_add_f32_e32 v124, v101, v98
	v_fmac_f32_e32 v111, v123, v123
	v_fmac_f32_e32 v111, v124, v124
	ds_bpermute_b32 v101, v120, v111
	v_lshl_add_u64 v[98:99], s[94:95], 0, v[186:187]
	v_lshl_add_u64 v[104:105], v[158:159], 1, v[98:99]
	global_store_dwordx4 v[104:105], v[106:109], off sc1
	v_cvt_pk_bf16_f32 v100, v102, v103
	s_waitcnt lgkmcnt(0)
	v_add_f32_e32 v98, v111, v101
	ds_bpermute_b32 v99, v121, v98
	v_cvt_pk_bf16_f32 v101, v110, v112
	v_cvt_pk_bf16_f32 v102, v113, v122
	v_cvt_pk_bf16_f32 v103, v123, v124
	global_store_dwordx4 v[104:105], v[100:103], off offset:256 sc1
	s_and_saveexec_b64 s[56:57], s[52:53]
	s_cbranch_execz .LBB0_453
	s_waitcnt lgkmcnt(0)
	v_add_f32_e32 v98, v98, v99
	v_mul_f32_e32 v98, 0x4d800000, v98
	v_trunc_f32_e32 v98, v98
	v_mul_f32_e32 v99, 0x2f800000, v98
	v_floor_f32_e32 v99, v99
	v_fmac_f32_e32 v98, 0xcf800000, v99
	v_cvt_u32_f32_e32 v98, v98
	v_cvt_u32_f32_e32 v99, v99
	global_atomic_add_x2 v[118:119], v[98:99], off offset:128
.LBB0_453:
	s_or_b64 exec, exec, s[56:57]
	v_lshlrev_b32_e32 v98, 16, v134
	v_add_f32_e32 v94, v94, v98
	v_and_b32_e32 v98, 0xffff0000, v134
	v_add_f32_e32 v95, v95, v98
	v_lshlrev_b32_e32 v98, 16, v135
	v_add_f32_e32 v96, v96, v98
	v_and_b32_e32 v98, 0xffff0000, v135
	v_add_f32_e32 v97, v97, v98
	v_lshlrev_b32_e32 v98, 16, v136
	v_add_f32_e32 v98, v90, v98
	v_and_b32_e32 v90, 0xffff0000, v136
	s_waitcnt lgkmcnt(0)
	v_add_f32_e32 v99, v91, v90
	v_lshlrev_b32_e32 v90, 16, v137
	v_add_f32_e32 v100, v92, v90
	v_and_b32_e32 v90, 0xffff0000, v137
	v_add_f32_e32 v101, v93, v90
	v_cvt_pk_bf16_f32 v90, v94, v95
	v_mul_f32_e32 v95, v95, v95
	v_fmac_f32_e32 v95, v94, v94
	v_fmac_f32_e32 v95, v96, v96
	v_fmac_f32_e32 v95, v97, v97
	v_fmac_f32_e32 v95, v98, v98
	v_fmac_f32_e32 v95, v99, v99
	v_fmac_f32_e32 v95, v100, v100
	v_lshlrev_b32_e32 v94, 16, v130
	v_fmac_f32_e32 v95, v101, v101
	v_add_f32_e32 v86, v86, v94
	v_and_b32_e32 v94, 0xffff0000, v130
	v_add_f32_e32 v87, v87, v94
	v_lshlrev_b32_e32 v94, 16, v131
	v_fmac_f32_e32 v95, v86, v86
	v_add_f32_e32 v94, v88, v94
	v_and_b32_e32 v88, 0xffff0000, v131
	v_fmac_f32_e32 v95, v87, v87
	v_cvt_pk_bf16_f32 v91, v96, v97
	v_add_f32_e32 v96, v89, v88
	v_lshlrev_b32_e32 v88, 16, v132
	v_fmac_f32_e32 v95, v94, v94
	v_add_f32_e32 v97, v82, v88
	v_and_b32_e32 v82, 0xffff0000, v132
	v_fmac_f32_e32 v95, v96, v96
	v_cvt_pk_bf16_f32 v92, v98, v99
	v_add_f32_e32 v98, v83, v82
	v_lshlrev_b32_e32 v82, 16, v133
	v_fmac_f32_e32 v95, v97, v97
	v_add_f32_e32 v99, v84, v82
	v_and_b32_e32 v82, 0xffff0000, v133
	v_fmac_f32_e32 v95, v98, v98
	v_cvt_pk_bf16_f32 v93, v100, v101
	v_add_f32_e32 v100, v85, v82
	v_fmac_f32_e32 v95, v99, v99
	v_fmac_f32_e32 v95, v100, v100
	ds_bpermute_b32 v85, v120, v95
	v_lshl_add_u64 v[82:83], s[94:95], 0, v[184:185]
	v_lshl_add_u64 v[88:89], v[158:159], 1, v[82:83]
	global_store_dwordx4 v[88:89], v[90:93], off sc1
	v_cvt_pk_bf16_f32 v84, v86, v87
	s_waitcnt lgkmcnt(0)
	v_add_f32_e32 v82, v95, v85
	ds_bpermute_b32 v83, v121, v82
	v_cvt_pk_bf16_f32 v85, v94, v96
	v_cvt_pk_bf16_f32 v86, v97, v98
	v_cvt_pk_bf16_f32 v87, v99, v100
	global_store_dwordx4 v[88:89], v[84:87], off offset:256 sc1
	s_and_saveexec_b64 s[56:57], s[52:53]
	s_cbranch_execz .LBB0_455
	s_waitcnt lgkmcnt(0)
	v_add_f32_e32 v82, v82, v83
	v_mul_f32_e32 v82, 0x4d800000, v82
	v_trunc_f32_e32 v82, v82
	v_mul_f32_e32 v83, 0x2f800000, v82
	v_floor_f32_e32 v83, v83
	v_fmac_f32_e32 v82, 0xcf800000, v83
	v_cvt_u32_f32_e32 v82, v82
	v_cvt_u32_f32_e32 v83, v83
	global_atomic_add_x2 v[118:119], v[82:83], off offset:256
.LBB0_455:
	s_or_b64 exec, exec, s[56:57]
	v_lshlrev_b32_e32 v82, 16, v126
	v_add_f32_e32 v78, v78, v82
	v_and_b32_e32 v82, 0xffff0000, v126
	v_add_f32_e32 v79, v79, v82
	v_lshlrev_b32_e32 v82, 16, v127
	v_add_f32_e32 v80, v80, v82
	v_and_b32_e32 v82, 0xffff0000, v127
	v_add_f32_e32 v81, v81, v82
	v_lshlrev_b32_e32 v82, 16, v128
	v_add_f32_e32 v82, v74, v82
	v_and_b32_e32 v74, 0xffff0000, v128
	s_waitcnt lgkmcnt(0)
	v_add_f32_e32 v83, v75, v74
	v_lshlrev_b32_e32 v74, 16, v129
	v_add_f32_e32 v84, v76, v74
	v_and_b32_e32 v74, 0xffff0000, v129
	v_add_f32_e32 v85, v77, v74
	v_cvt_pk_bf16_f32 v74, v78, v79
	v_mul_f32_e32 v79, v79, v79
	v_fmac_f32_e32 v79, v78, v78
	v_fmac_f32_e32 v79, v80, v80
	v_fmac_f32_e32 v79, v81, v81
	v_fmac_f32_e32 v79, v82, v82
	v_fmac_f32_e32 v79, v83, v83
	v_fmac_f32_e32 v79, v84, v84
	v_lshlrev_b32_e32 v78, 16, v114
	v_fmac_f32_e32 v79, v85, v85
	v_add_f32_e32 v70, v70, v78
	v_and_b32_e32 v78, 0xffff0000, v114
	v_add_f32_e32 v71, v71, v78
	v_lshlrev_b32_e32 v78, 16, v115
	v_fmac_f32_e32 v79, v70, v70
	v_add_f32_e32 v78, v72, v78
	v_and_b32_e32 v72, 0xffff0000, v115
	v_fmac_f32_e32 v79, v71, v71
	v_cvt_pk_bf16_f32 v75, v80, v81
	v_add_f32_e32 v80, v73, v72
	v_lshlrev_b32_e32 v72, 16, v116
	v_fmac_f32_e32 v79, v78, v78
	v_add_f32_e32 v81, v66, v72
	v_and_b32_e32 v66, 0xffff0000, v116
	v_fmac_f32_e32 v79, v80, v80
	v_cvt_pk_bf16_f32 v76, v82, v83
	v_add_f32_e32 v82, v67, v66
	v_lshlrev_b32_e32 v66, 16, v117
	v_fmac_f32_e32 v79, v81, v81
	v_add_f32_e32 v83, v68, v66
	v_and_b32_e32 v66, 0xffff0000, v117
	v_fmac_f32_e32 v79, v82, v82
	v_cvt_pk_bf16_f32 v77, v84, v85
	v_add_f32_e32 v84, v69, v66
	v_fmac_f32_e32 v79, v83, v83
	v_fmac_f32_e32 v79, v84, v84
	ds_bpermute_b32 v69, v120, v79
	v_lshl_add_u64 v[66:67], s[94:95], 0, v[182:183]
	v_lshl_add_u64 v[72:73], v[158:159], 1, v[66:67]
	global_store_dwordx4 v[72:73], v[74:77], off sc1
	v_cvt_pk_bf16_f32 v68, v70, v71
	s_waitcnt lgkmcnt(0)
	v_add_f32_e32 v66, v79, v69
	ds_bpermute_b32 v67, v121, v66
	v_cvt_pk_bf16_f32 v69, v78, v80
	v_cvt_pk_bf16_f32 v70, v81, v82
	v_cvt_pk_bf16_f32 v71, v83, v84
	global_store_dwordx4 v[72:73], v[68:71], off offset:256 sc1
	s_and_saveexec_b64 s[56:57], s[52:53]
	s_cbranch_execz .LBB0_457
	s_waitcnt lgkmcnt(0)
	v_add_f32_e32 v66, v66, v67
	v_mul_f32_e32 v66, 0x4d800000, v66
	v_trunc_f32_e32 v66, v66
	v_mul_f32_e32 v67, 0x2f800000, v66
	v_floor_f32_e32 v67, v67
	v_fmac_f32_e32 v66, 0xcf800000, v67
	v_cvt_u32_f32_e32 v66, v66
	v_cvt_u32_f32_e32 v67, v67
	global_atomic_add_x2 v[118:119], v[66:67], off offset:384
.LBB0_457:
	s_or_b64 exec, exec, s[56:57]
	v_lshl_add_u64 v[104:105], v[162:163], 0, s[28:29]
	s_waitcnt lgkmcnt(0)
	v_lshl_add_u64 v[66:67], v[160:161], 0, v[104:105]
	global_load_dwordx4 v[96:99], v[66:67], off
	global_load_dwordx4 v[100:103], v[66:67], off offset:256
	s_mov_b64 s[0:1], 0x48000
	v_lshl_add_u64 v[94:95], v[162:163], 0, s[0:1]
	s_mov_b64 s[0:1], 0x50000
	v_lshl_add_u64 v[66:67], v[160:161], 0, v[94:95]
	v_lshl_add_u64 v[92:93], v[162:163], 0, s[0:1]
	global_load_dwordx4 v[86:89], v[66:67], off
	global_load_dwordx4 v[82:85], v[66:67], off offset:256
	v_lshl_add_u64 v[66:67], v[160:161], 0, v[92:93]
	v_lshl_add_u64 v[90:91], v[162:163], 0, s[2:3]
	global_load_dwordx4 v[78:81], v[66:67], off
	global_load_dwordx4 v[74:77], v[66:67], off offset:256
	v_lshl_add_u64 v[66:67], v[160:161], 0, v[90:91]
	global_load_dwordx4 v[70:73], v[66:67], off
	s_nop 0
	global_load_dwordx4 v[66:69], v[66:67], off offset:256
	s_waitcnt vmcnt(7)
	v_lshlrev_b32_e32 v106, 16, v96
	v_add_f32_e32 v106, v62, v106
	v_and_b32_e32 v62, 0xffff0000, v96
	v_add_f32_e32 v96, v63, v62
	v_lshlrev_b32_e32 v62, 16, v97
	v_add_f32_e32 v64, v64, v62
	v_and_b32_e32 v62, 0xffff0000, v97
	v_add_f32_e32 v65, v65, v62
	v_lshlrev_b32_e32 v62, 16, v98
	v_add_f32_e32 v97, v58, v62
	v_and_b32_e32 v58, 0xffff0000, v98
	v_add_f32_e32 v98, v59, v58
	v_lshlrev_b32_e32 v58, 16, v99
	v_add_f32_e32 v107, v60, v58
	v_and_b32_e32 v58, 0xffff0000, v99
	v_lshl_add_u64 v[62:63], s[94:95], 0, v[104:105]
	v_add_f32_e32 v99, v61, v58
	v_cvt_pk_bf16_f32 v58, v106, v96
	v_lshl_add_u64 v[62:63], v[158:159], 1, v[62:63]
	v_cvt_pk_bf16_f32 v59, v64, v65
	v_cvt_pk_bf16_f32 v60, v97, v98
	v_cvt_pk_bf16_f32 v61, v107, v99
	global_store_dwordx4 v[62:63], v[58:61], off sc1
	s_nop 1
	v_mul_f32_e32 v58, v96, v96
	v_fmac_f32_e32 v58, v106, v106
	v_fmac_f32_e32 v58, v64, v64
	v_fmac_f32_e32 v58, v65, v65
	v_fmac_f32_e32 v58, v97, v97
	v_fmac_f32_e32 v58, v98, v98
	v_fmac_f32_e32 v58, v107, v107
	s_waitcnt vmcnt(7)
	v_lshlrev_b32_e32 v59, 16, v100
	v_fmac_f32_e32 v58, v99, v99
	v_add_f32_e32 v54, v54, v59
	v_and_b32_e32 v59, 0xffff0000, v100
	v_add_f32_e32 v55, v55, v59
	v_lshlrev_b32_e32 v59, 16, v101
	v_fmac_f32_e32 v58, v54, v54
	v_add_f32_e32 v56, v56, v59
	v_and_b32_e32 v59, 0xffff0000, v101
	v_fmac_f32_e32 v58, v55, v55
	v_add_f32_e32 v57, v57, v59
	v_lshlrev_b32_e32 v59, 16, v102
	v_fmac_f32_e32 v58, v56, v56
	v_add_f32_e32 v59, v50, v59
	v_and_b32_e32 v50, 0xffff0000, v102
	v_fmac_f32_e32 v58, v57, v57
	v_add_f32_e32 v60, v51, v50
	v_lshlrev_b32_e32 v50, 16, v103
	v_fmac_f32_e32 v58, v59, v59
	v_add_f32_e32 v61, v52, v50
	v_and_b32_e32 v50, 0xffff0000, v103
	v_fmac_f32_e32 v58, v60, v60
	v_add_f32_e32 v64, v53, v50
	v_fmac_f32_e32 v58, v61, v61
	v_cvt_pk_bf16_f32 v50, v54, v55
	v_fmac_f32_e32 v58, v64, v64
	v_cvt_pk_bf16_f32 v51, v56, v57
	v_cvt_pk_bf16_f32 v52, v59, v60
	v_cvt_pk_bf16_f32 v53, v61, v64
	global_store_dwordx4 v[62:63], v[50:53], off offset:256 sc1
	ds_bpermute_b32 v50, v120, v58
	s_waitcnt lgkmcnt(0)
	v_add_f32_e32 v50, v58, v50
	ds_bpermute_b32 v51, v121, v50
	s_and_saveexec_b64 s[56:57], s[52:53]
	s_cbranch_execz .LBB0_459
	s_waitcnt lgkmcnt(0)
	v_add_f32_e32 v50, v50, v51
	v_mul_f32_e32 v50, 0x4d800000, v50
	v_trunc_f32_e32 v50, v50
	v_mul_f32_e32 v51, 0x2f800000, v50
	v_floor_f32_e32 v51, v51
	v_fmac_f32_e32 v50, 0xcf800000, v51
	v_cvt_u32_f32_e32 v50, v50
	v_cvt_u32_f32_e32 v51, v51
	global_atomic_add_x2 v[118:119], v[50:51], off offset:1024
.LBB0_459:
	s_or_b64 exec, exec, s[56:57]
	s_waitcnt vmcnt(7)
	v_lshlrev_b32_e32 v50, 16, v86
	v_add_f32_e32 v46, v46, v50
	v_and_b32_e32 v50, 0xffff0000, v86
	v_add_f32_e32 v47, v47, v50
	v_lshlrev_b32_e32 v50, 16, v87
	v_add_f32_e32 v48, v48, v50
	v_and_b32_e32 v50, 0xffff0000, v87
	v_add_f32_e32 v49, v49, v50
	v_lshlrev_b32_e32 v50, 16, v88
	v_add_f32_e32 v50, v42, v50
	v_and_b32_e32 v42, 0xffff0000, v88
	s_waitcnt lgkmcnt(0)
	v_add_f32_e32 v51, v43, v42
	v_lshlrev_b32_e32 v42, 16, v89
	v_add_f32_e32 v52, v44, v42
	v_and_b32_e32 v42, 0xffff0000, v89
	v_add_f32_e32 v53, v45, v42
	v_cvt_pk_bf16_f32 v42, v46, v47
	v_mul_f32_e32 v47, v47, v47
	v_fmac_f32_e32 v47, v46, v46
	v_fmac_f32_e32 v47, v48, v48
	v_fmac_f32_e32 v47, v49, v49
	v_fmac_f32_e32 v47, v50, v50
	v_fmac_f32_e32 v47, v51, v51
	v_fmac_f32_e32 v47, v52, v52
	s_waitcnt vmcnt(6)
	v_lshlrev_b32_e32 v46, 16, v82
	v_fmac_f32_e32 v47, v53, v53
	v_add_f32_e32 v38, v38, v46
	v_and_b32_e32 v46, 0xffff0000, v82
	v_add_f32_e32 v39, v39, v46
	v_lshlrev_b32_e32 v46, 16, v83
	v_fmac_f32_e32 v47, v38, v38
	v_add_f32_e32 v46, v40, v46
	v_and_b32_e32 v40, 0xffff0000, v83
	v_fmac_f32_e32 v47, v39, v39
	v_cvt_pk_bf16_f32 v43, v48, v49
	v_add_f32_e32 v48, v41, v40
	v_lshlrev_b32_e32 v40, 16, v84
	v_fmac_f32_e32 v47, v46, v46
	v_add_f32_e32 v49, v34, v40
	v_and_b32_e32 v34, 0xffff0000, v84
	v_fmac_f32_e32 v47, v48, v48
	v_cvt_pk_bf16_f32 v44, v50, v51
	v_add_f32_e32 v50, v35, v34
	v_lshlrev_b32_e32 v34, 16, v85
	v_fmac_f32_e32 v47, v49, v49
	v_add_f32_e32 v51, v36, v34
	v_and_b32_e32 v34, 0xffff0000, v85
	v_fmac_f32_e32 v47, v50, v50
	v_cvt_pk_bf16_f32 v45, v52, v53
	v_add_f32_e32 v52, v37, v34
	v_fmac_f32_e32 v47, v51, v51
	v_fmac_f32_e32 v47, v52, v52
	ds_bpermute_b32 v37, v120, v47
	v_lshl_add_u64 v[34:35], s[94:95], 0, v[94:95]
	v_lshl_add_u64 v[40:41], v[158:159], 1, v[34:35]
	global_store_dwordx4 v[40:41], v[42:45], off sc1
	v_cvt_pk_bf16_f32 v36, v38, v39
	s_waitcnt lgkmcnt(0)
	v_add_f32_e32 v34, v47, v37
	ds_bpermute_b32 v35, v121, v34
	v_cvt_pk_bf16_f32 v37, v46, v48
	v_cvt_pk_bf16_f32 v38, v49, v50
	v_cvt_pk_bf16_f32 v39, v51, v52
	global_store_dwordx4 v[40:41], v[36:39], off offset:256 sc1
	s_and_saveexec_b64 s[56:57], s[52:53]
	s_cbranch_execz .LBB0_461
	s_waitcnt lgkmcnt(0)
	v_add_f32_e32 v34, v34, v35
	v_mul_f32_e32 v34, 0x4d800000, v34
	v_trunc_f32_e32 v34, v34
	v_mul_f32_e32 v35, 0x2f800000, v34
	v_floor_f32_e32 v35, v35
	v_fmac_f32_e32 v34, 0xcf800000, v35
	v_cvt_u32_f32_e32 v34, v34
	v_cvt_u32_f32_e32 v35, v35
	global_atomic_add_x2 v[118:119], v[34:35], off offset:1152
.LBB0_461:
	s_or_b64 exec, exec, s[56:57]
	s_waitcnt vmcnt(7)
	v_lshlrev_b32_e32 v34, 16, v78
	v_add_f32_e32 v30, v30, v34
	v_and_b32_e32 v34, 0xffff0000, v78
	v_add_f32_e32 v31, v31, v34
	v_lshlrev_b32_e32 v34, 16, v79
	v_add_f32_e32 v32, v32, v34
	v_and_b32_e32 v34, 0xffff0000, v79
	v_add_f32_e32 v33, v33, v34
	v_lshlrev_b32_e32 v34, 16, v80
	v_add_f32_e32 v34, v26, v34
	v_and_b32_e32 v26, 0xffff0000, v80
	s_waitcnt lgkmcnt(0)
	v_add_f32_e32 v35, v27, v26
	v_lshlrev_b32_e32 v26, 16, v81
	v_add_f32_e32 v36, v28, v26
	v_and_b32_e32 v26, 0xffff0000, v81
	v_add_f32_e32 v37, v29, v26
	v_cvt_pk_bf16_f32 v26, v30, v31
	v_mul_f32_e32 v31, v31, v31
	v_fmac_f32_e32 v31, v30, v30
	v_fmac_f32_e32 v31, v32, v32
	v_fmac_f32_e32 v31, v33, v33
	v_fmac_f32_e32 v31, v34, v34
	v_fmac_f32_e32 v31, v35, v35
	v_fmac_f32_e32 v31, v36, v36
	s_waitcnt vmcnt(6)
	v_lshlrev_b32_e32 v30, 16, v74
	v_fmac_f32_e32 v31, v37, v37
	v_add_f32_e32 v22, v22, v30
	v_and_b32_e32 v30, 0xffff0000, v74
	v_add_f32_e32 v23, v23, v30
	v_lshlrev_b32_e32 v30, 16, v75
	v_fmac_f32_e32 v31, v22, v22
	v_add_f32_e32 v30, v24, v30
	v_and_b32_e32 v24, 0xffff0000, v75
	v_fmac_f32_e32 v31, v23, v23
	v_cvt_pk_bf16_f32 v27, v32, v33
	v_add_f32_e32 v32, v25, v24
	v_lshlrev_b32_e32 v24, 16, v76
	v_fmac_f32_e32 v31, v30, v30
	v_add_f32_e32 v33, v18, v24
	v_and_b32_e32 v18, 0xffff0000, v76
	v_fmac_f32_e32 v31, v32, v32
	v_cvt_pk_bf16_f32 v28, v34, v35
	v_add_f32_e32 v34, v19, v18
	v_lshlrev_b32_e32 v18, 16, v77
	v_fmac_f32_e32 v31, v33, v33
	v_add_f32_e32 v35, v20, v18
	v_and_b32_e32 v18, 0xffff0000, v77
	v_fmac_f32_e32 v31, v34, v34
	v_cvt_pk_bf16_f32 v29, v36, v37
	v_add_f32_e32 v36, v21, v18
	v_fmac_f32_e32 v31, v35, v35
	v_fmac_f32_e32 v31, v36, v36
	ds_bpermute_b32 v21, v120, v31
	v_lshl_add_u64 v[18:19], s[94:95], 0, v[92:93]
	v_lshl_add_u64 v[24:25], v[158:159], 1, v[18:19]
	global_store_dwordx4 v[24:25], v[26:29], off sc1
	v_cvt_pk_bf16_f32 v20, v22, v23
	s_waitcnt lgkmcnt(0)
	v_add_f32_e32 v18, v31, v21
	ds_bpermute_b32 v19, v121, v18
	v_cvt_pk_bf16_f32 v21, v30, v32
	v_cvt_pk_bf16_f32 v22, v33, v34
	v_cvt_pk_bf16_f32 v23, v35, v36
	global_store_dwordx4 v[24:25], v[20:23], off offset:256 sc1
	s_and_saveexec_b64 s[56:57], s[52:53]
	s_cbranch_execz .LBB0_463
	s_waitcnt lgkmcnt(0)
	v_add_f32_e32 v18, v18, v19
	v_mul_f32_e32 v18, 0x4d800000, v18
	v_trunc_f32_e32 v18, v18
	v_mul_f32_e32 v19, 0x2f800000, v18
	v_floor_f32_e32 v19, v19
	v_fmac_f32_e32 v18, 0xcf800000, v19
	v_cvt_u32_f32_e32 v18, v18
	v_cvt_u32_f32_e32 v19, v19
	global_atomic_add_x2 v[118:119], v[18:19], off offset:1280
.LBB0_463:
	s_or_b64 exec, exec, s[56:57]
	s_waitcnt vmcnt(7)
	v_lshlrev_b32_e32 v18, 16, v70
	v_add_f32_e32 v14, v14, v18
	v_and_b32_e32 v18, 0xffff0000, v70
	v_add_f32_e32 v15, v15, v18
	v_lshlrev_b32_e32 v18, 16, v71
	v_add_f32_e32 v16, v16, v18
	v_and_b32_e32 v18, 0xffff0000, v71
	v_add_f32_e32 v17, v17, v18
	v_lshlrev_b32_e32 v18, 16, v72
	v_add_f32_e32 v18, v10, v18
	v_and_b32_e32 v10, 0xffff0000, v72
	s_waitcnt lgkmcnt(0)
	v_add_f32_e32 v19, v11, v10
	v_lshlrev_b32_e32 v10, 16, v73
	v_add_f32_e32 v20, v12, v10
	v_and_b32_e32 v10, 0xffff0000, v73
	v_add_f32_e32 v21, v13, v10
	v_cvt_pk_bf16_f32 v10, v14, v15
	v_mul_f32_e32 v15, v15, v15
	v_fmac_f32_e32 v15, v14, v14
	v_fmac_f32_e32 v15, v16, v16
	v_fmac_f32_e32 v15, v17, v17
	v_fmac_f32_e32 v15, v18, v18
	v_fmac_f32_e32 v15, v19, v19
	v_fmac_f32_e32 v15, v20, v20
	s_waitcnt vmcnt(6)
	v_lshlrev_b32_e32 v14, 16, v66
	v_fmac_f32_e32 v15, v21, v21
	v_add_f32_e32 v6, v6, v14
	v_and_b32_e32 v14, 0xffff0000, v66
	v_add_f32_e32 v7, v7, v14
	v_lshlrev_b32_e32 v14, 16, v67
	v_fmac_f32_e32 v15, v6, v6
	v_add_f32_e32 v14, v8, v14
	v_and_b32_e32 v8, 0xffff0000, v67
	v_fmac_f32_e32 v15, v7, v7
	v_cvt_pk_bf16_f32 v11, v16, v17
	v_add_f32_e32 v16, v9, v8
	v_lshlrev_b32_e32 v8, 16, v68
	v_fmac_f32_e32 v15, v14, v14
	v_add_f32_e32 v17, v2, v8
	v_and_b32_e32 v2, 0xffff0000, v68
	v_fmac_f32_e32 v15, v16, v16
	v_cvt_pk_bf16_f32 v12, v18, v19
	v_add_f32_e32 v18, v3, v2
	v_lshlrev_b32_e32 v2, 16, v69
	v_fmac_f32_e32 v15, v17, v17
	v_add_f32_e32 v19, v4, v2
	v_and_b32_e32 v2, 0xffff0000, v69
	v_fmac_f32_e32 v15, v18, v18
	v_cvt_pk_bf16_f32 v13, v20, v21
	v_add_f32_e32 v20, v5, v2
	v_fmac_f32_e32 v15, v19, v19
	v_fmac_f32_e32 v15, v20, v20
	ds_bpermute_b32 v5, v120, v15
	v_lshl_add_u64 v[2:3], s[94:95], 0, v[90:91]
	v_lshl_add_u64 v[8:9], v[158:159], 1, v[2:3]
	global_store_dwordx4 v[8:9], v[10:13], off sc1
	v_cvt_pk_bf16_f32 v4, v6, v7
	s_waitcnt lgkmcnt(0)
	v_add_f32_e32 v2, v15, v5
	ds_bpermute_b32 v3, v121, v2
	v_cvt_pk_bf16_f32 v5, v14, v16
	v_cvt_pk_bf16_f32 v6, v17, v18
	v_cvt_pk_bf16_f32 v7, v19, v20
	global_store_dwordx4 v[8:9], v[4:7], off offset:256 sc1
	s_and_saveexec_b64 s[56:57], s[52:53]
	s_cbranch_execz .LBB0_465
	s_waitcnt lgkmcnt(0)
	v_add_f32_e32 v2, v2, v3
	v_mul_f32_e32 v2, 0x4d800000, v2
	v_trunc_f32_e32 v2, v2
	v_mul_f32_e32 v3, 0x2f800000, v2
	v_floor_f32_e32 v3, v3
	v_fmac_f32_e32 v2, 0xcf800000, v3
	v_cvt_u32_f32_e32 v2, v2
	v_cvt_u32_f32_e32 v3, v3
	global_atomic_add_x2 v[118:119], v[2:3], off offset:1408

.LBB0_567:
	v_lshl_or_b32 v2, s84, 8, v217
	v_lshl_add_u32 v190, s85, 8, v214
	v_ashrrev_i32_e32 v3, 31, v2
	v_lshlrev_b64 v[228:229], 1, v[2:3]
	v_ashrrev_i32_e32 v191, 31, v190
	v_lshl_add_u64 v[188:189], s[4:5], 0, v[228:229]
	v_lshlrev_b64 v[230:231], 11, v[190:191]
	v_lshl_add_u64 v[116:117], v[188:189], 0, v[230:231]
	global_load_dwordx4 v[220:223], v[116:117], off
	global_load_dwordx4 v[224:227], v[116:117], off offset:256
	v_or_b32_e32 v200, 16, v190
	v_ashrrev_i32_e32 v201, 31, v200
	v_or_b32_e32 v196, 32, v190
	v_or_b32_e32 v192, 48, v190
	v_lshlrev_b64 v[202:203], 11, v[200:201]
	v_ashrrev_i32_e32 v197, 31, v196
	v_ashrrev_i32_e32 v193, 31, v192
	v_lshl_add_u64 v[116:117], v[188:189], 0, v[202:203]
	v_lshlrev_b64 v[198:199], 11, v[196:197]
	v_lshlrev_b64 v[194:195], 11, v[192:193]
	s_waitcnt vmcnt(0)
	ds_read2_b64 v[152:155], v219 offset1:16
	global_load_dwordx4 v[160:163], v[116:117], off
	global_load_dwordx4 v[156:159], v[116:117], off offset:256
	v_lshl_add_u64 v[116:117], v[188:189], 0, v[198:199]
	v_lshl_add_u64 v[120:121], v[188:189], 0, v[194:195]
	global_load_dwordx4 v[148:151], v[116:117], off
	global_load_dwordx4 v[132:135], v[116:117], off offset:256
	ds_read2_b64 v[116:119], v219 offset0:32 offset1:48
	global_load_dwordx4 v[124:127], v[120:121], off
	s_nop 0
	global_load_dwordx4 v[120:123], v[120:121], off offset:256
	s_waitcnt lgkmcnt(0)
	v_lshlrev_b32_e32 v118, 16, v221
	v_and_b32_e32 v116, 0xffff0000, v220
	v_fmac_f32_e32 v118, v146, v153
	v_and_b32_e32 v146, 0xffff0000, v221
	v_lshlrev_b32_e32 v0, 16, v220
	v_fmac_f32_e32 v116, v145, v153
	v_fmac_f32_e32 v146, v147, v153
	v_lshlrev_b32_e32 v147, 16, v222
	v_fmac_f32_e32 v0, v144, v153
	v_fmac_f32_e32 v147, v140, v153
	v_cvt_pk_bf16_f32 v140, v0, v116
	v_mul_f32_e32 v116, v116, v116
	v_fmac_f32_e32 v116, v0, v0
	v_fmac_f32_e32 v116, v118, v118
	v_and_b32_e32 v152, 0xffff0000, v222
	v_fmac_f32_e32 v116, v146, v146
	v_fmac_f32_e32 v152, v141, v153
	v_lshlrev_b32_e32 v154, 16, v223
	v_fmac_f32_e32 v116, v147, v147
	v_fmac_f32_e32 v154, v142, v153
	v_and_b32_e32 v220, 0xffff0000, v223
	v_fmac_f32_e32 v116, v152, v152
	v_fmac_f32_e32 v220, v143, v153
	v_fmac_f32_e32 v116, v154, v154
	v_lshlrev_b32_e32 v0, 16, v224
	v_cvt_pk_bf16_f32 v141, v118, v146
	v_fmac_f32_e32 v116, v220, v220
	v_fmac_f32_e32 v0, v136, v153
	v_and_b32_e32 v118, 0xffff0000, v224
	v_fmac_f32_e32 v118, v137, v153
	v_lshlrev_b32_e32 v136, 16, v225
	v_fmac_f32_e32 v116, v0, v0
	v_lshl_add_u64 v[144:145], s[94:95], 0, v[230:231]
	v_fmac_f32_e32 v136, v138, v153
	v_and_b32_e32 v137, 0xffff0000, v225
	v_fmac_f32_e32 v116, v118, v118
	v_lshl_add_u64 v[144:145], v[144:145], 0, v[228:229]
	v_fmac_f32_e32 v137, v139, v153
	v_lshlrev_b32_e32 v138, 16, v226
	v_fmac_f32_e32 v116, v136, v136
	v_cvt_pk_bf16_f32 v142, v147, v152
	v_cvt_pk_bf16_f32 v143, v154, v220
	global_store_dwordx4 v[144:145], v[140:143], off sc1
	v_fmac_f32_e32 v138, v128, v153
	v_and_b32_e32 v139, 0xffff0000, v226
	v_cvt_pk_bf16_f32 v128, v0, v118
	v_fmac_f32_e32 v116, v137, v137
	v_and_b32_e32 v118, 64, v206
	v_fmac_f32_e32 v139, v129, v153
	v_lshlrev_b32_e32 v140, 16, v227
	v_fmac_f32_e32 v116, v138, v138
	v_xor_b32_e32 v0, 16, v206
	v_add_u32_e32 v118, 64, v118
	v_fmac_f32_e32 v140, v130, v153
	v_and_b32_e32 v141, 0xffff0000, v227
	v_fmac_f32_e32 v116, v139, v139
	v_cmp_lt_i32_e32 vcc, v0, v118
	v_fmac_f32_e32 v141, v131, v153
	v_fmac_f32_e32 v116, v140, v140
	v_cndmask_b32_e32 v0, v206, v0, vcc
	v_fmac_f32_e32 v116, v141, v141
	v_lshlrev_b32_e32 v0, 2, v0
	v_cvt_pk_bf16_f32 v129, v136, v137
	v_cvt_pk_bf16_f32 v130, v138, v139
	v_cvt_pk_bf16_f32 v131, v140, v141
	global_store_dwordx4 v[144:145], v[128:131], off offset:256 sc1
	ds_bpermute_b32 v128, v0, v116
	s_waitcnt lgkmcnt(0)
	v_add_f32_e32 v116, v116, v128
	v_xor_b32_e32 v128, 32, v206
	v_cmp_lt_i32_e32 vcc, v128, v118
	s_nop 1
	v_cndmask_b32_e32 v118, v206, v128, vcc
	v_lshlrev_b32_e32 v118, 2, v118
	ds_bpermute_b32 v128, v118, v116
	s_and_saveexec_b64 s[62:63], s[52:53]
	s_mov_b64 s[86:87], 0x30080
	s_cbranch_execz .LBB0_569
	s_waitcnt lgkmcnt(0)
	v_add_f32_e32 v116, v116, v128
	v_mul_f32_e32 v116, 0x4d800000, v116
	v_trunc_f32_e32 v116, v116
	v_mul_f32_e32 v128, 0x2f800000, v116
	v_floor_f32_e32 v129, v128
	v_fmac_f32_e32 v116, 0xcf800000, v129
	v_cvt_u32_f32_e32 v128, v116
	v_cvt_u32_f32_e32 v129, v129
	v_lshl_add_u64 v[130:131], v[190:191], 3, s[6:7]
	global_atomic_add_x2 v[130:131], v[128:129], off
.LBB0_569:
	s_or_b64 exec, exec, s[62:63]
	s_waitcnt vmcnt(7)
	v_lshlrev_b32_e32 v116, 16, v160
	v_fmac_f32_e32 v116, v112, v155
	v_and_b32_e32 v112, 0xffff0000, v160
	v_fmac_f32_e32 v112, v113, v155
	v_lshlrev_b32_e32 v113, 16, v161
	v_fmac_f32_e32 v113, v114, v155
	v_and_b32_e32 v114, 0xffff0000, v161
	v_fmac_f32_e32 v114, v115, v155
	v_lshlrev_b32_e32 v115, 16, v162
	v_fmac_f32_e32 v115, v108, v155
	v_cvt_pk_bf16_f32 v108, v116, v112
	v_mul_f32_e32 v112, v112, v112
	v_fmac_f32_e32 v112, v116, v116
	v_fmac_f32_e32 v112, v113, v113
	s_waitcnt lgkmcnt(0)
	v_and_b32_e32 v128, 0xffff0000, v162
	v_fmac_f32_e32 v112, v114, v114
	v_fmac_f32_e32 v128, v109, v155
	v_lshlrev_b32_e32 v129, 16, v163
	v_fmac_f32_e32 v112, v115, v115
	v_fmac_f32_e32 v129, v110, v155
	v_and_b32_e32 v130, 0xffff0000, v163
	v_fmac_f32_e32 v112, v128, v128
	v_fmac_f32_e32 v130, v111, v155
	v_cvt_pk_bf16_f32 v109, v113, v114
	v_fmac_f32_e32 v112, v129, v129
	s_waitcnt vmcnt(6)
	v_lshlrev_b32_e32 v113, 16, v156
	v_fmac_f32_e32 v112, v130, v130
	v_fmac_f32_e32 v113, v104, v155
	v_and_b32_e32 v104, 0xffff0000, v156
	v_fmac_f32_e32 v104, v105, v155
	v_lshlrev_b32_e32 v105, 16, v157
	v_fmac_f32_e32 v112, v113, v113
	v_fmac_f32_e32 v105, v106, v155
	v_and_b32_e32 v114, 0xffff0000, v157
	v_fmac_f32_e32 v112, v104, v104
	v_cvt_pk_bf16_f32 v110, v115, v128
	v_fmac_f32_e32 v114, v107, v155
	v_lshlrev_b32_e32 v115, 16, v158
	v_fmac_f32_e32 v112, v105, v105
	v_fmac_f32_e32 v115, v100, v155
	v_and_b32_e32 v116, 0xffff0000, v158
	v_fmac_f32_e32 v112, v114, v114
	v_fmac_f32_e32 v116, v101, v155
	v_lshlrev_b32_e32 v128, 16, v159
	v_fmac_f32_e32 v112, v115, v115
	v_cvt_pk_bf16_f32 v111, v129, v130
	v_fmac_f32_e32 v128, v102, v155
	v_and_b32_e32 v129, 0xffff0000, v159
	v_fmac_f32_e32 v112, v116, v116
	v_fmac_f32_e32 v129, v103, v155
	v_fmac_f32_e32 v112, v128, v128
	v_fmac_f32_e32 v112, v129, v129
	ds_bpermute_b32 v103, v0, v112
	v_lshl_add_u64 v[100:101], s[94:95], 0, v[202:203]
	v_lshl_add_u64 v[106:107], v[2:3], 1, v[100:101]
	global_store_dwordx4 v[106:107], v[108:111], off sc1
	v_cvt_pk_bf16_f32 v102, v113, v104
	s_waitcnt lgkmcnt(0)
	v_add_f32_e32 v100, v112, v103
	ds_bpermute_b32 v101, v118, v100
	v_cvt_pk_bf16_f32 v103, v105, v114
	v_cvt_pk_bf16_f32 v104, v115, v116
	v_cvt_pk_bf16_f32 v105, v128, v129
	global_store_dwordx4 v[106:107], v[102:105], off offset:256 sc1
	s_and_saveexec_b64 s[62:63], s[52:53]
	s_cbranch_execz .LBB0_571
	s_waitcnt lgkmcnt(0)
	v_add_f32_e32 v100, v100, v101
	v_mul_f32_e32 v100, 0x4d800000, v100
	v_trunc_f32_e32 v100, v100
	v_mul_f32_e32 v101, 0x2f800000, v100
	v_floor_f32_e32 v101, v101
	v_fmac_f32_e32 v100, 0xcf800000, v101
	v_cvt_u32_f32_e32 v100, v100
	v_cvt_u32_f32_e32 v101, v101
	v_lshl_add_u64 v[102:103], v[200:201], 3, s[6:7]
	global_atomic_add_x2 v[102:103], v[100:101], off
.LBB0_571:
	s_or_b64 exec, exec, s[62:63]
	s_waitcnt vmcnt(7)
	v_lshlrev_b32_e32 v100, 16, v148
	v_fmac_f32_e32 v100, v96, v117
	v_and_b32_e32 v96, 0xffff0000, v148
	v_fmac_f32_e32 v96, v97, v117
	v_lshlrev_b32_e32 v97, 16, v149
	v_fmac_f32_e32 v97, v98, v117
	v_and_b32_e32 v98, 0xffff0000, v149
	v_fmac_f32_e32 v98, v99, v117
	v_lshlrev_b32_e32 v99, 16, v150
	v_fmac_f32_e32 v99, v92, v117
	v_cvt_pk_bf16_f32 v92, v100, v96
	v_mul_f32_e32 v96, v96, v96
	v_fmac_f32_e32 v96, v100, v100
	v_fmac_f32_e32 v96, v97, v97
	s_waitcnt lgkmcnt(0)
	v_and_b32_e32 v101, 0xffff0000, v150
	v_fmac_f32_e32 v96, v98, v98
	v_fmac_f32_e32 v101, v93, v117
	v_lshlrev_b32_e32 v102, 16, v151
	v_fmac_f32_e32 v96, v99, v99
	v_fmac_f32_e32 v102, v94, v117
	v_and_b32_e32 v103, 0xffff0000, v151
	v_fmac_f32_e32 v96, v101, v101
	v_fmac_f32_e32 v103, v95, v117
	v_cvt_pk_bf16_f32 v93, v97, v98
	v_fmac_f32_e32 v96, v102, v102
	s_waitcnt vmcnt(6)
	v_lshlrev_b32_e32 v97, 16, v132
	v_fmac_f32_e32 v96, v103, v103
	v_fmac_f32_e32 v97, v88, v117
	v_and_b32_e32 v88, 0xffff0000, v132
	v_fmac_f32_e32 v88, v89, v117
	v_lshlrev_b32_e32 v89, 16, v133
	v_fmac_f32_e32 v96, v97, v97
	v_fmac_f32_e32 v89, v90, v117
	v_and_b32_e32 v98, 0xffff0000, v133
	v_fmac_f32_e32 v96, v88, v88
	v_cvt_pk_bf16_f32 v94, v99, v101
	v_fmac_f32_e32 v98, v91, v117
	v_lshlrev_b32_e32 v99, 16, v134
	v_fmac_f32_e32 v96, v89, v89
	v_fmac_f32_e32 v99, v84, v117
	v_and_b32_e32 v100, 0xffff0000, v134
	v_fmac_f32_e32 v96, v98, v98
	v_fmac_f32_e32 v100, v85, v117
	v_lshlrev_b32_e32 v101, 16, v135
	v_fmac_f32_e32 v96, v99, v99
	v_cvt_pk_bf16_f32 v95, v102, v103
	v_fmac_f32_e32 v101, v86, v117
	v_and_b32_e32 v102, 0xffff0000, v135
	v_fmac_f32_e32 v96, v100, v100
	v_fmac_f32_e32 v102, v87, v117
	v_fmac_f32_e32 v96, v101, v101
	v_fmac_f32_e32 v96, v102, v102
	ds_bpermute_b32 v87, v0, v96
	v_lshl_add_u64 v[84:85], s[94:95], 0, v[198:199]
	v_lshl_add_u64 v[90:91], v[2:3], 1, v[84:85]
	global_store_dwordx4 v[90:91], v[92:95], off sc1
	v_cvt_pk_bf16_f32 v86, v97, v88
	s_waitcnt lgkmcnt(0)
	v_add_f32_e32 v84, v96, v87
	ds_bpermute_b32 v85, v118, v84
	v_cvt_pk_bf16_f32 v87, v89, v98
	v_cvt_pk_bf16_f32 v88, v99, v100
	v_cvt_pk_bf16_f32 v89, v101, v102
	global_store_dwordx4 v[90:91], v[86:89], off offset:256 sc1
	s_and_saveexec_b64 s[62:63], s[52:53]
	s_cbranch_execz .LBB0_573
	s_waitcnt lgkmcnt(0)
	v_add_f32_e32 v84, v84, v85
	v_mul_f32_e32 v84, 0x4d800000, v84
	v_trunc_f32_e32 v84, v84
	v_mul_f32_e32 v85, 0x2f800000, v84
	v_floor_f32_e32 v85, v85
	v_fmac_f32_e32 v84, 0xcf800000, v85
	v_cvt_u32_f32_e32 v84, v84
	v_cvt_u32_f32_e32 v85, v85
	v_lshl_add_u64 v[86:87], v[196:197], 3, s[6:7]
	global_atomic_add_x2 v[86:87], v[84:85], off
.LBB0_573:
	s_or_b64 exec, exec, s[62:63]
	s_waitcnt vmcnt(7)
	v_lshlrev_b32_e32 v84, 16, v124
	v_fmac_f32_e32 v84, v80, v119
	v_and_b32_e32 v80, 0xffff0000, v124
	v_fmac_f32_e32 v80, v81, v119
	v_lshlrev_b32_e32 v81, 16, v125
	v_fmac_f32_e32 v81, v82, v119
	v_and_b32_e32 v82, 0xffff0000, v125
	v_fmac_f32_e32 v82, v83, v119
	v_lshlrev_b32_e32 v83, 16, v126
	v_fmac_f32_e32 v83, v76, v119
	v_cvt_pk_bf16_f32 v76, v84, v80
	v_mul_f32_e32 v80, v80, v80
	v_fmac_f32_e32 v80, v84, v84
	v_fmac_f32_e32 v80, v81, v81
	s_waitcnt lgkmcnt(0)
	v_and_b32_e32 v85, 0xffff0000, v126
	v_fmac_f32_e32 v80, v82, v82
	v_fmac_f32_e32 v85, v77, v119
	v_lshlrev_b32_e32 v86, 16, v127
	v_fmac_f32_e32 v80, v83, v83
	v_fmac_f32_e32 v86, v78, v119
	v_and_b32_e32 v87, 0xffff0000, v127
	v_fmac_f32_e32 v80, v85, v85
	v_fmac_f32_e32 v87, v79, v119
	v_cvt_pk_bf16_f32 v77, v81, v82
	v_fmac_f32_e32 v80, v86, v86
	s_waitcnt vmcnt(6)
	v_lshlrev_b32_e32 v81, 16, v120
	v_fmac_f32_e32 v80, v87, v87
	v_fmac_f32_e32 v81, v72, v119
	v_and_b32_e32 v72, 0xffff0000, v120
	v_fmac_f32_e32 v72, v73, v119
	v_lshlrev_b32_e32 v73, 16, v121
	v_fmac_f32_e32 v80, v81, v81
	v_fmac_f32_e32 v73, v74, v119
	v_and_b32_e32 v82, 0xffff0000, v121
	v_fmac_f32_e32 v80, v72, v72
	v_cvt_pk_bf16_f32 v78, v83, v85
	v_fmac_f32_e32 v82, v75, v119
	v_lshlrev_b32_e32 v83, 16, v122
	v_fmac_f32_e32 v80, v73, v73
	v_fmac_f32_e32 v83, v68, v119
	v_and_b32_e32 v84, 0xffff0000, v122
	v_fmac_f32_e32 v80, v82, v82
	v_fmac_f32_e32 v84, v69, v119
	v_lshlrev_b32_e32 v85, 16, v123
	v_fmac_f32_e32 v80, v83, v83
	v_cvt_pk_bf16_f32 v79, v86, v87
	v_fmac_f32_e32 v85, v70, v119
	v_and_b32_e32 v86, 0xffff0000, v123
	v_fmac_f32_e32 v80, v84, v84
	v_fmac_f32_e32 v86, v71, v119
	v_fmac_f32_e32 v80, v85, v85
	v_fmac_f32_e32 v80, v86, v86
	ds_bpermute_b32 v71, v0, v80
	v_lshl_add_u64 v[68:69], s[94:95], 0, v[194:195]
	v_lshl_add_u64 v[74:75], v[2:3], 1, v[68:69]
	global_store_dwordx4 v[74:75], v[76:79], off sc1
	v_cvt_pk_bf16_f32 v70, v81, v72
	s_waitcnt lgkmcnt(0)
	v_add_f32_e32 v68, v80, v71
	ds_bpermute_b32 v69, v118, v68
	v_cvt_pk_bf16_f32 v71, v73, v82
	v_cvt_pk_bf16_f32 v72, v83, v84
	v_cvt_pk_bf16_f32 v73, v85, v86
	global_store_dwordx4 v[74:75], v[70:73], off offset:256 sc1
	s_and_saveexec_b64 s[62:63], s[52:53]
	s_cbranch_execz .LBB0_575
	s_waitcnt lgkmcnt(0)
	v_add_f32_e32 v68, v68, v69
	v_mul_f32_e32 v68, 0x4d800000, v68
	v_trunc_f32_e32 v68, v68
	v_mul_f32_e32 v69, 0x2f800000, v68
	v_floor_f32_e32 v69, v69
	v_fmac_f32_e32 v68, 0xcf800000, v69
	v_cvt_u32_f32_e32 v68, v68
	v_cvt_u32_f32_e32 v69, v69
	v_lshl_add_u64 v[70:71], v[192:193], 3, s[6:7]
	global_atomic_add_x2 v[70:71], v[68:69], off
.LBB0_575:
	s_or_b64 exec, exec, s[62:63]
	v_add_u32_e32 v116, 0x80, v190
	v_ashrrev_i32_e32 v117, 31, v116
	v_lshlrev_b64 v[124:125], 11, v[116:117]
	s_waitcnt lgkmcnt(0)
	v_lshl_add_u64 v[68:69], v[188:189], 0, v[124:125]
	global_load_dwordx4 v[120:123], v[68:69], off
	global_load_dwordx4 v[100:103], v[68:69], off offset:256
	v_add_u32_e32 v112, 0x90, v190
	v_ashrrev_i32_e32 v113, 31, v112
	v_add_u32_e32 v108, 0xa0, v190
	v_add_u32_e32 v104, 0xb0, v190
	v_lshlrev_b64 v[114:115], 11, v[112:113]
	v_ashrrev_i32_e32 v109, 31, v108
	v_ashrrev_i32_e32 v105, 31, v104
	v_lshl_add_u64 v[68:69], v[188:189], 0, v[114:115]
	v_lshlrev_b64 v[110:111], 11, v[108:109]
	v_lshlrev_b64 v[106:107], 11, v[104:105]
	ds_read2_b64 v[88:91], v219 offset0:128 offset1:144
	global_load_dwordx4 v[96:99], v[68:69], off
	global_load_dwordx4 v[92:95], v[68:69], off offset:256
	v_lshl_add_u64 v[68:69], v[188:189], 0, v[110:111]
	v_lshl_add_u64 v[72:73], v[188:189], 0, v[106:107]
	global_load_dwordx4 v[84:87], v[68:69], off
	global_load_dwordx4 v[80:83], v[68:69], off offset:256
	ds_read2_b64 v[68:71], v219 offset0:160 offset1:176
	global_load_dwordx4 v[76:79], v[72:73], off
	s_nop 0
	global_load_dwordx4 v[72:75], v[72:73], off offset:256
	s_waitcnt vmcnt(7) lgkmcnt(1)
	v_lshlrev_b32_e32 v88, 16, v121
	s_waitcnt lgkmcnt(0)
	v_lshlrev_b32_e32 v68, 16, v120
	v_and_b32_e32 v70, 0xffff0000, v120
	v_fmac_f32_e32 v88, v66, v89
	v_and_b32_e32 v66, 0xffff0000, v121
	v_fmac_f32_e32 v68, v64, v89
	v_fmac_f32_e32 v70, v65, v89
	v_fmac_f32_e32 v66, v67, v89
	v_lshlrev_b32_e32 v67, 16, v122
	v_lshl_add_u64 v[64:65], s[94:95], 0, v[124:125]
	v_fmac_f32_e32 v67, v60, v89
	v_and_b32_e32 v90, 0xffff0000, v122
	v_lshlrev_b32_e32 v119, 16, v123
	v_and_b32_e32 v120, 0xffff0000, v123
	v_cvt_pk_bf16_f32 v60, v68, v70
	v_lshl_add_u64 v[64:65], v[2:3], 1, v[64:65]
	v_fmac_f32_e32 v90, v61, v89
	v_fmac_f32_e32 v119, v62, v89
	v_fmac_f32_e32 v120, v63, v89
	v_cvt_pk_bf16_f32 v61, v88, v66
	v_cvt_pk_bf16_f32 v62, v67, v90
	v_cvt_pk_bf16_f32 v63, v119, v120
	global_store_dwordx4 v[64:65], v[60:63], off sc1
	s_nop 1
	v_mul_f32_e32 v60, v70, v70
	v_fmac_f32_e32 v60, v68, v68
	v_fmac_f32_e32 v60, v88, v88
	v_fmac_f32_e32 v60, v66, v66
	v_fmac_f32_e32 v60, v67, v67
	v_fmac_f32_e32 v60, v90, v90
	v_fmac_f32_e32 v60, v119, v119
	s_waitcnt vmcnt(7)
	v_lshlrev_b32_e32 v61, 16, v100
	v_fmac_f32_e32 v60, v120, v120
	v_fmac_f32_e32 v61, v56, v89
	v_and_b32_e32 v56, 0xffff0000, v100
	v_fmac_f32_e32 v56, v57, v89
	v_lshlrev_b32_e32 v57, 16, v101
	v_fmac_f32_e32 v60, v61, v61
	v_fmac_f32_e32 v57, v58, v89
	v_and_b32_e32 v58, 0xffff0000, v101
	v_fmac_f32_e32 v60, v56, v56
	v_fmac_f32_e32 v58, v59, v89
	v_lshlrev_b32_e32 v59, 16, v102
	v_fmac_f32_e32 v60, v57, v57
	v_fmac_f32_e32 v59, v52, v89
	v_and_b32_e32 v62, 0xffff0000, v102
	v_fmac_f32_e32 v60, v58, v58
	v_fmac_f32_e32 v62, v53, v89
	v_lshlrev_b32_e32 v63, 16, v103
	v_fmac_f32_e32 v60, v59, v59
	v_fmac_f32_e32 v63, v54, v89
	v_and_b32_e32 v66, 0xffff0000, v103
	v_fmac_f32_e32 v60, v62, v62
	v_fmac_f32_e32 v66, v55, v89
	v_fmac_f32_e32 v60, v63, v63
	v_cvt_pk_bf16_f32 v52, v61, v56
	v_fmac_f32_e32 v60, v66, v66
	v_cvt_pk_bf16_f32 v53, v57, v58
	v_cvt_pk_bf16_f32 v54, v59, v62
	v_cvt_pk_bf16_f32 v55, v63, v66
	global_store_dwordx4 v[64:65], v[52:55], off offset:256 sc1
	ds_bpermute_b32 v52, v0, v60
	s_waitcnt lgkmcnt(0)
	v_add_f32_e32 v52, v60, v52
	ds_bpermute_b32 v53, v118, v52
	s_and_saveexec_b64 s[62:63], s[52:53]
	s_cbranch_execz .LBB0_577
	s_waitcnt lgkmcnt(0)
	v_add_f32_e32 v52, v52, v53
	v_mul_f32_e32 v52, 0x4d800000, v52
	v_trunc_f32_e32 v52, v52
	v_mul_f32_e32 v53, 0x2f800000, v52
	v_floor_f32_e32 v53, v53
	v_fmac_f32_e32 v52, 0xcf800000, v53
	v_cvt_u32_f32_e32 v52, v52
	v_cvt_u32_f32_e32 v53, v53
	v_lshl_add_u64 v[54:55], v[116:117], 3, s[6:7]
	global_atomic_add_x2 v[54:55], v[52:53], off
.LBB0_577:
	s_or_b64 exec, exec, s[62:63]
	s_waitcnt vmcnt(7)
	v_lshlrev_b32_e32 v52, 16, v96
	v_fmac_f32_e32 v52, v48, v91
	v_and_b32_e32 v48, 0xffff0000, v96
	v_fmac_f32_e32 v48, v49, v91
	v_lshlrev_b32_e32 v49, 16, v97
	v_fmac_f32_e32 v49, v50, v91
	v_and_b32_e32 v50, 0xffff0000, v97
	v_fmac_f32_e32 v50, v51, v91
	v_lshlrev_b32_e32 v51, 16, v98
	v_fmac_f32_e32 v51, v44, v91
	v_cvt_pk_bf16_f32 v44, v52, v48
	v_mul_f32_e32 v48, v48, v48
	v_fmac_f32_e32 v48, v52, v52
	v_fmac_f32_e32 v48, v49, v49
	s_waitcnt lgkmcnt(0)
	v_and_b32_e32 v53, 0xffff0000, v98
	v_fmac_f32_e32 v48, v50, v50
	v_fmac_f32_e32 v53, v45, v91
	v_lshlrev_b32_e32 v54, 16, v99
	v_fmac_f32_e32 v48, v51, v51
	v_fmac_f32_e32 v54, v46, v91
	v_and_b32_e32 v55, 0xffff0000, v99
	v_fmac_f32_e32 v48, v53, v53
	v_fmac_f32_e32 v55, v47, v91
	v_cvt_pk_bf16_f32 v45, v49, v50
	v_fmac_f32_e32 v48, v54, v54
	s_waitcnt vmcnt(6)
	v_lshlrev_b32_e32 v49, 16, v92
	v_fmac_f32_e32 v48, v55, v55
	v_fmac_f32_e32 v49, v40, v91
	v_and_b32_e32 v40, 0xffff0000, v92
	v_fmac_f32_e32 v40, v41, v91
	v_lshlrev_b32_e32 v41, 16, v93
	v_fmac_f32_e32 v48, v49, v49
	v_fmac_f32_e32 v41, v42, v91
	v_and_b32_e32 v50, 0xffff0000, v93
	v_fmac_f32_e32 v48, v40, v40
	v_cvt_pk_bf16_f32 v46, v51, v53
	v_fmac_f32_e32 v50, v43, v91
	v_lshlrev_b32_e32 v51, 16, v94
	v_fmac_f32_e32 v48, v41, v41
	v_fmac_f32_e32 v51, v36, v91
	v_and_b32_e32 v52, 0xffff0000, v94
	v_fmac_f32_e32 v48, v50, v50
	v_fmac_f32_e32 v52, v37, v91
	v_lshlrev_b32_e32 v53, 16, v95
	v_fmac_f32_e32 v48, v51, v51
	v_cvt_pk_bf16_f32 v47, v54, v55
	v_fmac_f32_e32 v53, v38, v91
	v_and_b32_e32 v54, 0xffff0000, v95
	v_fmac_f32_e32 v48, v52, v52
	v_fmac_f32_e32 v54, v39, v91
	v_fmac_f32_e32 v48, v53, v53
	v_fmac_f32_e32 v48, v54, v54
	ds_bpermute_b32 v39, v0, v48
	v_lshl_add_u64 v[36:37], s[94:95], 0, v[114:115]
	v_lshl_add_u64 v[42:43], v[2:3], 1, v[36:37]
	global_store_dwordx4 v[42:43], v[44:47], off sc1
	v_cvt_pk_bf16_f32 v38, v49, v40
	s_waitcnt lgkmcnt(0)
	v_add_f32_e32 v36, v48, v39
	ds_bpermute_b32 v37, v118, v36
	v_cvt_pk_bf16_f32 v39, v41, v50
	v_cvt_pk_bf16_f32 v40, v51, v52
	v_cvt_pk_bf16_f32 v41, v53, v54
	global_store_dwordx4 v[42:43], v[38:41], off offset:256 sc1
	s_and_saveexec_b64 s[62:63], s[52:53]
	s_cbranch_execz .LBB0_579
	s_waitcnt lgkmcnt(0)
	v_add_f32_e32 v36, v36, v37
	v_mul_f32_e32 v36, 0x4d800000, v36
	v_trunc_f32_e32 v36, v36
	v_mul_f32_e32 v37, 0x2f800000, v36
	v_floor_f32_e32 v37, v37
	v_fmac_f32_e32 v36, 0xcf800000, v37
	v_cvt_u32_f32_e32 v36, v36
	v_cvt_u32_f32_e32 v37, v37
	v_lshl_add_u64 v[38:39], v[112:113], 3, s[6:7]
	global_atomic_add_x2 v[38:39], v[36:37], off
.LBB0_579:
	s_or_b64 exec, exec, s[62:63]
	s_waitcnt vmcnt(7)
	v_lshlrev_b32_e32 v36, 16, v84
	v_fmac_f32_e32 v36, v32, v69
	v_and_b32_e32 v32, 0xffff0000, v84
	v_fmac_f32_e32 v32, v33, v69
	v_lshlrev_b32_e32 v33, 16, v85
	v_fmac_f32_e32 v33, v34, v69
	v_and_b32_e32 v34, 0xffff0000, v85
	v_fmac_f32_e32 v34, v35, v69
	v_lshlrev_b32_e32 v35, 16, v86
	v_fmac_f32_e32 v35, v28, v69
	v_cvt_pk_bf16_f32 v28, v36, v32
	v_mul_f32_e32 v32, v32, v32
	v_fmac_f32_e32 v32, v36, v36
	v_fmac_f32_e32 v32, v33, v33
	s_waitcnt lgkmcnt(0)
	v_and_b32_e32 v37, 0xffff0000, v86
	v_fmac_f32_e32 v32, v34, v34
	v_fmac_f32_e32 v37, v29, v69
	v_lshlrev_b32_e32 v38, 16, v87
	v_fmac_f32_e32 v32, v35, v35
	v_fmac_f32_e32 v38, v30, v69
	v_and_b32_e32 v39, 0xffff0000, v87
	v_fmac_f32_e32 v32, v37, v37
	v_fmac_f32_e32 v39, v31, v69
	v_cvt_pk_bf16_f32 v29, v33, v34
	v_fmac_f32_e32 v32, v38, v38
	s_waitcnt vmcnt(6)
	v_lshlrev_b32_e32 v33, 16, v80
	v_fmac_f32_e32 v32, v39, v39
	v_fmac_f32_e32 v33, v24, v69
	v_and_b32_e32 v24, 0xffff0000, v80
	v_fmac_f32_e32 v24, v25, v69
	v_lshlrev_b32_e32 v25, 16, v81
	v_fmac_f32_e32 v32, v33, v33
	v_fmac_f32_e32 v25, v26, v69
	v_and_b32_e32 v34, 0xffff0000, v81
	v_fmac_f32_e32 v32, v24, v24
	v_cvt_pk_bf16_f32 v30, v35, v37
	v_fmac_f32_e32 v34, v27, v69
	v_lshlrev_b32_e32 v35, 16, v82
	v_fmac_f32_e32 v32, v25, v25
	v_fmac_f32_e32 v35, v20, v69
	v_and_b32_e32 v36, 0xffff0000, v82
	v_fmac_f32_e32 v32, v34, v34
	v_fmac_f32_e32 v36, v21, v69
	v_lshlrev_b32_e32 v37, 16, v83
	v_fmac_f32_e32 v32, v35, v35
	v_cvt_pk_bf16_f32 v31, v38, v39
	v_fmac_f32_e32 v37, v22, v69
	v_and_b32_e32 v38, 0xffff0000, v83
	v_fmac_f32_e32 v32, v36, v36
	v_fmac_f32_e32 v38, v23, v69
	v_fmac_f32_e32 v32, v37, v37
	v_fmac_f32_e32 v32, v38, v38
	ds_bpermute_b32 v23, v0, v32
	v_lshl_add_u64 v[20:21], s[94:95], 0, v[110:111]
	v_lshl_add_u64 v[26:27], v[2:3], 1, v[20:21]
	global_store_dwordx4 v[26:27], v[28:31], off sc1
	v_cvt_pk_bf16_f32 v22, v33, v24
	s_waitcnt lgkmcnt(0)
	v_add_f32_e32 v20, v32, v23
	ds_bpermute_b32 v21, v118, v20
	v_cvt_pk_bf16_f32 v23, v25, v34
	v_cvt_pk_bf16_f32 v24, v35, v36
	v_cvt_pk_bf16_f32 v25, v37, v38
	global_store_dwordx4 v[26:27], v[22:25], off offset:256 sc1
	s_and_saveexec_b64 s[62:63], s[52:53]
	s_cbranch_execz .LBB0_581
	s_waitcnt lgkmcnt(0)
	v_add_f32_e32 v20, v20, v21
	v_mul_f32_e32 v20, 0x4d800000, v20
	v_trunc_f32_e32 v20, v20
	v_mul_f32_e32 v21, 0x2f800000, v20
	v_floor_f32_e32 v21, v21
	v_fmac_f32_e32 v20, 0xcf800000, v21
	v_cvt_u32_f32_e32 v20, v20
	v_cvt_u32_f32_e32 v21, v21
	v_lshl_add_u64 v[22:23], v[108:109], 3, s[6:7]
	global_atomic_add_x2 v[22:23], v[20:21], off
.LBB0_581:
	s_or_b64 exec, exec, s[62:63]
	s_waitcnt vmcnt(7)
	v_lshlrev_b32_e32 v20, 16, v76
	v_fmac_f32_e32 v20, v16, v71
	v_and_b32_e32 v16, 0xffff0000, v76
	v_fmac_f32_e32 v16, v17, v71
	v_lshlrev_b32_e32 v17, 16, v77
	v_fmac_f32_e32 v17, v18, v71
	v_and_b32_e32 v18, 0xffff0000, v77
	v_fmac_f32_e32 v18, v19, v71
	v_lshlrev_b32_e32 v19, 16, v78
	v_fmac_f32_e32 v19, v12, v71
	v_cvt_pk_bf16_f32 v12, v20, v16
	v_mul_f32_e32 v16, v16, v16
	v_fmac_f32_e32 v16, v20, v20
	v_fmac_f32_e32 v16, v17, v17
	s_waitcnt lgkmcnt(0)
	v_and_b32_e32 v21, 0xffff0000, v78
	v_fmac_f32_e32 v16, v18, v18
	v_fmac_f32_e32 v21, v13, v71
	v_lshlrev_b32_e32 v22, 16, v79
	v_fmac_f32_e32 v16, v19, v19
	v_fmac_f32_e32 v22, v14, v71
	v_and_b32_e32 v23, 0xffff0000, v79
	v_fmac_f32_e32 v16, v21, v21
	v_fmac_f32_e32 v23, v15, v71
	v_cvt_pk_bf16_f32 v13, v17, v18
	v_fmac_f32_e32 v16, v22, v22
	s_waitcnt vmcnt(6)
	v_lshlrev_b32_e32 v17, 16, v72
	v_fmac_f32_e32 v16, v23, v23
	v_fmac_f32_e32 v17, v8, v71
	v_and_b32_e32 v18, 0xffff0000, v72
	v_cvt_pk_bf16_f32 v14, v19, v21
	v_fmac_f32_e32 v18, v9, v71
	v_lshlrev_b32_e32 v19, 16, v73
	v_fmac_f32_e32 v16, v17, v17
	v_fmac_f32_e32 v19, v10, v71
	v_and_b32_e32 v10, 0xffff0000, v73
	v_fmac_f32_e32 v16, v18, v18
	v_fmac_f32_e32 v10, v11, v71
	v_lshlrev_b32_e32 v11, 16, v74
	v_fmac_f32_e32 v16, v19, v19
	v_fmac_f32_e32 v11, v4, v71
	v_and_b32_e32 v20, 0xffff0000, v74
	v_fmac_f32_e32 v16, v10, v10
	v_fmac_f32_e32 v20, v5, v71
	v_lshlrev_b32_e32 v21, 16, v75
	v_fmac_f32_e32 v16, v11, v11
	v_cvt_pk_bf16_f32 v15, v22, v23
	v_fmac_f32_e32 v21, v6, v71
	v_and_b32_e32 v22, 0xffff0000, v75
	v_fmac_f32_e32 v16, v20, v20
	v_fmac_f32_e32 v22, v7, v71
	v_fmac_f32_e32 v16, v21, v21
	v_fmac_f32_e32 v16, v22, v22
	ds_bpermute_b32 v0, v0, v16
	v_lshl_add_u64 v[4:5], s[94:95], 0, v[106:107]
	v_lshl_add_u64 v[8:9], v[2:3], 1, v[4:5]
	global_store_dwordx4 v[8:9], v[12:15], off sc1
	v_cvt_pk_bf16_f32 v4, v17, v18
	s_waitcnt lgkmcnt(0)
	v_add_f32_e32 v0, v16, v0
	ds_bpermute_b32 v2, v118, v0
	v_cvt_pk_bf16_f32 v5, v19, v10
	v_cvt_pk_bf16_f32 v6, v11, v20
	v_cvt_pk_bf16_f32 v7, v21, v22
	global_store_dwordx4 v[8:9], v[4:7], off offset:256 sc1
	s_and_saveexec_b64 s[62:63], s[52:53]
	s_cbranch_execz .LBB0_583
	s_waitcnt lgkmcnt(0)
	v_add_f32_e32 v0, v0, v2
	v_mul_f32_e32 v0, 0x4d800000, v0
	v_trunc_f32_e32 v0, v0
	v_mul_f32_e32 v2, 0x2f800000, v0
	v_floor_f32_e32 v3, v2
	v_fmac_f32_e32 v0, 0xcf800000, v3
	v_cvt_u32_f32_e32 v2, v0
	v_cvt_u32_f32_e32 v3, v3
	v_lshl_add_u64 v[4:5], v[104:105], 3, s[6:7]
	global_atomic_add_x2 v[4:5], v[2:3], off

.LBB0_607:
	v_lshl_add_u32 v136, s15, 8, v138
	v_lshl_or_b32 v134, s14, 8, v140
	v_ashrrev_i32_e32 v137, 31, v136
	v_lshlrev_b64 v[142:143], 10, v[136:137]
	v_ashrrev_i32_e32 v135, 31, v134
	v_lshl_add_u64 v[142:143], s[0:1], 0, v[142:143]
	v_lshlrev_b64 v[134:135], 1, v[134:135]
	v_lshl_add_u64 v[146:147], v[142:143], 0, v[134:135]
	global_load_dwordx4 v[142:145], v[146:147], off
	v_mul_f32_e32 v126, 0xbfb8aa3b, v126
	v_mul_f32_e32 v127, 0xbfb8aa3b, v127
	v_mul_f32_e32 v128, 0xbfb8aa3b, v128
	v_mul_f32_e32 v129, 0xbfb8aa3b, v129
	v_mul_f32_e32 v122, 0xbfb8aa3b, v122
	v_mul_f32_e32 v123, 0xbfb8aa3b, v123
	v_mul_f32_e32 v124, 0xbfb8aa3b, v124
	v_mul_f32_e32 v125, 0xbfb8aa3b, v125
	v_exp_f32_e32 v126, v126
	v_exp_f32_e32 v127, v127
	v_exp_f32_e32 v128, v128
	v_exp_f32_e32 v129, v129
	v_exp_f32_e32 v122, v122
	v_exp_f32_e32 v123, v123
	v_exp_f32_e32 v124, v124
	v_exp_f32_e32 v125, v125
	v_add_f32_e32 v126, 1.0, v126
	v_add_f32_e32 v127, 1.0, v127
	v_add_f32_e32 v128, 1.0, v128
	v_add_f32_e32 v129, 1.0, v129
	v_add_f32_e32 v122, 1.0, v122
	v_add_f32_e32 v123, 1.0, v123
	v_add_f32_e32 v124, 1.0, v124
	v_add_f32_e32 v125, 1.0, v125
	v_rcp_f32_e32 v126, v126
	v_rcp_f32_e32 v127, v127
	v_rcp_f32_e32 v128, v128
	v_rcp_f32_e32 v129, v129
	v_rcp_f32_e32 v122, v122
	v_rcp_f32_e32 v123, v123
	v_rcp_f32_e32 v124, v124
	v_rcp_f32_e32 v125, v125
	v_mul_f32_e32 v118, 0xbfb8aa3b, v118
	v_mul_f32_e32 v119, 0xbfb8aa3b, v119
	v_exp_f32_e32 v118, v118
	v_mul_f32_e32 v120, 0xbfb8aa3b, v120
	v_exp_f32_e32 v119, v119
	v_mul_f32_e32 v121, 0xbfb8aa3b, v121
	v_exp_f32_e32 v153, v120
	v_mul_f32_e32 v114, 0xbfb8aa3b, v114
	v_exp_f32_e32 v121, v121
	v_mul_f32_e32 v115, 0xbfb8aa3b, v115
	v_exp_f32_e32 v154, v114
	v_add_f32_e32 v118, 1.0, v118
	v_mul_f32_e32 v116, 0xbfb8aa3b, v116
	v_xor_b32_e32 v152, 32, v206
	v_exp_f32_e32 v155, v115
	v_add_f32_e32 v119, 1.0, v119
	v_rcp_f32_e32 v118, v118
	v_mul_f32_e32 v117, 0xbfb8aa3b, v117
	v_exp_f32_e32 v116, v116
	v_rcp_f32_e32 v119, v119
	v_exp_f32_e32 v117, v117
	v_add_f32_e32 v121, 1.0, v121
	v_rcp_f32_e32 v121, v121
	v_add_f32_e32 v116, 1.0, v116
	v_add_f32_e32 v117, 1.0, v117
	v_rcp_f32_e32 v116, v116
	v_rcp_f32_e32 v117, v117
	v_lshlrev_b64 v[114:115], 11, v[136:137]
	v_lshl_add_u64 v[114:115], s[60:61], 0, v[114:115]
	v_lshl_add_u64 v[114:115], v[114:115], 0, v[134:135]
	s_waitcnt vmcnt(0)
	v_lshlrev_b32_e32 v148, 16, v142
	v_and_b32_e32 v142, 0xffff0000, v142
	v_lshlrev_b32_e32 v149, 16, v143
	v_and_b32_e32 v143, 0xffff0000, v143
	v_lshlrev_b32_e32 v150, 16, v144
	v_and_b32_e32 v144, 0xffff0000, v144
	v_lshlrev_b32_e32 v151, 16, v145
	v_and_b32_e32 v145, 0xffff0000, v145
	v_mul_f32_e32 v148, v126, v148
	v_mul_f32_e32 v142, v127, v142
	v_mul_f32_e32 v149, v128, v149
	v_mul_f32_e32 v143, v129, v143
	v_mul_f32_e32 v150, v122, v150
	v_mul_f32_e32 v144, v123, v144
	v_mul_f32_e32 v151, v124, v151
	v_mul_f32_e32 v145, v125, v145
	v_cvt_pk_bf16_f32 v122, v148, v142
	v_cvt_pk_bf16_f32 v123, v149, v143
	v_cvt_pk_bf16_f32 v124, v150, v144
	v_cvt_pk_bf16_f32 v125, v151, v145
	global_load_dwordx4 v[126:129], v[146:147], off offset:256
	v_and_b32_e32 v147, 64, v206
	v_mul_f32_e32 v142, v142, v142
	v_xor_b32_e32 v146, 16, v206
	v_add_u32_e32 v120, 64, v147
	v_fmac_f32_e32 v142, v148, v148
	v_cmp_lt_i32_e32 vcc, v146, v120
	v_fmac_f32_e32 v142, v149, v149
	v_fmac_f32_e32 v142, v143, v143
	v_cndmask_b32_e32 v146, v206, v146, vcc
	v_cmp_lt_i32_e32 vcc, v152, v120
	v_lshlrev_b32_e32 v120, 2, v146
	v_add_f32_e32 v146, 1.0, v153
	v_fmac_f32_e32 v142, v150, v150
	v_rcp_f32_e32 v146, v146
	v_fmac_f32_e32 v142, v144, v144
	v_cndmask_b32_e32 v147, v206, v152, vcc
	v_add_f32_e32 v152, 1.0, v154
	v_fmac_f32_e32 v142, v151, v151
	v_add_f32_e32 v153, 1.0, v155
	v_rcp_f32_e32 v152, v152
	v_fmac_f32_e32 v142, v145, v145
	v_rcp_f32_e32 v153, v153
	global_store_dwordx4 v[114:115], v[122:125], off sc1
	s_waitcnt vmcnt(1)
	v_lshlrev_b32_e32 v143, 16, v126
	v_and_b32_e32 v126, 0xffff0000, v126
	v_mul_f32_e32 v118, v118, v143
	v_lshlrev_b32_e32 v144, 16, v127
	v_mul_f32_e32 v119, v119, v126
	v_fmac_f32_e32 v142, v118, v118
	v_and_b32_e32 v127, 0xffff0000, v127
	v_mul_f32_e32 v126, v146, v144
	v_fmac_f32_e32 v142, v119, v119
	v_lshlrev_b32_e32 v145, 16, v128
	v_mul_f32_e32 v121, v121, v127
	v_fmac_f32_e32 v142, v126, v126
	v_and_b32_e32 v128, 0xffff0000, v128
	v_mul_f32_e32 v127, v152, v145
	v_fmac_f32_e32 v142, v121, v121
	v_lshlrev_b32_e32 v148, 16, v129
	v_mul_f32_e32 v128, v153, v128
	v_fmac_f32_e32 v142, v127, v127
	v_and_b32_e32 v129, 0xffff0000, v129
	v_mul_f32_e32 v143, v116, v148
	v_fmac_f32_e32 v142, v128, v128
	v_mul_f32_e32 v129, v117, v129
	v_fmac_f32_e32 v142, v143, v143
	v_fmac_f32_e32 v142, v129, v129
	ds_bpermute_b32 v116, v120, v142
	v_cvt_pk_bf16_f32 v122, v118, v119
	v_cvt_pk_bf16_f32 v123, v126, v121
	v_lshlrev_b32_e32 v121, 2, v147
	v_cvt_pk_bf16_f32 v124, v127, v128
	s_waitcnt lgkmcnt(0)
	v_add_f32_e32 v116, v142, v116
	ds_bpermute_b32 v117, v121, v116
	v_cvt_pk_bf16_f32 v125, v143, v129
	global_store_dwordx4 v[114:115], v[122:125], off offset:256 sc1
	v_lshl_add_u64 v[114:115], v[136:137], 3, s[62:63]
	s_and_saveexec_b64 s[6:7], s[54:55]
	s_cbranch_execz .LBB0_609
	s_waitcnt lgkmcnt(0)
	v_add_f32_e32 v116, v116, v117
	v_mul_f32_e32 v116, 0x4d800000, v116
	v_trunc_f32_e32 v116, v116
	v_mul_f32_e32 v117, 0x2f800000, v116
	v_floor_f32_e32 v117, v117
	v_fmac_f32_e32 v116, 0xcf800000, v117
	v_cvt_u32_f32_e32 v116, v116
	v_cvt_u32_f32_e32 v117, v117
	global_atomic_add_x2 v[114:115], v[116:117], off
.LBB0_609:
	s_or_b64 exec, exec, s[6:7]
	v_or_b32_e32 v116, 16, v136
	s_waitcnt lgkmcnt(0)
	v_ashrrev_i32_e32 v117, 31, v116
	v_lshlrev_b64 v[122:123], 10, v[116:117]
	v_lshlrev_b64 v[118:119], 11, v[116:117]
	v_lshl_add_u64 v[116:117], s[0:1], 0, v[122:123]
	v_lshl_add_u64 v[116:117], v[116:117], 0, v[134:135]
	global_load_dwordx4 v[122:125], v[116:117], off
	v_mul_f32_e32 v111, 0xbfb8aa3b, v111
	v_exp_f32_e32 v111, v111
	v_mul_f32_e32 v112, 0xbfb8aa3b, v112
	v_exp_f32_e32 v112, v112
	v_mul_f32_e32 v113, 0xbfb8aa3b, v113
	v_exp_f32_e32 v113, v113
	v_mul_f32_e32 v106, 0xbfb8aa3b, v106
	v_exp_f32_e32 v106, v106
	v_mul_f32_e32 v107, 0xbfb8aa3b, v107
	v_add_f32_e32 v111, 1.0, v111
	v_exp_f32_e32 v107, v107
	v_mul_f32_e32 v108, 0xbfb8aa3b, v108
	v_mul_f32_e32 v110, 0xbfb8aa3b, v110
	v_rcp_f32_e32 v111, v111
	v_add_f32_e32 v112, 1.0, v112
	v_exp_f32_e32 v108, v108
	v_mul_f32_e32 v109, 0xbfb8aa3b, v109
	v_exp_f32_e32 v110, v110
	v_rcp_f32_e32 v112, v112
	v_add_f32_e32 v113, 1.0, v113
	v_exp_f32_e32 v109, v109
	v_rcp_f32_e32 v113, v113
	v_add_f32_e32 v106, 1.0, v106
	v_rcp_f32_e32 v106, v106
	v_add_f32_e32 v107, 1.0, v107
	v_rcp_f32_e32 v107, v107
	v_add_f32_e32 v108, 1.0, v108
	v_add_f32_e32 v110, 1.0, v110
	v_rcp_f32_e32 v108, v108
	v_add_f32_e32 v109, 1.0, v109
	v_rcp_f32_e32 v110, v110
	v_rcp_f32_e32 v109, v109
	v_mul_f32_e32 v102, 0xbfb8aa3b, v102
	v_exp_f32_e32 v102, v102
	v_mul_f32_e32 v103, 0xbfb8aa3b, v103
	v_exp_f32_e32 v103, v103
	v_mul_f32_e32 v104, 0xbfb8aa3b, v104
	v_exp_f32_e32 v104, v104
	v_mul_f32_e32 v105, 0xbfb8aa3b, v105
	v_exp_f32_e32 v105, v105
	v_mul_f32_e32 v98, 0xbfb8aa3b, v98
	v_add_f32_e32 v102, 1.0, v102
	v_exp_f32_e32 v98, v98
	v_mul_f32_e32 v99, 0xbfb8aa3b, v99
	v_rcp_f32_e32 v102, v102
	v_add_f32_e32 v103, 1.0, v103
	v_exp_f32_e32 v99, v99
	v_rcp_f32_e32 v103, v103
	v_add_f32_e32 v104, 1.0, v104
	v_rcp_f32_e32 v104, v104
	v_add_f32_e32 v105, 1.0, v105
	v_rcp_f32_e32 v105, v105
	v_add_f32_e32 v98, 1.0, v98
	v_rcp_f32_e32 v98, v98
	v_add_f32_e32 v99, 1.0, v99
	v_rcp_f32_e32 v99, v99
	s_waitcnt vmcnt(0)
	v_lshlrev_b32_e32 v126, 16, v122
	v_and_b32_e32 v122, 0xffff0000, v122
	v_mul_f32_e32 v111, v111, v122
	v_lshlrev_b32_e32 v122, 16, v123
	v_mul_f32_e32 v112, v112, v122
	v_and_b32_e32 v122, 0xffff0000, v123
	v_mul_f32_e32 v113, v113, v122
	v_lshlrev_b32_e32 v122, 16, v124
	v_mul_f32_e32 v106, v106, v122
	v_and_b32_e32 v122, 0xffff0000, v124
	v_mul_f32_e32 v107, v107, v122
	v_lshlrev_b32_e32 v122, 16, v125
	v_mul_f32_e32 v122, v108, v122
	v_and_b32_e32 v108, 0xffff0000, v125
	v_mul_f32_e32 v110, v110, v126
	v_mul_f32_e32 v109, v109, v108
	v_mul_f32_e32 v108, v111, v111
	v_fmac_f32_e32 v108, v110, v110
	v_fmac_f32_e32 v108, v112, v112
	v_fmac_f32_e32 v108, v113, v113
	v_fmac_f32_e32 v108, v106, v106
	v_fmac_f32_e32 v108, v107, v107
	v_cvt_pk_bf16_f32 v110, v110, v111
	v_cvt_pk_bf16_f32 v111, v112, v113
	v_cvt_pk_bf16_f32 v112, v106, v107
	v_lshl_add_u64 v[106:107], s[60:61], 0, v[118:119]
	v_cvt_pk_bf16_f32 v113, v122, v109
	v_lshl_add_u64 v[106:107], v[106:107], 0, v[134:135]
	global_store_dwordx4 v[106:107], v[110:113], off sc1
	global_load_dwordx4 v[110:113], v[116:117], off offset:256
	v_fmac_f32_e32 v108, v122, v122
	v_fmac_f32_e32 v108, v109, v109
	s_waitcnt vmcnt(0)
	v_lshlrev_b32_e32 v109, 16, v110
	v_mul_f32_e32 v102, v102, v109
	v_and_b32_e32 v109, 0xffff0000, v110
	v_mul_f32_e32 v103, v103, v109
	v_lshlrev_b32_e32 v109, 16, v111
	v_mul_f32_e32 v104, v104, v109
	v_and_b32_e32 v109, 0xffff0000, v111
	v_mul_f32_e32 v105, v105, v109
	v_lshlrev_b32_e32 v109, 16, v112
	v_mul_f32_e32 v109, v98, v109
	v_and_b32_e32 v98, 0xffff0000, v112
	v_mul_f32_e32 v110, v99, v98
	v_mul_f32_e32 v99, 0xbfb8aa3b, v100
	v_exp_f32_e32 v99, v99
	v_lshlrev_b32_e32 v98, 16, v113
	v_fmac_f32_e32 v108, v102, v102
	v_fmac_f32_e32 v108, v103, v103
	v_add_f32_e32 v99, 1.0, v99
	v_rcp_f32_e32 v99, v99
	v_fmac_f32_e32 v108, v104, v104
	v_fmac_f32_e32 v108, v105, v105
	v_fmac_f32_e32 v108, v109, v109
	v_mul_f32_e32 v111, v99, v98
	v_mul_f32_e32 v99, 0xbfb8aa3b, v101
	v_exp_f32_e32 v99, v99
	v_and_b32_e32 v98, 0xffff0000, v113
	v_fmac_f32_e32 v108, v110, v110
	v_fmac_f32_e32 v108, v111, v111
	v_add_f32_e32 v99, 1.0, v99
	v_rcp_f32_e32 v99, v99
	s_nop 0
	v_mul_f32_e32 v101, v99, v98
	v_fmac_f32_e32 v108, v101, v101
	v_cvt_pk_bf16_f32 v98, v102, v103
	v_cvt_pk_bf16_f32 v99, v104, v105
	v_cvt_pk_bf16_f32 v100, v109, v110
	v_cvt_pk_bf16_f32 v101, v111, v101
	global_store_dwordx4 v[106:107], v[98:101], off offset:256 sc1
	ds_bpermute_b32 v98, v120, v108
	s_waitcnt lgkmcnt(0)
	v_add_f32_e32 v98, v108, v98
	ds_bpermute_b32 v99, v121, v98
	s_and_saveexec_b64 s[6:7], s[54:55]
	s_cbranch_execz .LBB0_611
	s_waitcnt lgkmcnt(0)
	v_add_f32_e32 v98, v98, v99
	v_mul_f32_e32 v98, 0x4d800000, v98
	v_trunc_f32_e32 v98, v98
	v_mul_f32_e32 v99, 0x2f800000, v98
	v_floor_f32_e32 v99, v99
	v_fmac_f32_e32 v98, 0xcf800000, v99
	v_cvt_u32_f32_e32 v98, v98
	v_cvt_u32_f32_e32 v99, v99
	global_atomic_add_x2 v[114:115], v[98:99], off offset:128
.LBB0_611:
	s_or_b64 exec, exec, s[6:7]
	v_or_b32_e32 v98, 32, v136
	s_waitcnt lgkmcnt(0)
	v_ashrrev_i32_e32 v99, 31, v98
	v_lshlrev_b64 v[102:103], 10, v[98:99]
	v_lshlrev_b64 v[100:101], 11, v[98:99]
	v_lshl_add_u64 v[98:99], s[0:1], 0, v[102:103]
	v_lshl_add_u64 v[98:99], v[98:99], 0, v[134:135]
	global_load_dwordx4 v[102:105], v[98:99], off
	v_mul_f32_e32 v95, 0xbfb8aa3b, v95
	v_exp_f32_e32 v95, v95
	v_mul_f32_e32 v96, 0xbfb8aa3b, v96
	v_exp_f32_e32 v96, v96
	v_mul_f32_e32 v97, 0xbfb8aa3b, v97
	v_exp_f32_e32 v97, v97
	v_mul_f32_e32 v90, 0xbfb8aa3b, v90
	v_exp_f32_e32 v90, v90
	v_mul_f32_e32 v91, 0xbfb8aa3b, v91
	v_add_f32_e32 v95, 1.0, v95
	v_exp_f32_e32 v91, v91
	v_mul_f32_e32 v92, 0xbfb8aa3b, v92
	v_mul_f32_e32 v94, 0xbfb8aa3b, v94
	v_rcp_f32_e32 v95, v95
	v_add_f32_e32 v96, 1.0, v96
	v_exp_f32_e32 v92, v92
	v_mul_f32_e32 v93, 0xbfb8aa3b, v93
	v_exp_f32_e32 v94, v94
	v_rcp_f32_e32 v96, v96
	v_add_f32_e32 v97, 1.0, v97
	v_exp_f32_e32 v93, v93
	v_rcp_f32_e32 v97, v97
	v_add_f32_e32 v90, 1.0, v90
	v_rcp_f32_e32 v90, v90
	v_add_f32_e32 v91, 1.0, v91
	v_rcp_f32_e32 v91, v91
	v_add_f32_e32 v92, 1.0, v92
	v_add_f32_e32 v94, 1.0, v94
	v_rcp_f32_e32 v92, v92
	v_add_f32_e32 v93, 1.0, v93
	v_rcp_f32_e32 v94, v94
	v_rcp_f32_e32 v93, v93
	v_mul_f32_e32 v86, 0xbfb8aa3b, v86
	v_exp_f32_e32 v86, v86
	v_mul_f32_e32 v87, 0xbfb8aa3b, v87
	v_exp_f32_e32 v87, v87
	v_mul_f32_e32 v88, 0xbfb8aa3b, v88
	v_exp_f32_e32 v88, v88
	v_mul_f32_e32 v89, 0xbfb8aa3b, v89
	v_exp_f32_e32 v89, v89
	v_mul_f32_e32 v82, 0xbfb8aa3b, v82
	v_add_f32_e32 v86, 1.0, v86
	v_exp_f32_e32 v82, v82
	v_mul_f32_e32 v83, 0xbfb8aa3b, v83
	v_rcp_f32_e32 v86, v86
	v_add_f32_e32 v87, 1.0, v87
	v_exp_f32_e32 v83, v83
	v_rcp_f32_e32 v87, v87
	v_add_f32_e32 v88, 1.0, v88
	v_rcp_f32_e32 v88, v88
	v_add_f32_e32 v89, 1.0, v89
	v_rcp_f32_e32 v89, v89
	v_add_f32_e32 v82, 1.0, v82
	v_rcp_f32_e32 v82, v82
	v_add_f32_e32 v83, 1.0, v83
	v_rcp_f32_e32 v83, v83
	s_waitcnt vmcnt(0)
	v_lshlrev_b32_e32 v106, 16, v102
	v_and_b32_e32 v102, 0xffff0000, v102
	v_mul_f32_e32 v95, v95, v102
	v_lshlrev_b32_e32 v102, 16, v103
	v_mul_f32_e32 v96, v96, v102
	v_and_b32_e32 v102, 0xffff0000, v103
	v_mul_f32_e32 v97, v97, v102
	v_lshlrev_b32_e32 v102, 16, v104
	v_mul_f32_e32 v90, v90, v102
	v_and_b32_e32 v102, 0xffff0000, v104
	v_mul_f32_e32 v91, v91, v102
	v_lshlrev_b32_e32 v102, 16, v105
	v_mul_f32_e32 v102, v92, v102
	v_and_b32_e32 v92, 0xffff0000, v105
	v_mul_f32_e32 v94, v94, v106
	v_mul_f32_e32 v93, v93, v92
	v_mul_f32_e32 v92, v95, v95
	v_fmac_f32_e32 v92, v94, v94
	v_fmac_f32_e32 v92, v96, v96
	v_fmac_f32_e32 v92, v97, v97
	v_fmac_f32_e32 v92, v90, v90
	v_fmac_f32_e32 v92, v91, v91
	v_cvt_pk_bf16_f32 v94, v94, v95
	v_cvt_pk_bf16_f32 v95, v96, v97
	v_cvt_pk_bf16_f32 v96, v90, v91
	v_lshl_add_u64 v[90:91], s[60:61], 0, v[100:101]
	v_cvt_pk_bf16_f32 v97, v102, v93
	v_lshl_add_u64 v[90:91], v[90:91], 0, v[134:135]
	global_store_dwordx4 v[90:91], v[94:97], off sc1
	global_load_dwordx4 v[94:97], v[98:99], off offset:256
	v_fmac_f32_e32 v92, v102, v102
	v_fmac_f32_e32 v92, v93, v93
	s_waitcnt vmcnt(0)
	v_lshlrev_b32_e32 v93, 16, v94
	v_mul_f32_e32 v86, v86, v93
	v_and_b32_e32 v93, 0xffff0000, v94
	v_mul_f32_e32 v87, v87, v93
	v_lshlrev_b32_e32 v93, 16, v95
	v_mul_f32_e32 v88, v88, v93
	v_and_b32_e32 v93, 0xffff0000, v95
	v_mul_f32_e32 v89, v89, v93
	v_lshlrev_b32_e32 v93, 16, v96
	v_mul_f32_e32 v93, v82, v93
	v_and_b32_e32 v82, 0xffff0000, v96
	v_mul_f32_e32 v94, v83, v82
	v_mul_f32_e32 v83, 0xbfb8aa3b, v84
	v_exp_f32_e32 v83, v83
	v_lshlrev_b32_e32 v82, 16, v97
	v_fmac_f32_e32 v92, v86, v86
	v_fmac_f32_e32 v92, v87, v87
	v_add_f32_e32 v83, 1.0, v83
	v_rcp_f32_e32 v83, v83
	v_fmac_f32_e32 v92, v88, v88
	v_fmac_f32_e32 v92, v89, v89
	v_fmac_f32_e32 v92, v93, v93
	v_mul_f32_e32 v95, v83, v82
	v_mul_f32_e32 v83, 0xbfb8aa3b, v85
	v_exp_f32_e32 v83, v83
	v_and_b32_e32 v82, 0xffff0000, v97
	v_fmac_f32_e32 v92, v94, v94
	v_fmac_f32_e32 v92, v95, v95
	v_add_f32_e32 v83, 1.0, v83
	v_rcp_f32_e32 v83, v83
	s_nop 0
	v_mul_f32_e32 v85, v83, v82
	v_fmac_f32_e32 v92, v85, v85
	v_cvt_pk_bf16_f32 v82, v86, v87
	v_cvt_pk_bf16_f32 v83, v88, v89
	v_cvt_pk_bf16_f32 v84, v93, v94
	v_cvt_pk_bf16_f32 v85, v95, v85
	global_store_dwordx4 v[90:91], v[82:85], off offset:256 sc1
	ds_bpermute_b32 v82, v120, v92
	s_waitcnt lgkmcnt(0)
	v_add_f32_e32 v82, v92, v82
	ds_bpermute_b32 v83, v121, v82
	s_and_saveexec_b64 s[6:7], s[54:55]
	s_cbranch_execz .LBB0_613
	s_waitcnt lgkmcnt(0)
	v_add_f32_e32 v82, v82, v83
	v_mul_f32_e32 v82, 0x4d800000, v82
	v_trunc_f32_e32 v82, v82
	v_mul_f32_e32 v83, 0x2f800000, v82
	v_floor_f32_e32 v83, v83
	v_fmac_f32_e32 v82, 0xcf800000, v83
	v_cvt_u32_f32_e32 v82, v82
	v_cvt_u32_f32_e32 v83, v83
	global_atomic_add_x2 v[114:115], v[82:83], off offset:256
.LBB0_613:
	s_or_b64 exec, exec, s[6:7]
	v_or_b32_e32 v82, 48, v136
	s_waitcnt lgkmcnt(0)
	v_ashrrev_i32_e32 v83, 31, v82
	v_lshlrev_b64 v[86:87], 10, v[82:83]
	v_lshlrev_b64 v[84:85], 11, v[82:83]
	v_lshl_add_u64 v[82:83], s[0:1], 0, v[86:87]
	v_lshl_add_u64 v[82:83], v[82:83], 0, v[134:135]
	global_load_dwordx4 v[86:89], v[82:83], off
	v_mul_f32_e32 v79, 0xbfb8aa3b, v79
	v_exp_f32_e32 v79, v79
	v_mul_f32_e32 v80, 0xbfb8aa3b, v80
	v_exp_f32_e32 v80, v80
	v_mul_f32_e32 v81, 0xbfb8aa3b, v81
	v_exp_f32_e32 v81, v81
	v_mul_f32_e32 v74, 0xbfb8aa3b, v74
	v_exp_f32_e32 v74, v74
	v_mul_f32_e32 v75, 0xbfb8aa3b, v75
	v_add_f32_e32 v79, 1.0, v79
	v_exp_f32_e32 v75, v75
	v_mul_f32_e32 v76, 0xbfb8aa3b, v76
	v_mul_f32_e32 v78, 0xbfb8aa3b, v78
	v_rcp_f32_e32 v79, v79
	v_add_f32_e32 v80, 1.0, v80
	v_exp_f32_e32 v76, v76
	v_mul_f32_e32 v77, 0xbfb8aa3b, v77
	v_exp_f32_e32 v78, v78
	v_rcp_f32_e32 v80, v80
	v_add_f32_e32 v81, 1.0, v81
	v_exp_f32_e32 v77, v77
	v_rcp_f32_e32 v81, v81
	v_add_f32_e32 v74, 1.0, v74
	v_rcp_f32_e32 v74, v74
	v_add_f32_e32 v75, 1.0, v75
	v_rcp_f32_e32 v75, v75
	v_add_f32_e32 v76, 1.0, v76
	v_add_f32_e32 v78, 1.0, v78
	v_rcp_f32_e32 v76, v76
	v_add_f32_e32 v77, 1.0, v77
	v_rcp_f32_e32 v78, v78
	v_rcp_f32_e32 v77, v77
	v_mul_f32_e32 v70, 0xbfb8aa3b, v70
	v_exp_f32_e32 v70, v70
	v_mul_f32_e32 v71, 0xbfb8aa3b, v71
	v_exp_f32_e32 v71, v71
	v_mul_f32_e32 v72, 0xbfb8aa3b, v72
	v_exp_f32_e32 v72, v72
	v_mul_f32_e32 v73, 0xbfb8aa3b, v73
	v_exp_f32_e32 v73, v73
	v_mul_f32_e32 v66, 0xbfb8aa3b, v66
	v_add_f32_e32 v70, 1.0, v70
	v_exp_f32_e32 v66, v66
	v_mul_f32_e32 v67, 0xbfb8aa3b, v67
	v_rcp_f32_e32 v70, v70
	v_add_f32_e32 v71, 1.0, v71
	v_exp_f32_e32 v67, v67
	v_rcp_f32_e32 v71, v71
	v_add_f32_e32 v72, 1.0, v72
	v_rcp_f32_e32 v72, v72
	v_add_f32_e32 v73, 1.0, v73
	v_rcp_f32_e32 v73, v73
	v_add_f32_e32 v66, 1.0, v66
	v_rcp_f32_e32 v66, v66
	v_add_f32_e32 v67, 1.0, v67
	v_rcp_f32_e32 v67, v67
	s_waitcnt vmcnt(0)
	v_lshlrev_b32_e32 v90, 16, v86
	v_and_b32_e32 v86, 0xffff0000, v86
	v_mul_f32_e32 v79, v79, v86
	v_lshlrev_b32_e32 v86, 16, v87
	v_mul_f32_e32 v80, v80, v86
	v_and_b32_e32 v86, 0xffff0000, v87
	v_mul_f32_e32 v81, v81, v86
	v_lshlrev_b32_e32 v86, 16, v88
	v_mul_f32_e32 v74, v74, v86
	v_and_b32_e32 v86, 0xffff0000, v88
	v_mul_f32_e32 v75, v75, v86
	v_lshlrev_b32_e32 v86, 16, v89
	v_mul_f32_e32 v86, v76, v86
	v_and_b32_e32 v76, 0xffff0000, v89
	v_mul_f32_e32 v78, v78, v90
	v_mul_f32_e32 v77, v77, v76
	v_mul_f32_e32 v76, v79, v79
	v_fmac_f32_e32 v76, v78, v78
	v_fmac_f32_e32 v76, v80, v80
	v_fmac_f32_e32 v76, v81, v81
	v_fmac_f32_e32 v76, v74, v74
	v_fmac_f32_e32 v76, v75, v75
	v_cvt_pk_bf16_f32 v78, v78, v79
	v_cvt_pk_bf16_f32 v79, v80, v81
	v_cvt_pk_bf16_f32 v80, v74, v75
	v_lshl_add_u64 v[74:75], s[60:61], 0, v[84:85]
	v_cvt_pk_bf16_f32 v81, v86, v77
	v_lshl_add_u64 v[74:75], v[74:75], 0, v[134:135]
	global_store_dwordx4 v[74:75], v[78:81], off sc1
	global_load_dwordx4 v[78:81], v[82:83], off offset:256
	v_fmac_f32_e32 v76, v86, v86
	v_fmac_f32_e32 v76, v77, v77
	s_waitcnt vmcnt(0)
	v_lshlrev_b32_e32 v77, 16, v78
	v_mul_f32_e32 v70, v70, v77
	v_and_b32_e32 v77, 0xffff0000, v78
	v_mul_f32_e32 v71, v71, v77
	v_lshlrev_b32_e32 v77, 16, v79
	v_mul_f32_e32 v72, v72, v77
	v_and_b32_e32 v77, 0xffff0000, v79
	v_mul_f32_e32 v73, v73, v77
	v_lshlrev_b32_e32 v77, 16, v80
	v_mul_f32_e32 v77, v66, v77
	v_and_b32_e32 v66, 0xffff0000, v80
	v_mul_f32_e32 v78, v67, v66
	v_mul_f32_e32 v67, 0xbfb8aa3b, v68
	v_exp_f32_e32 v67, v67
	v_lshlrev_b32_e32 v66, 16, v81
	v_fmac_f32_e32 v76, v70, v70
	v_fmac_f32_e32 v76, v71, v71
	v_add_f32_e32 v67, 1.0, v67
	v_rcp_f32_e32 v67, v67
	v_fmac_f32_e32 v76, v72, v72
	v_fmac_f32_e32 v76, v73, v73
	v_fmac_f32_e32 v76, v77, v77
	v_mul_f32_e32 v79, v67, v66
	v_mul_f32_e32 v67, 0xbfb8aa3b, v69
	v_exp_f32_e32 v67, v67
	v_and_b32_e32 v66, 0xffff0000, v81
	v_fmac_f32_e32 v76, v78, v78
	v_fmac_f32_e32 v76, v79, v79
	v_add_f32_e32 v67, 1.0, v67
	v_rcp_f32_e32 v67, v67
	s_nop 0
	v_mul_f32_e32 v69, v67, v66
	v_fmac_f32_e32 v76, v69, v69
	v_cvt_pk_bf16_f32 v66, v70, v71
	v_cvt_pk_bf16_f32 v67, v72, v73
	v_cvt_pk_bf16_f32 v68, v77, v78
	v_cvt_pk_bf16_f32 v69, v79, v69
	global_store_dwordx4 v[74:75], v[66:69], off offset:256 sc1
	ds_bpermute_b32 v66, v120, v76
	s_waitcnt lgkmcnt(0)
	v_add_f32_e32 v66, v76, v66
	ds_bpermute_b32 v67, v121, v66
	s_and_saveexec_b64 s[6:7], s[54:55]
	s_cbranch_execz .LBB0_615
	s_waitcnt lgkmcnt(0)
	v_add_f32_e32 v66, v66, v67
	v_mul_f32_e32 v66, 0x4d800000, v66
	v_trunc_f32_e32 v66, v66
	v_mul_f32_e32 v67, 0x2f800000, v66
	v_floor_f32_e32 v67, v67
	v_fmac_f32_e32 v66, 0xcf800000, v67
	v_cvt_u32_f32_e32 v66, v66
	v_cvt_u32_f32_e32 v67, v67
	global_atomic_add_x2 v[114:115], v[66:67], off offset:384
.LBB0_615:
	s_or_b64 exec, exec, s[6:7]
	v_add_u32_e32 v66, 0x80, v136
	s_waitcnt lgkmcnt(0)
	v_ashrrev_i32_e32 v67, 31, v66
	v_lshlrev_b64 v[70:71], 10, v[66:67]
	v_lshlrev_b64 v[68:69], 11, v[66:67]
	v_lshl_add_u64 v[66:67], s[0:1], 0, v[70:71]
	v_lshl_add_u64 v[66:67], v[66:67], 0, v[134:135]
	global_load_dwordx4 v[70:73], v[66:67], off
	v_mul_f32_e32 v63, 0xbfb8aa3b, v63
	v_exp_f32_e32 v63, v63
	v_mul_f32_e32 v64, 0xbfb8aa3b, v64
	v_exp_f32_e32 v64, v64
	v_mul_f32_e32 v65, 0xbfb8aa3b, v65
	v_exp_f32_e32 v65, v65
	v_mul_f32_e32 v58, 0xbfb8aa3b, v58
	v_exp_f32_e32 v58, v58
	v_mul_f32_e32 v59, 0xbfb8aa3b, v59
	v_add_f32_e32 v63, 1.0, v63
	v_exp_f32_e32 v59, v59
	v_mul_f32_e32 v60, 0xbfb8aa3b, v60
	v_mul_f32_e32 v62, 0xbfb8aa3b, v62
	v_rcp_f32_e32 v63, v63
	v_add_f32_e32 v64, 1.0, v64
	v_exp_f32_e32 v60, v60
	v_mul_f32_e32 v61, 0xbfb8aa3b, v61
	v_exp_f32_e32 v62, v62
	v_rcp_f32_e32 v64, v64
	v_add_f32_e32 v65, 1.0, v65
	v_exp_f32_e32 v61, v61
	v_rcp_f32_e32 v65, v65
	v_add_f32_e32 v58, 1.0, v58
	v_rcp_f32_e32 v58, v58
	v_add_f32_e32 v59, 1.0, v59
	v_rcp_f32_e32 v59, v59
	v_add_f32_e32 v60, 1.0, v60
	v_add_f32_e32 v62, 1.0, v62
	v_rcp_f32_e32 v60, v60
	v_add_f32_e32 v61, 1.0, v61
	v_rcp_f32_e32 v62, v62
	v_rcp_f32_e32 v61, v61
	v_mul_f32_e32 v54, 0xbfb8aa3b, v54
	v_exp_f32_e32 v54, v54
	v_mul_f32_e32 v55, 0xbfb8aa3b, v55
	v_exp_f32_e32 v55, v55
	v_mul_f32_e32 v56, 0xbfb8aa3b, v56
	v_exp_f32_e32 v56, v56
	v_mul_f32_e32 v57, 0xbfb8aa3b, v57
	v_exp_f32_e32 v57, v57
	v_mul_f32_e32 v50, 0xbfb8aa3b, v50
	v_add_f32_e32 v54, 1.0, v54
	v_exp_f32_e32 v50, v50
	v_mul_f32_e32 v51, 0xbfb8aa3b, v51
	v_rcp_f32_e32 v54, v54
	v_add_f32_e32 v55, 1.0, v55
	v_exp_f32_e32 v51, v51
	v_rcp_f32_e32 v55, v55
	v_add_f32_e32 v56, 1.0, v56
	v_rcp_f32_e32 v56, v56
	v_add_f32_e32 v57, 1.0, v57
	v_rcp_f32_e32 v57, v57
	v_add_f32_e32 v50, 1.0, v50
	v_rcp_f32_e32 v50, v50
	v_add_f32_e32 v51, 1.0, v51
	v_rcp_f32_e32 v51, v51
	s_waitcnt vmcnt(0)
	v_lshlrev_b32_e32 v74, 16, v70
	v_and_b32_e32 v70, 0xffff0000, v70
	v_mul_f32_e32 v63, v63, v70
	v_lshlrev_b32_e32 v70, 16, v71
	v_mul_f32_e32 v64, v64, v70
	v_and_b32_e32 v70, 0xffff0000, v71
	v_mul_f32_e32 v65, v65, v70
	v_lshlrev_b32_e32 v70, 16, v72
	v_mul_f32_e32 v58, v58, v70
	v_and_b32_e32 v70, 0xffff0000, v72
	v_mul_f32_e32 v59, v59, v70
	v_lshlrev_b32_e32 v70, 16, v73
	v_mul_f32_e32 v70, v60, v70
	v_and_b32_e32 v60, 0xffff0000, v73
	v_mul_f32_e32 v62, v62, v74
	v_mul_f32_e32 v61, v61, v60
	v_mul_f32_e32 v60, v63, v63
	v_fmac_f32_e32 v60, v62, v62
	v_fmac_f32_e32 v60, v64, v64
	v_fmac_f32_e32 v60, v65, v65
	v_fmac_f32_e32 v60, v58, v58
	v_fmac_f32_e32 v60, v59, v59
	v_cvt_pk_bf16_f32 v62, v62, v63
	v_cvt_pk_bf16_f32 v63, v64, v65
	v_cvt_pk_bf16_f32 v64, v58, v59
	v_lshl_add_u64 v[58:59], s[60:61], 0, v[68:69]
	v_cvt_pk_bf16_f32 v65, v70, v61
	v_lshl_add_u64 v[58:59], v[58:59], 0, v[134:135]
	global_store_dwordx4 v[58:59], v[62:65], off sc1
	global_load_dwordx4 v[62:65], v[66:67], off offset:256
	v_fmac_f32_e32 v60, v70, v70
	v_fmac_f32_e32 v60, v61, v61
	s_waitcnt vmcnt(0)
	v_lshlrev_b32_e32 v61, 16, v62
	v_mul_f32_e32 v54, v54, v61
	v_and_b32_e32 v61, 0xffff0000, v62
	v_mul_f32_e32 v55, v55, v61
	v_lshlrev_b32_e32 v61, 16, v63
	v_mul_f32_e32 v56, v56, v61
	v_and_b32_e32 v61, 0xffff0000, v63
	v_mul_f32_e32 v57, v57, v61
	v_lshlrev_b32_e32 v61, 16, v64
	v_mul_f32_e32 v61, v50, v61
	v_and_b32_e32 v50, 0xffff0000, v64
	v_mul_f32_e32 v62, v51, v50
	v_mul_f32_e32 v51, 0xbfb8aa3b, v52
	v_exp_f32_e32 v51, v51
	v_lshlrev_b32_e32 v50, 16, v65
	v_fmac_f32_e32 v60, v54, v54
	v_fmac_f32_e32 v60, v55, v55
	v_add_f32_e32 v51, 1.0, v51
	v_rcp_f32_e32 v51, v51
	v_fmac_f32_e32 v60, v56, v56
	v_fmac_f32_e32 v60, v57, v57
	v_fmac_f32_e32 v60, v61, v61
	v_mul_f32_e32 v63, v51, v50
	v_mul_f32_e32 v51, 0xbfb8aa3b, v53
	v_exp_f32_e32 v51, v51
	v_and_b32_e32 v50, 0xffff0000, v65
	v_fmac_f32_e32 v60, v62, v62
	v_fmac_f32_e32 v60, v63, v63
	v_add_f32_e32 v51, 1.0, v51
	v_rcp_f32_e32 v51, v51
	s_nop 0
	v_mul_f32_e32 v53, v51, v50
	v_fmac_f32_e32 v60, v53, v53
	v_cvt_pk_bf16_f32 v50, v54, v55
	v_cvt_pk_bf16_f32 v51, v56, v57
	v_cvt_pk_bf16_f32 v52, v61, v62
	v_cvt_pk_bf16_f32 v53, v63, v53
	global_store_dwordx4 v[58:59], v[50:53], off offset:256 sc1
	ds_bpermute_b32 v50, v120, v60
	s_waitcnt lgkmcnt(0)
	v_add_f32_e32 v50, v60, v50
	ds_bpermute_b32 v51, v121, v50
	s_and_saveexec_b64 s[6:7], s[54:55]
	s_cbranch_execz .LBB0_617
	s_waitcnt lgkmcnt(0)
	v_add_f32_e32 v50, v50, v51
	v_mul_f32_e32 v50, 0x4d800000, v50
	v_trunc_f32_e32 v50, v50
	v_mul_f32_e32 v51, 0x2f800000, v50
	v_floor_f32_e32 v51, v51
	v_fmac_f32_e32 v50, 0xcf800000, v51
	v_cvt_u32_f32_e32 v50, v50
	v_cvt_u32_f32_e32 v51, v51
	global_atomic_add_x2 v[114:115], v[50:51], off offset:1024
.LBB0_617:
	s_or_b64 exec, exec, s[6:7]
	v_add_u32_e32 v50, 0x90, v136
	s_waitcnt lgkmcnt(0)
	v_ashrrev_i32_e32 v51, 31, v50
	v_lshlrev_b64 v[54:55], 10, v[50:51]
	v_lshlrev_b64 v[52:53], 11, v[50:51]
	v_lshl_add_u64 v[50:51], s[0:1], 0, v[54:55]
	v_lshl_add_u64 v[50:51], v[50:51], 0, v[134:135]
	global_load_dwordx4 v[54:57], v[50:51], off
	v_mul_f32_e32 v47, 0xbfb8aa3b, v47
	v_exp_f32_e32 v47, v47
	v_mul_f32_e32 v48, 0xbfb8aa3b, v48
	v_exp_f32_e32 v48, v48
	v_mul_f32_e32 v49, 0xbfb8aa3b, v49
	v_exp_f32_e32 v49, v49
	v_mul_f32_e32 v42, 0xbfb8aa3b, v42
	v_exp_f32_e32 v42, v42
	v_mul_f32_e32 v43, 0xbfb8aa3b, v43
	v_add_f32_e32 v47, 1.0, v47
	v_exp_f32_e32 v43, v43
	v_mul_f32_e32 v44, 0xbfb8aa3b, v44
	v_mul_f32_e32 v46, 0xbfb8aa3b, v46
	v_rcp_f32_e32 v47, v47
	v_add_f32_e32 v48, 1.0, v48
	v_exp_f32_e32 v44, v44
	v_mul_f32_e32 v45, 0xbfb8aa3b, v45
	v_exp_f32_e32 v46, v46
	v_rcp_f32_e32 v48, v48
	v_add_f32_e32 v49, 1.0, v49
	v_exp_f32_e32 v45, v45
	v_rcp_f32_e32 v49, v49
	v_add_f32_e32 v42, 1.0, v42
	v_rcp_f32_e32 v42, v42
	v_add_f32_e32 v43, 1.0, v43
	v_rcp_f32_e32 v43, v43
	v_add_f32_e32 v44, 1.0, v44
	v_add_f32_e32 v46, 1.0, v46
	v_rcp_f32_e32 v44, v44
	v_add_f32_e32 v45, 1.0, v45
	v_rcp_f32_e32 v46, v46
	v_rcp_f32_e32 v45, v45
	v_mul_f32_e32 v38, 0xbfb8aa3b, v38
	v_exp_f32_e32 v38, v38
	v_mul_f32_e32 v39, 0xbfb8aa3b, v39
	v_exp_f32_e32 v39, v39
	v_mul_f32_e32 v40, 0xbfb8aa3b, v40
	v_exp_f32_e32 v40, v40
	v_mul_f32_e32 v41, 0xbfb8aa3b, v41
	v_exp_f32_e32 v41, v41
	v_mul_f32_e32 v34, 0xbfb8aa3b, v34
	v_add_f32_e32 v38, 1.0, v38
	v_exp_f32_e32 v34, v34
	v_mul_f32_e32 v35, 0xbfb8aa3b, v35
	v_rcp_f32_e32 v38, v38
	v_add_f32_e32 v39, 1.0, v39
	v_exp_f32_e32 v35, v35
	v_rcp_f32_e32 v39, v39
	v_add_f32_e32 v40, 1.0, v40
	v_rcp_f32_e32 v40, v40
	v_add_f32_e32 v41, 1.0, v41
	v_rcp_f32_e32 v41, v41
	v_add_f32_e32 v34, 1.0, v34
	v_rcp_f32_e32 v34, v34
	v_add_f32_e32 v35, 1.0, v35
	v_rcp_f32_e32 v35, v35
	s_waitcnt vmcnt(0)
	v_lshlrev_b32_e32 v58, 16, v54
	v_and_b32_e32 v54, 0xffff0000, v54
	v_mul_f32_e32 v47, v47, v54
	v_lshlrev_b32_e32 v54, 16, v55
	v_mul_f32_e32 v48, v48, v54
	v_and_b32_e32 v54, 0xffff0000, v55
	v_mul_f32_e32 v49, v49, v54
	v_lshlrev_b32_e32 v54, 16, v56
	v_mul_f32_e32 v42, v42, v54
	v_and_b32_e32 v54, 0xffff0000, v56
	v_mul_f32_e32 v43, v43, v54
	v_lshlrev_b32_e32 v54, 16, v57
	v_mul_f32_e32 v54, v44, v54
	v_and_b32_e32 v44, 0xffff0000, v57
	v_mul_f32_e32 v46, v46, v58
	v_mul_f32_e32 v45, v45, v44
	v_mul_f32_e32 v44, v47, v47
	v_fmac_f32_e32 v44, v46, v46
	v_fmac_f32_e32 v44, v48, v48
	v_fmac_f32_e32 v44, v49, v49
	v_fmac_f32_e32 v44, v42, v42
	v_fmac_f32_e32 v44, v43, v43
	v_cvt_pk_bf16_f32 v46, v46, v47
	v_cvt_pk_bf16_f32 v47, v48, v49
	v_cvt_pk_bf16_f32 v48, v42, v43
	v_lshl_add_u64 v[42:43], s[60:61], 0, v[52:53]
	v_cvt_pk_bf16_f32 v49, v54, v45
	v_lshl_add_u64 v[42:43], v[42:43], 0, v[134:135]
	global_store_dwordx4 v[42:43], v[46:49], off sc1
	global_load_dwordx4 v[46:49], v[50:51], off offset:256
	v_fmac_f32_e32 v44, v54, v54
	v_fmac_f32_e32 v44, v45, v45
	s_waitcnt vmcnt(0)
	v_lshlrev_b32_e32 v45, 16, v46
	v_mul_f32_e32 v38, v38, v45
	v_and_b32_e32 v45, 0xffff0000, v46
	v_mul_f32_e32 v39, v39, v45
	v_lshlrev_b32_e32 v45, 16, v47
	v_mul_f32_e32 v40, v40, v45
	v_and_b32_e32 v45, 0xffff0000, v47
	v_mul_f32_e32 v41, v41, v45
	v_lshlrev_b32_e32 v45, 16, v48
	v_mul_f32_e32 v45, v34, v45
	v_and_b32_e32 v34, 0xffff0000, v48
	v_mul_f32_e32 v46, v35, v34
	v_mul_f32_e32 v35, 0xbfb8aa3b, v36
	v_exp_f32_e32 v35, v35
	v_lshlrev_b32_e32 v34, 16, v49
	v_fmac_f32_e32 v44, v38, v38
	v_fmac_f32_e32 v44, v39, v39
	v_add_f32_e32 v35, 1.0, v35
	v_rcp_f32_e32 v35, v35
	v_fmac_f32_e32 v44, v40, v40
	v_fmac_f32_e32 v44, v41, v41
	v_fmac_f32_e32 v44, v45, v45
	v_mul_f32_e32 v47, v35, v34
	v_mul_f32_e32 v35, 0xbfb8aa3b, v37
	v_exp_f32_e32 v35, v35
	v_and_b32_e32 v34, 0xffff0000, v49
	v_fmac_f32_e32 v44, v46, v46
	v_fmac_f32_e32 v44, v47, v47
	v_add_f32_e32 v35, 1.0, v35
	v_rcp_f32_e32 v35, v35
	s_nop 0
	v_mul_f32_e32 v37, v35, v34
	v_fmac_f32_e32 v44, v37, v37
	v_cvt_pk_bf16_f32 v34, v38, v39
	v_cvt_pk_bf16_f32 v35, v40, v41
	v_cvt_pk_bf16_f32 v36, v45, v46
	v_cvt_pk_bf16_f32 v37, v47, v37
	global_store_dwordx4 v[42:43], v[34:37], off offset:256 sc1
	ds_bpermute_b32 v34, v120, v44
	s_waitcnt lgkmcnt(0)
	v_add_f32_e32 v34, v44, v34
	ds_bpermute_b32 v35, v121, v34
	s_and_saveexec_b64 s[6:7], s[54:55]
	s_cbranch_execz .LBB0_619
	s_waitcnt lgkmcnt(0)
	v_add_f32_e32 v34, v34, v35
	v_mul_f32_e32 v34, 0x4d800000, v34
	v_trunc_f32_e32 v34, v34
	v_mul_f32_e32 v35, 0x2f800000, v34
	v_floor_f32_e32 v35, v35
	v_fmac_f32_e32 v34, 0xcf800000, v35
	v_cvt_u32_f32_e32 v34, v34
	v_cvt_u32_f32_e32 v35, v35
	global_atomic_add_x2 v[114:115], v[34:35], off offset:1152
.LBB0_619:
	s_or_b64 exec, exec, s[6:7]
	v_add_u32_e32 v34, 0xa0, v136
	s_waitcnt lgkmcnt(0)
	v_ashrrev_i32_e32 v35, 31, v34
	v_lshlrev_b64 v[38:39], 10, v[34:35]
	v_lshlrev_b64 v[36:37], 11, v[34:35]
	v_lshl_add_u64 v[34:35], s[0:1], 0, v[38:39]
	v_lshl_add_u64 v[34:35], v[34:35], 0, v[134:135]
	global_load_dwordx4 v[38:41], v[34:35], off
	v_mul_f32_e32 v31, 0xbfb8aa3b, v31
	v_exp_f32_e32 v31, v31
	v_mul_f32_e32 v32, 0xbfb8aa3b, v32
	v_exp_f32_e32 v32, v32
	v_mul_f32_e32 v33, 0xbfb8aa3b, v33
	v_exp_f32_e32 v33, v33
	v_mul_f32_e32 v26, 0xbfb8aa3b, v26
	v_exp_f32_e32 v26, v26
	v_mul_f32_e32 v27, 0xbfb8aa3b, v27
	v_add_f32_e32 v31, 1.0, v31
	v_exp_f32_e32 v27, v27
	v_mul_f32_e32 v28, 0xbfb8aa3b, v28
	v_mul_f32_e32 v30, 0xbfb8aa3b, v30
	v_rcp_f32_e32 v31, v31
	v_add_f32_e32 v32, 1.0, v32
	v_exp_f32_e32 v28, v28
	v_mul_f32_e32 v29, 0xbfb8aa3b, v29
	v_exp_f32_e32 v30, v30
	v_rcp_f32_e32 v32, v32
	v_add_f32_e32 v33, 1.0, v33
	v_exp_f32_e32 v29, v29
	v_rcp_f32_e32 v33, v33
	v_add_f32_e32 v26, 1.0, v26
	v_rcp_f32_e32 v26, v26
	v_add_f32_e32 v27, 1.0, v27
	v_rcp_f32_e32 v27, v27
	v_add_f32_e32 v28, 1.0, v28
	v_add_f32_e32 v30, 1.0, v30
	v_rcp_f32_e32 v28, v28
	v_add_f32_e32 v29, 1.0, v29
	v_rcp_f32_e32 v30, v30
	v_rcp_f32_e32 v29, v29
	v_mul_f32_e32 v22, 0xbfb8aa3b, v22
	v_exp_f32_e32 v22, v22
	v_mul_f32_e32 v23, 0xbfb8aa3b, v23
	v_exp_f32_e32 v23, v23
	v_mul_f32_e32 v24, 0xbfb8aa3b, v24
	v_exp_f32_e32 v24, v24
	v_mul_f32_e32 v25, 0xbfb8aa3b, v25
	v_exp_f32_e32 v25, v25
	v_mul_f32_e32 v18, 0xbfb8aa3b, v18
	v_add_f32_e32 v22, 1.0, v22
	v_exp_f32_e32 v18, v18
	v_mul_f32_e32 v19, 0xbfb8aa3b, v19
	v_rcp_f32_e32 v22, v22
	v_add_f32_e32 v23, 1.0, v23
	v_exp_f32_e32 v19, v19
	v_rcp_f32_e32 v23, v23
	v_add_f32_e32 v24, 1.0, v24
	v_rcp_f32_e32 v24, v24
	v_add_f32_e32 v25, 1.0, v25
	v_rcp_f32_e32 v25, v25
	v_add_f32_e32 v18, 1.0, v18
	v_rcp_f32_e32 v18, v18
	v_add_f32_e32 v19, 1.0, v19
	v_rcp_f32_e32 v19, v19
	s_waitcnt vmcnt(0)
	v_lshlrev_b32_e32 v42, 16, v38
	v_and_b32_e32 v38, 0xffff0000, v38
	v_mul_f32_e32 v31, v31, v38
	v_lshlrev_b32_e32 v38, 16, v39
	v_mul_f32_e32 v32, v32, v38
	v_and_b32_e32 v38, 0xffff0000, v39
	v_mul_f32_e32 v33, v33, v38
	v_lshlrev_b32_e32 v38, 16, v40
	v_mul_f32_e32 v26, v26, v38
	v_and_b32_e32 v38, 0xffff0000, v40
	v_mul_f32_e32 v27, v27, v38
	v_lshlrev_b32_e32 v38, 16, v41
	v_mul_f32_e32 v38, v28, v38
	v_and_b32_e32 v28, 0xffff0000, v41
	v_mul_f32_e32 v30, v30, v42
	v_mul_f32_e32 v29, v29, v28
	v_mul_f32_e32 v28, v31, v31
	v_fmac_f32_e32 v28, v30, v30
	v_fmac_f32_e32 v28, v32, v32
	v_fmac_f32_e32 v28, v33, v33
	v_fmac_f32_e32 v28, v26, v26
	v_fmac_f32_e32 v28, v27, v27
	v_cvt_pk_bf16_f32 v30, v30, v31
	v_cvt_pk_bf16_f32 v31, v32, v33
	v_cvt_pk_bf16_f32 v32, v26, v27
	v_lshl_add_u64 v[26:27], s[60:61], 0, v[36:37]
	v_cvt_pk_bf16_f32 v33, v38, v29
	v_lshl_add_u64 v[26:27], v[26:27], 0, v[134:135]
	global_store_dwordx4 v[26:27], v[30:33], off sc1
	global_load_dwordx4 v[30:33], v[34:35], off offset:256
	v_fmac_f32_e32 v28, v38, v38
	v_fmac_f32_e32 v28, v29, v29
	s_waitcnt vmcnt(0)
	v_lshlrev_b32_e32 v29, 16, v30
	v_mul_f32_e32 v22, v22, v29
	v_and_b32_e32 v29, 0xffff0000, v30
	v_mul_f32_e32 v23, v23, v29
	v_lshlrev_b32_e32 v29, 16, v31
	v_mul_f32_e32 v24, v24, v29
	v_and_b32_e32 v29, 0xffff0000, v31
	v_mul_f32_e32 v25, v25, v29
	v_lshlrev_b32_e32 v29, 16, v32
	v_mul_f32_e32 v29, v18, v29
	v_and_b32_e32 v18, 0xffff0000, v32
	v_mul_f32_e32 v30, v19, v18
	v_mul_f32_e32 v19, 0xbfb8aa3b, v20
	v_exp_f32_e32 v19, v19
	v_lshlrev_b32_e32 v18, 16, v33
	v_fmac_f32_e32 v28, v22, v22
	v_fmac_f32_e32 v28, v23, v23
	v_add_f32_e32 v19, 1.0, v19
	v_rcp_f32_e32 v19, v19
	v_fmac_f32_e32 v28, v24, v24
	v_fmac_f32_e32 v28, v25, v25
	v_fmac_f32_e32 v28, v29, v29
	v_mul_f32_e32 v31, v19, v18
	v_mul_f32_e32 v19, 0xbfb8aa3b, v21
	v_exp_f32_e32 v19, v19
	v_and_b32_e32 v18, 0xffff0000, v33
	v_fmac_f32_e32 v28, v30, v30
	v_fmac_f32_e32 v28, v31, v31
	v_add_f32_e32 v19, 1.0, v19
	v_rcp_f32_e32 v19, v19
	s_nop 0
	v_mul_f32_e32 v21, v19, v18
	v_fmac_f32_e32 v28, v21, v21
	v_cvt_pk_bf16_f32 v18, v22, v23
	v_cvt_pk_bf16_f32 v19, v24, v25
	v_cvt_pk_bf16_f32 v20, v29, v30
	v_cvt_pk_bf16_f32 v21, v31, v21
	global_store_dwordx4 v[26:27], v[18:21], off offset:256 sc1
	ds_bpermute_b32 v18, v120, v28
	s_waitcnt lgkmcnt(0)
	v_add_f32_e32 v18, v28, v18
	ds_bpermute_b32 v19, v121, v18
	s_and_saveexec_b64 s[6:7], s[54:55]
	s_cbranch_execz .LBB0_621
	s_waitcnt lgkmcnt(0)
	v_add_f32_e32 v18, v18, v19
	v_mul_f32_e32 v18, 0x4d800000, v18
	v_trunc_f32_e32 v18, v18
	v_mul_f32_e32 v19, 0x2f800000, v18
	v_floor_f32_e32 v19, v19
	v_fmac_f32_e32 v18, 0xcf800000, v19
	v_cvt_u32_f32_e32 v18, v18
	v_cvt_u32_f32_e32 v19, v19
	global_atomic_add_x2 v[114:115], v[18:19], off offset:1280
.LBB0_621:
	s_or_b64 exec, exec, s[6:7]
	v_add_u32_e32 v18, 0xb0, v136
	s_waitcnt lgkmcnt(0)
	v_ashrrev_i32_e32 v19, 31, v18
	v_lshlrev_b64 v[22:23], 10, v[18:19]
	v_lshlrev_b64 v[20:21], 11, v[18:19]
	v_lshl_add_u64 v[18:19], s[0:1], 0, v[22:23]
	v_lshl_add_u64 v[18:19], v[18:19], 0, v[134:135]
	global_load_dwordx4 v[22:25], v[18:19], off
	v_mul_f32_e32 v15, 0xbfb8aa3b, v15
	v_exp_f32_e32 v15, v15
	v_mul_f32_e32 v16, 0xbfb8aa3b, v16
	v_exp_f32_e32 v16, v16
	v_mul_f32_e32 v17, 0xbfb8aa3b, v17
	v_exp_f32_e32 v17, v17
	v_mul_f32_e32 v10, 0xbfb8aa3b, v10
	v_exp_f32_e32 v10, v10
	v_mul_f32_e32 v11, 0xbfb8aa3b, v11
	v_add_f32_e32 v15, 1.0, v15
	v_exp_f32_e32 v11, v11
	v_mul_f32_e32 v12, 0xbfb8aa3b, v12
	v_mul_f32_e32 v14, 0xbfb8aa3b, v14
	v_rcp_f32_e32 v15, v15
	v_add_f32_e32 v16, 1.0, v16
	v_exp_f32_e32 v12, v12
	v_mul_f32_e32 v13, 0xbfb8aa3b, v13
	v_exp_f32_e32 v14, v14
	v_rcp_f32_e32 v16, v16
	v_add_f32_e32 v17, 1.0, v17
	v_exp_f32_e32 v13, v13
	v_rcp_f32_e32 v17, v17
	v_add_f32_e32 v10, 1.0, v10
	v_rcp_f32_e32 v10, v10
	v_add_f32_e32 v11, 1.0, v11
	v_rcp_f32_e32 v11, v11
	v_add_f32_e32 v12, 1.0, v12
	v_add_f32_e32 v14, 1.0, v14
	v_rcp_f32_e32 v12, v12
	v_add_f32_e32 v13, 1.0, v13
	v_rcp_f32_e32 v14, v14
	v_rcp_f32_e32 v13, v13
	v_mul_f32_e32 v6, 0xbfb8aa3b, v6
	v_exp_f32_e32 v6, v6
	v_mul_f32_e32 v7, 0xbfb8aa3b, v7
	v_exp_f32_e32 v7, v7
	v_mul_f32_e32 v8, 0xbfb8aa3b, v8
	v_exp_f32_e32 v8, v8
	v_mul_f32_e32 v9, 0xbfb8aa3b, v9
	v_exp_f32_e32 v9, v9
	v_mul_f32_e32 v2, 0xbfb8aa3b, v2
	v_add_f32_e32 v6, 1.0, v6
	v_exp_f32_e32 v2, v2
	v_mul_f32_e32 v3, 0xbfb8aa3b, v3
	v_rcp_f32_e32 v6, v6
	v_add_f32_e32 v7, 1.0, v7
	v_exp_f32_e32 v3, v3
	v_rcp_f32_e32 v7, v7
	v_add_f32_e32 v8, 1.0, v8
	v_rcp_f32_e32 v8, v8
	v_add_f32_e32 v9, 1.0, v9
	v_rcp_f32_e32 v9, v9
	v_add_f32_e32 v2, 1.0, v2
	v_rcp_f32_e32 v2, v2
	v_add_f32_e32 v3, 1.0, v3
	v_rcp_f32_e32 v3, v3
	s_waitcnt vmcnt(0)
	v_lshlrev_b32_e32 v26, 16, v22
	v_and_b32_e32 v22, 0xffff0000, v22
	v_mul_f32_e32 v15, v15, v22
	v_lshlrev_b32_e32 v22, 16, v23
	v_mul_f32_e32 v16, v16, v22
	v_and_b32_e32 v22, 0xffff0000, v23
	v_mul_f32_e32 v17, v17, v22
	v_lshlrev_b32_e32 v22, 16, v24
	v_mul_f32_e32 v10, v10, v22
	v_and_b32_e32 v22, 0xffff0000, v24
	v_mul_f32_e32 v11, v11, v22
	v_lshlrev_b32_e32 v22, 16, v25
	v_mul_f32_e32 v22, v12, v22
	v_and_b32_e32 v12, 0xffff0000, v25
	v_mul_f32_e32 v14, v14, v26
	v_mul_f32_e32 v13, v13, v12
	v_mul_f32_e32 v12, v15, v15
	v_fmac_f32_e32 v12, v14, v14
	v_fmac_f32_e32 v12, v16, v16
	v_fmac_f32_e32 v12, v17, v17
	v_fmac_f32_e32 v12, v10, v10
	v_fmac_f32_e32 v12, v11, v11
	v_cvt_pk_bf16_f32 v14, v14, v15
	v_cvt_pk_bf16_f32 v15, v16, v17
	v_cvt_pk_bf16_f32 v16, v10, v11
	v_lshl_add_u64 v[10:11], s[60:61], 0, v[20:21]
	v_cvt_pk_bf16_f32 v17, v22, v13
	v_lshl_add_u64 v[10:11], v[10:11], 0, v[134:135]
	global_store_dwordx4 v[10:11], v[14:17], off sc1
	global_load_dwordx4 v[14:17], v[18:19], off offset:256
	v_fmac_f32_e32 v12, v22, v22
	v_fmac_f32_e32 v12, v13, v13
	s_waitcnt vmcnt(0)
	v_lshlrev_b32_e32 v13, 16, v14
	v_mul_f32_e32 v6, v6, v13
	v_and_b32_e32 v13, 0xffff0000, v14
	v_mul_f32_e32 v7, v7, v13
	v_lshlrev_b32_e32 v13, 16, v15
	v_mul_f32_e32 v8, v8, v13
	v_and_b32_e32 v13, 0xffff0000, v15
	v_mul_f32_e32 v9, v9, v13
	v_lshlrev_b32_e32 v13, 16, v16
	v_mul_f32_e32 v13, v2, v13
	v_and_b32_e32 v2, 0xffff0000, v16
	v_mul_f32_e32 v14, v3, v2
	v_mul_f32_e32 v3, 0xbfb8aa3b, v4
	v_exp_f32_e32 v3, v3
	v_lshlrev_b32_e32 v2, 16, v17
	v_fmac_f32_e32 v12, v6, v6
	v_fmac_f32_e32 v12, v7, v7
	v_add_f32_e32 v3, 1.0, v3
	v_rcp_f32_e32 v3, v3
	v_fmac_f32_e32 v12, v8, v8
	v_fmac_f32_e32 v12, v9, v9
	v_fmac_f32_e32 v12, v13, v13
	v_mul_f32_e32 v15, v3, v2
	v_mul_f32_e32 v3, 0xbfb8aa3b, v5
	v_exp_f32_e32 v3, v3
	v_and_b32_e32 v2, 0xffff0000, v17
	v_fmac_f32_e32 v12, v14, v14
	v_fmac_f32_e32 v12, v15, v15
	v_add_f32_e32 v3, 1.0, v3
	v_rcp_f32_e32 v3, v3
	s_nop 0
	v_mul_f32_e32 v5, v3, v2
	v_fmac_f32_e32 v12, v5, v5
	v_cvt_pk_bf16_f32 v2, v6, v7
	v_cvt_pk_bf16_f32 v3, v8, v9
	v_cvt_pk_bf16_f32 v4, v13, v14
	v_cvt_pk_bf16_f32 v5, v15, v5
	global_store_dwordx4 v[10:11], v[2:5], off offset:256 sc1
	ds_bpermute_b32 v2, v120, v12
	s_waitcnt lgkmcnt(0)
	v_add_f32_e32 v2, v12, v2
	ds_bpermute_b32 v3, v121, v2
	s_and_saveexec_b64 s[6:7], s[54:55]
	s_cbranch_execz .LBB0_623
	s_waitcnt lgkmcnt(0)
	v_add_f32_e32 v2, v2, v3
	v_mul_f32_e32 v2, 0x4d800000, v2
	v_trunc_f32_e32 v2, v2
	v_mul_f32_e32 v3, 0x2f800000, v2
	v_floor_f32_e32 v3, v3
	v_fmac_f32_e32 v2, 0xcf800000, v3
	v_cvt_u32_f32_e32 v2, v2
	v_cvt_u32_f32_e32 v3, v3
	global_atomic_add_x2 v[114:115], v[2:3], off offset:1408

.LBB0_645:
	v_lshl_add_u32 v136, s15, 8, v132
	v_lshl_or_b32 v138, s14, 8, v134
	v_ashrrev_i32_e32 v137, 31, v136
	v_lshlrev_b64 v[140:141], 11, v[136:137]
	v_ashrrev_i32_e32 v139, 31, v138
	v_cvt_pk_bf16_f32 v126, v126, v127
	v_cvt_pk_bf16_f32 v127, v128, v129
	v_cvt_pk_bf16_f32 v128, v122, v123
	v_cvt_pk_bf16_f32 v129, v124, v125
	v_lshl_add_u64 v[122:123], s[6:7], 0, v[140:141]
	v_lshlrev_b64 v[124:125], 1, v[138:139]
	v_lshl_add_u64 v[122:123], v[122:123], 0, v[124:125]
	global_store_dwordx4 v[122:123], v[126:129], off sc1
	v_cvt_pk_bf16_f32 v114, v114, v115
	v_cvt_pk_bf16_f32 v115, v116, v117
	v_cvt_pk_bf16_f32 v116, v106, v107
	v_or_b32_e32 v106, 16, v136
	v_ashrrev_i32_e32 v107, 31, v106
	v_cvt_pk_bf16_f32 v117, v108, v109
	global_store_dwordx4 v[122:123], v[114:117], off offset:256 sc1
	s_mov_b32 s12, 0x40000
	s_mov_b64 s[86:87], 0x30080
	v_lshlrev_b64 v[114:115], 11, v[106:107]
	v_cvt_pk_bf16_f32 v106, v118, v119
	v_cvt_pk_bf16_f32 v107, v120, v121
	v_cvt_pk_bf16_f32 v108, v110, v111
	v_lshl_add_u64 v[110:111], s[6:7], 0, v[114:115]
	v_lshl_add_u64 v[110:111], v[110:111], 0, v[124:125]
	v_cvt_pk_bf16_f32 v109, v112, v113
	global_store_dwordx4 v[110:111], v[106:109], off sc1
	v_cvt_pk_bf16_f32 v98, v98, v99
	v_cvt_pk_bf16_f32 v99, v100, v101
	v_cvt_pk_bf16_f32 v100, v90, v91
	v_or_b32_e32 v90, 32, v136
	v_ashrrev_i32_e32 v91, 31, v90
	v_cvt_pk_bf16_f32 v101, v92, v93
	global_store_dwordx4 v[110:111], v[98:101], off offset:256 sc1
	s_nop 1
	v_lshlrev_b64 v[98:99], 11, v[90:91]
	v_cvt_pk_bf16_f32 v90, v102, v103
	v_cvt_pk_bf16_f32 v91, v104, v105
	v_cvt_pk_bf16_f32 v92, v94, v95
	v_lshl_add_u64 v[94:95], s[6:7], 0, v[98:99]
	v_lshl_add_u64 v[94:95], v[94:95], 0, v[124:125]
	v_cvt_pk_bf16_f32 v93, v96, v97
	global_store_dwordx4 v[94:95], v[90:93], off sc1
	v_cvt_pk_bf16_f32 v82, v82, v83
	v_cvt_pk_bf16_f32 v83, v84, v85
	v_cvt_pk_bf16_f32 v84, v74, v75
	v_or_b32_e32 v74, 48, v136
	v_ashrrev_i32_e32 v75, 31, v74
	v_cvt_pk_bf16_f32 v85, v76, v77
	global_store_dwordx4 v[94:95], v[82:85], off offset:256 sc1
	s_nop 1
	v_lshlrev_b64 v[82:83], 11, v[74:75]
	v_cvt_pk_bf16_f32 v74, v86, v87
	v_cvt_pk_bf16_f32 v75, v88, v89
	v_cvt_pk_bf16_f32 v76, v78, v79
	v_lshl_add_u64 v[78:79], s[6:7], 0, v[82:83]
	v_lshl_add_u64 v[78:79], v[78:79], 0, v[124:125]
	v_cvt_pk_bf16_f32 v77, v80, v81
	global_store_dwordx4 v[78:79], v[74:77], off sc1
	v_cvt_pk_bf16_f32 v70, v70, v71
	v_cvt_pk_bf16_f32 v71, v72, v73
	v_cvt_pk_bf16_f32 v72, v66, v67
	v_cvt_pk_bf16_f32 v73, v68, v69
	global_store_dwordx4 v[78:79], v[70:73], off offset:256 sc1
	v_cvt_pk_bf16_f32 v62, v62, v63
	v_cvt_pk_bf16_f32 v63, v64, v65
	v_cvt_pk_bf16_f32 v64, v58, v59
	v_cvt_pk_bf16_f32 v65, v60, v61
	v_add_co_u32_e32 v60, vcc, s12, v122
	v_lshl_add_u64 v[58:59], v[122:123], 0, s[28:29]
	s_nop 0
	v_addc_co_u32_e32 v61, vcc, 0, v123, vcc
	s_mov_b64 s[12:13], 0x48000
	global_store_dwordx4 v[60:61], v[62:65], off sc1
	v_cvt_pk_bf16_f32 v50, v50, v51
	v_cvt_pk_bf16_f32 v51, v52, v53
	v_cvt_pk_bf16_f32 v52, v42, v43
	v_cvt_pk_bf16_f32 v53, v44, v45
	global_store_dwordx4 v[58:59], v[50:53], off offset:256 sc1
	v_cvt_pk_bf16_f32 v42, v54, v55
	v_cvt_pk_bf16_f32 v43, v56, v57
	v_cvt_pk_bf16_f32 v44, v46, v47
	v_lshl_add_u64 v[46:47], v[122:123], 0, s[12:13]
	s_mov_b32 s12, 0x48000
	v_cvt_pk_bf16_f32 v45, v48, v49
	v_add_co_u32_e32 v48, vcc, s12, v122
	s_mov_b64 s[12:13], 0x50000
	s_nop 0
	v_addc_co_u32_e32 v49, vcc, 0, v123, vcc
	global_store_dwordx4 v[48:49], v[42:45], off sc1
	v_cvt_pk_bf16_f32 v34, v34, v35
	v_cvt_pk_bf16_f32 v35, v36, v37
	v_cvt_pk_bf16_f32 v36, v26, v27
	v_cvt_pk_bf16_f32 v37, v28, v29
	global_store_dwordx4 v[46:47], v[34:37], off offset:256 sc1
	v_cvt_pk_bf16_f32 v26, v38, v39
	v_cvt_pk_bf16_f32 v27, v40, v41
	v_cvt_pk_bf16_f32 v28, v30, v31
	v_lshl_add_u64 v[30:31], v[122:123], 0, s[12:13]
	s_mov_b32 s12, 0x50000
	v_cvt_pk_bf16_f32 v29, v32, v33
	v_add_co_u32_e32 v32, vcc, s12, v122
	s_mov_b32 s12, 0x58000
	s_nop 0
	v_addc_co_u32_e32 v33, vcc, 0, v123, vcc
	global_store_dwordx4 v[32:33], v[26:29], off sc1
	v_cvt_pk_bf16_f32 v18, v18, v19
	v_cvt_pk_bf16_f32 v19, v20, v21
	v_cvt_pk_bf16_f32 v20, v10, v11
	v_cvt_pk_bf16_f32 v21, v12, v13
	global_store_dwordx4 v[30:31], v[18:21], off offset:256 sc1
	v_cvt_pk_bf16_f32 v10, v22, v23
	v_cvt_pk_bf16_f32 v11, v24, v25
	v_cvt_pk_bf16_f32 v12, v14, v15
	v_cvt_pk_bf16_f32 v13, v16, v17
	v_add_co_u32_e32 v16, vcc, s12, v122
	v_lshl_add_u64 v[14:15], v[122:123], 0, s[2:3]
	s_nop 0
	v_addc_co_u32_e32 v17, vcc, 0, v123, vcc
	s_andn2_b64 vcc, exec, s[54:55]
	s_mov_b64 s[54:55], -1
	global_store_dwordx4 v[16:17], v[10:13], off sc1
	v_cvt_pk_bf16_f32 v6, v6, v7
	v_cvt_pk_bf16_f32 v7, v8, v9
	v_cvt_pk_bf16_f32 v8, v2, v3
	v_cvt_pk_bf16_f32 v9, v4, v5
	global_store_dwordx4 v[14:15], v[6:9], off offset:256 sc1
	s_cbranch_vccnz .LBB0_634
	v_readlane_b32 s12, v244, 10
	v_readlane_b32 s13, v244, 11
	s_andn2_b64 vcc, exec, s[12:13]
	s_cbranch_vccnz .LBB0_633
	s_barrier
	s_branch .LBB0_633

.LBB0_655:
	s_mov_b32 s98, 0x3d372713
	s_mov_b32 s100, 0x3fcc422a
	s_mov_b32 s20, 0xbfb8aa3b
	s_mov_b32 s22, 1.0
	s_barrier
	v_and_b32_e32 v74, 63, v173
	v_and_b32_e32 v75, 15, v173
	s_lshl_b32 s24, s47, 13
	v_lshlrev_b32_e32 v75, 1, v75
	v_lshl_add_u32 v75, v198, 1, v75
	v_add_u32_e32 v75, s24, v75
	v_lshl_add_u32 v76, v74, 4, s24
	v_lshrrev_b32_e32 v77, 1, v74
	v_and_b32_e32 v74, 1, v74
	v_lshlrev_b32_e32 v77, 14, v77
	v_lshl_or_b32 v77, v74, 4, v77
	v_readfirstlane_b32 s18, v140
	v_readfirstlane_b32 s19, v141
	v_pk_mul_f32 v[2:3], v[114:115], s[98:99] op_sel_hi:[1,0]
	v_pk_mul_f32 v[2:3], v[114:115], v[2:3]
	v_pk_fma_f32 v[2:3], v[114:115], v[2:3], v[114:115]
	v_pk_mul_f32 v[2:3], v[2:3], s[100:101] op_sel_hi:[1,0]
	v_pk_mul_f32 v[2:3], v[2:3], s[20:21] op_sel_hi:[1,0]
	v_exp_f32_e32 v10, v2
	v_exp_f32_e32 v11, v3
	v_pk_mul_f32 v[4:5], v[116:117], s[98:99] op_sel_hi:[1,0]
	v_pk_mul_f32 v[4:5], v[116:117], v[4:5]
	v_pk_fma_f32 v[4:5], v[116:117], v[4:5], v[116:117]
	v_pk_mul_f32 v[4:5], v[4:5], s[100:101] op_sel_hi:[1,0]
	v_pk_mul_f32 v[4:5], v[4:5], s[20:21] op_sel_hi:[1,0]
	v_exp_f32_e32 v12, v4
	v_exp_f32_e32 v13, v5
	v_pk_add_f32 v[10:11], v[10:11], s[22:23] op_sel_hi:[1,0]
	v_rcp_f32_e32 v10, v10
	v_rcp_f32_e32 v11, v11
	v_pk_mul_f32 v[6:7], v[102:103], s[98:99] op_sel_hi:[1,0]
	v_pk_mul_f32 v[6:7], v[102:103], v[6:7]
	v_pk_fma_f32 v[6:7], v[102:103], v[6:7], v[102:103]
	v_pk_mul_f32 v[6:7], v[6:7], s[100:101] op_sel_hi:[1,0]
	v_pk_mul_f32 v[6:7], v[6:7], s[20:21] op_sel_hi:[1,0]
	v_exp_f32_e32 v14, v6
	v_exp_f32_e32 v15, v7
	v_pk_add_f32 v[12:13], v[12:13], s[22:23] op_sel_hi:[1,0]
	v_rcp_f32_e32 v12, v12
	v_rcp_f32_e32 v13, v13
	v_pk_mul_f32 v[10:11], v[114:115], v[10:11]
	v_cvt_pk_bf16_f32 v18, v10, v11
	ds_write_b16 v75, v18
	ds_write_b16_d16_hi v75, v18 offset:32
	v_pk_mul_f32 v[8:9], v[104:105], s[98:99] op_sel_hi:[1,0]
	v_pk_mul_f32 v[8:9], v[104:105], v[8:9]
	v_pk_fma_f32 v[8:9], v[104:105], v[8:9], v[104:105]
	v_pk_mul_f32 v[8:9], v[8:9], s[100:101] op_sel_hi:[1,0]
	v_pk_mul_f32 v[8:9], v[8:9], s[20:21] op_sel_hi:[1,0]
	v_exp_f32_e32 v16, v8
	v_exp_f32_e32 v17, v9
	v_pk_add_f32 v[14:15], v[14:15], s[22:23] op_sel_hi:[1,0]
	v_rcp_f32_e32 v14, v14
	v_rcp_f32_e32 v15, v15
	v_pk_mul_f32 v[12:13], v[116:117], v[12:13]
	v_cvt_pk_bf16_f32 v19, v12, v13
	ds_write_b16 v75, v19 offset:64
	ds_write_b16_d16_hi v75, v19 offset:96
	v_pk_mul_f32 v[2:3], v[86:87], s[98:99] op_sel_hi:[1,0]
	v_pk_mul_f32 v[2:3], v[86:87], v[2:3]
	v_pk_fma_f32 v[2:3], v[86:87], v[2:3], v[86:87]
	v_pk_mul_f32 v[2:3], v[2:3], s[100:101] op_sel_hi:[1,0]
	v_pk_mul_f32 v[2:3], v[2:3], s[20:21] op_sel_hi:[1,0]
	v_exp_f32_e32 v10, v2
	v_exp_f32_e32 v11, v3
	v_pk_add_f32 v[16:17], v[16:17], s[22:23] op_sel_hi:[1,0]
	v_rcp_f32_e32 v16, v16
	v_rcp_f32_e32 v17, v17
	v_pk_mul_f32 v[14:15], v[102:103], v[14:15]
	v_cvt_pk_bf16_f32 v20, v14, v15
	ds_write_b16 v75, v20 offset:512
	ds_write_b16_d16_hi v75, v20 offset:544
	v_pk_mul_f32 v[4:5], v[88:89], s[98:99] op_sel_hi:[1,0]
	v_pk_mul_f32 v[4:5], v[88:89], v[4:5]
	v_pk_fma_f32 v[4:5], v[88:89], v[4:5], v[88:89]
	v_pk_mul_f32 v[4:5], v[4:5], s[100:101] op_sel_hi:[1,0]
	v_pk_mul_f32 v[4:5], v[4:5], s[20:21] op_sel_hi:[1,0]
	v_exp_f32_e32 v12, v4
	v_exp_f32_e32 v13, v5
	v_pk_add_f32 v[10:11], v[10:11], s[22:23] op_sel_hi:[1,0]
	v_rcp_f32_e32 v10, v10
	v_rcp_f32_e32 v11, v11
	v_pk_mul_f32 v[16:17], v[104:105], v[16:17]
	v_cvt_pk_bf16_f32 v21, v16, v17
	ds_write_b16 v75, v21 offset:576
	ds_write_b16_d16_hi v75, v21 offset:608
	v_pk_mul_f32 v[6:7], v[70:71], s[98:99] op_sel_hi:[1,0]
	v_pk_mul_f32 v[6:7], v[70:71], v[6:7]
	v_pk_fma_f32 v[6:7], v[70:71], v[6:7], v[70:71]
	v_pk_mul_f32 v[6:7], v[6:7], s[100:101] op_sel_hi:[1,0]
	v_pk_mul_f32 v[6:7], v[6:7], s[20:21] op_sel_hi:[1,0]
	v_exp_f32_e32 v14, v6
	v_exp_f32_e32 v15, v7
	v_pk_add_f32 v[12:13], v[12:13], s[22:23] op_sel_hi:[1,0]
	v_rcp_f32_e32 v12, v12
	v_rcp_f32_e32 v13, v13
	v_pk_mul_f32 v[10:11], v[86:87], v[10:11]
	v_cvt_pk_bf16_f32 v18, v10, v11
	ds_write_b16 v75, v18 offset:1024
	ds_write_b16_d16_hi v75, v18 offset:1056
	v_pk_mul_f32 v[8:9], v[72:73], s[98:99] op_sel_hi:[1,0]
	v_pk_mul_f32 v[8:9], v[72:73], v[8:9]
	v_pk_fma_f32 v[8:9], v[72:73], v[8:9], v[72:73]
	v_pk_mul_f32 v[8:9], v[8:9], s[100:101] op_sel_hi:[1,0]
	v_pk_mul_f32 v[8:9], v[8:9], s[20:21] op_sel_hi:[1,0]
	v_exp_f32_e32 v16, v8
	v_exp_f32_e32 v17, v9
	v_pk_add_f32 v[14:15], v[14:15], s[22:23] op_sel_hi:[1,0]
	v_rcp_f32_e32 v14, v14
	v_rcp_f32_e32 v15, v15
	v_pk_mul_f32 v[12:13], v[88:89], v[12:13]
	v_cvt_pk_bf16_f32 v19, v12, v13
	ds_write_b16 v75, v19 offset:1088
	ds_write_b16_d16_hi v75, v19 offset:1120
	v_pk_mul_f32 v[2:3], v[62:63], s[98:99] op_sel_hi:[1,0]
	v_pk_mul_f32 v[2:3], v[62:63], v[2:3]
	v_pk_fma_f32 v[2:3], v[62:63], v[2:3], v[62:63]
	v_pk_mul_f32 v[2:3], v[2:3], s[100:101] op_sel_hi:[1,0]
	v_pk_mul_f32 v[2:3], v[2:3], s[20:21] op_sel_hi:[1,0]
	v_exp_f32_e32 v10, v2
	v_exp_f32_e32 v11, v3
	v_pk_add_f32 v[16:17], v[16:17], s[22:23] op_sel_hi:[1,0]
	v_rcp_f32_e32 v16, v16
	v_rcp_f32_e32 v17, v17
	v_pk_mul_f32 v[14:15], v[70:71], v[14:15]
	v_cvt_pk_bf16_f32 v20, v14, v15
	ds_write_b16 v75, v20 offset:1536
	ds_write_b16_d16_hi v75, v20 offset:1568
	v_pk_mul_f32 v[4:5], v[64:65], s[98:99] op_sel_hi:[1,0]
	v_pk_mul_f32 v[4:5], v[64:65], v[4:5]
	v_pk_fma_f32 v[4:5], v[64:65], v[4:5], v[64:65]
	v_pk_mul_f32 v[4:5], v[4:5], s[100:101] op_sel_hi:[1,0]
	v_pk_mul_f32 v[4:5], v[4:5], s[20:21] op_sel_hi:[1,0]
	v_exp_f32_e32 v12, v4
	v_exp_f32_e32 v13, v5
	v_pk_add_f32 v[10:11], v[10:11], s[22:23] op_sel_hi:[1,0]
	v_rcp_f32_e32 v10, v10
	v_rcp_f32_e32 v11, v11
	v_pk_mul_f32 v[16:17], v[72:73], v[16:17]
	v_cvt_pk_bf16_f32 v21, v16, v17
	ds_write_b16 v75, v21 offset:1600
	ds_write_b16_d16_hi v75, v21 offset:1632
	v_pk_mul_f32 v[6:7], v[54:55], s[98:99] op_sel_hi:[1,0]
	v_pk_mul_f32 v[6:7], v[54:55], v[6:7]
	v_pk_fma_f32 v[6:7], v[54:55], v[6:7], v[54:55]
	v_pk_mul_f32 v[6:7], v[6:7], s[100:101] op_sel_hi:[1,0]
	v_pk_mul_f32 v[6:7], v[6:7], s[20:21] op_sel_hi:[1,0]
	v_exp_f32_e32 v14, v6
	v_exp_f32_e32 v15, v7
	v_pk_add_f32 v[12:13], v[12:13], s[22:23] op_sel_hi:[1,0]
	v_rcp_f32_e32 v12, v12
	v_rcp_f32_e32 v13, v13
	v_pk_mul_f32 v[10:11], v[62:63], v[10:11]
	v_cvt_pk_bf16_f32 v18, v10, v11
	ds_write_b16 v75, v18 offset:2048
	ds_write_b16_d16_hi v75, v18 offset:2080
	v_pk_mul_f32 v[8:9], v[56:57], s[98:99] op_sel_hi:[1,0]
	v_pk_mul_f32 v[8:9], v[56:57], v[8:9]
	v_pk_fma_f32 v[8:9], v[56:57], v[8:9], v[56:57]
	v_pk_mul_f32 v[8:9], v[8:9], s[100:101] op_sel_hi:[1,0]
	v_pk_mul_f32 v[8:9], v[8:9], s[20:21] op_sel_hi:[1,0]
	v_exp_f32_e32 v16, v8
	v_exp_f32_e32 v17, v9
	v_pk_add_f32 v[14:15], v[14:15], s[22:23] op_sel_hi:[1,0]
	v_rcp_f32_e32 v14, v14
	v_rcp_f32_e32 v15, v15
	v_pk_mul_f32 v[12:13], v[64:65], v[12:13]
	v_cvt_pk_bf16_f32 v19, v12, v13
	ds_write_b16 v75, v19 offset:2112
	ds_write_b16_d16_hi v75, v19 offset:2144
	v_pk_mul_f32 v[2:3], v[46:47], s[98:99] op_sel_hi:[1,0]
	v_pk_mul_f32 v[2:3], v[46:47], v[2:3]
	v_pk_fma_f32 v[2:3], v[46:47], v[2:3], v[46:47]
	v_pk_mul_f32 v[2:3], v[2:3], s[100:101] op_sel_hi:[1,0]
	v_pk_mul_f32 v[2:3], v[2:3], s[20:21] op_sel_hi:[1,0]
	v_exp_f32_e32 v10, v2
	v_exp_f32_e32 v11, v3
	v_pk_add_f32 v[16:17], v[16:17], s[22:23] op_sel_hi:[1,0]
	v_rcp_f32_e32 v16, v16
	v_rcp_f32_e32 v17, v17
	v_pk_mul_f32 v[14:15], v[54:55], v[14:15]
	v_cvt_pk_bf16_f32 v20, v14, v15
	ds_write_b16 v75, v20 offset:2560
	ds_write_b16_d16_hi v75, v20 offset:2592
	v_pk_mul_f32 v[4:5], v[48:49], s[98:99] op_sel_hi:[1,0]
	v_pk_mul_f32 v[4:5], v[48:49], v[4:5]
	v_pk_fma_f32 v[4:5], v[48:49], v[4:5], v[48:49]
	v_pk_mul_f32 v[4:5], v[4:5], s[100:101] op_sel_hi:[1,0]
	v_pk_mul_f32 v[4:5], v[4:5], s[20:21] op_sel_hi:[1,0]
	v_exp_f32_e32 v12, v4
	v_exp_f32_e32 v13, v5
	v_pk_add_f32 v[10:11], v[10:11], s[22:23] op_sel_hi:[1,0]
	v_rcp_f32_e32 v10, v10
	v_rcp_f32_e32 v11, v11
	v_pk_mul_f32 v[16:17], v[56:57], v[16:17]
	v_cvt_pk_bf16_f32 v21, v16, v17
	ds_write_b16 v75, v21 offset:2624
	ds_write_b16_d16_hi v75, v21 offset:2656
	v_pk_mul_f32 v[6:7], v[38:39], s[98:99] op_sel_hi:[1,0]
	v_pk_mul_f32 v[6:7], v[38:39], v[6:7]
	v_pk_fma_f32 v[6:7], v[38:39], v[6:7], v[38:39]
	v_pk_mul_f32 v[6:7], v[6:7], s[100:101] op_sel_hi:[1,0]
	v_pk_mul_f32 v[6:7], v[6:7], s[20:21] op_sel_hi:[1,0]
	v_exp_f32_e32 v14, v6
	v_exp_f32_e32 v15, v7
	v_pk_add_f32 v[12:13], v[12:13], s[22:23] op_sel_hi:[1,0]
	v_rcp_f32_e32 v12, v12
	v_rcp_f32_e32 v13, v13
	v_pk_mul_f32 v[10:11], v[46:47], v[10:11]
	v_cvt_pk_bf16_f32 v18, v10, v11
	ds_write_b16 v75, v18 offset:3072
	ds_write_b16_d16_hi v75, v18 offset:3104
	v_pk_mul_f32 v[8:9], v[40:41], s[98:99] op_sel_hi:[1,0]
	v_pk_mul_f32 v[8:9], v[40:41], v[8:9]
	v_pk_fma_f32 v[8:9], v[40:41], v[8:9], v[40:41]
	v_pk_mul_f32 v[8:9], v[8:9], s[100:101] op_sel_hi:[1,0]
	v_pk_mul_f32 v[8:9], v[8:9], s[20:21] op_sel_hi:[1,0]
	v_exp_f32_e32 v16, v8
	v_exp_f32_e32 v17, v9
	v_pk_add_f32 v[14:15], v[14:15], s[22:23] op_sel_hi:[1,0]
	v_rcp_f32_e32 v14, v14
	v_rcp_f32_e32 v15, v15
	v_pk_mul_f32 v[12:13], v[48:49], v[12:13]
	v_cvt_pk_bf16_f32 v19, v12, v13
	ds_write_b16 v75, v19 offset:3136
	ds_write_b16_d16_hi v75, v19 offset:3168
	v_pk_mul_f32 v[2:3], v[110:111], s[98:99] op_sel_hi:[1,0]
	v_pk_mul_f32 v[2:3], v[110:111], v[2:3]
	v_pk_fma_f32 v[2:3], v[110:111], v[2:3], v[110:111]
	v_pk_mul_f32 v[2:3], v[2:3], s[100:101] op_sel_hi:[1,0]
	v_pk_mul_f32 v[2:3], v[2:3], s[20:21] op_sel_hi:[1,0]
	v_exp_f32_e32 v10, v2
	v_exp_f32_e32 v11, v3
	v_pk_add_f32 v[16:17], v[16:17], s[22:23] op_sel_hi:[1,0]
	v_rcp_f32_e32 v16, v16
	v_rcp_f32_e32 v17, v17
	v_pk_mul_f32 v[14:15], v[38:39], v[14:15]
	v_cvt_pk_bf16_f32 v20, v14, v15
	ds_write_b16 v75, v20 offset:3584
	ds_write_b16_d16_hi v75, v20 offset:3616
	v_pk_mul_f32 v[4:5], v[112:113], s[98:99] op_sel_hi:[1,0]
	v_pk_mul_f32 v[4:5], v[112:113], v[4:5]
	v_pk_fma_f32 v[4:5], v[112:113], v[4:5], v[112:113]
	v_pk_mul_f32 v[4:5], v[4:5], s[100:101] op_sel_hi:[1,0]
	v_pk_mul_f32 v[4:5], v[4:5], s[20:21] op_sel_hi:[1,0]
	v_exp_f32_e32 v12, v4
	v_exp_f32_e32 v13, v5
	v_pk_add_f32 v[10:11], v[10:11], s[22:23] op_sel_hi:[1,0]
	v_rcp_f32_e32 v10, v10
	v_rcp_f32_e32 v11, v11
	v_pk_mul_f32 v[16:17], v[40:41], v[16:17]
	v_cvt_pk_bf16_f32 v21, v16, v17
	ds_write_b16 v75, v21 offset:3648
	ds_write_b16_d16_hi v75, v21 offset:3680
	v_pk_mul_f32 v[6:7], v[94:95], s[98:99] op_sel_hi:[1,0]
	v_pk_mul_f32 v[6:7], v[94:95], v[6:7]
	v_pk_fma_f32 v[6:7], v[94:95], v[6:7], v[94:95]
	v_pk_mul_f32 v[6:7], v[6:7], s[100:101] op_sel_hi:[1,0]
	v_pk_mul_f32 v[6:7], v[6:7], s[20:21] op_sel_hi:[1,0]
	v_exp_f32_e32 v14, v6
	v_exp_f32_e32 v15, v7
	v_pk_add_f32 v[12:13], v[12:13], s[22:23] op_sel_hi:[1,0]
	v_rcp_f32_e32 v12, v12
	v_rcp_f32_e32 v13, v13
	v_pk_mul_f32 v[10:11], v[110:111], v[10:11]
	v_cvt_pk_bf16_f32 v18, v10, v11
	ds_write_b16 v75, v18 offset:4096
	ds_write_b16_d16_hi v75, v18 offset:4128
	v_pk_mul_f32 v[8:9], v[96:97], s[98:99] op_sel_hi:[1,0]
	v_pk_mul_f32 v[8:9], v[96:97], v[8:9]
	v_pk_fma_f32 v[8:9], v[96:97], v[8:9], v[96:97]
	v_pk_mul_f32 v[8:9], v[8:9], s[100:101] op_sel_hi:[1,0]
	v_pk_mul_f32 v[8:9], v[8:9], s[20:21] op_sel_hi:[1,0]
	v_exp_f32_e32 v16, v8
	v_exp_f32_e32 v17, v9
	v_pk_add_f32 v[14:15], v[14:15], s[22:23] op_sel_hi:[1,0]
	v_rcp_f32_e32 v14, v14
	v_rcp_f32_e32 v15, v15
	v_pk_mul_f32 v[12:13], v[112:113], v[12:13]
	v_cvt_pk_bf16_f32 v19, v12, v13
	ds_write_b16 v75, v19 offset:4160
	ds_write_b16_d16_hi v75, v19 offset:4192
	v_pk_mul_f32 v[2:3], v[78:79], s[98:99] op_sel_hi:[1,0]
	v_pk_mul_f32 v[2:3], v[78:79], v[2:3]
	v_pk_fma_f32 v[2:3], v[78:79], v[2:3], v[78:79]
	v_pk_mul_f32 v[2:3], v[2:3], s[100:101] op_sel_hi:[1,0]
	v_pk_mul_f32 v[2:3], v[2:3], s[20:21] op_sel_hi:[1,0]
	v_exp_f32_e32 v10, v2
	v_exp_f32_e32 v11, v3
	v_pk_add_f32 v[16:17], v[16:17], s[22:23] op_sel_hi:[1,0]
	v_rcp_f32_e32 v16, v16
	v_rcp_f32_e32 v17, v17
	v_pk_mul_f32 v[14:15], v[94:95], v[14:15]
	v_cvt_pk_bf16_f32 v20, v14, v15
	ds_write_b16 v75, v20 offset:4608
	ds_write_b16_d16_hi v75, v20 offset:4640
	v_pk_mul_f32 v[4:5], v[80:81], s[98:99] op_sel_hi:[1,0]
	v_pk_mul_f32 v[4:5], v[80:81], v[4:5]
	v_pk_fma_f32 v[4:5], v[80:81], v[4:5], v[80:81]
	v_pk_mul_f32 v[4:5], v[4:5], s[100:101] op_sel_hi:[1,0]
	v_pk_mul_f32 v[4:5], v[4:5], s[20:21] op_sel_hi:[1,0]
	v_exp_f32_e32 v12, v4
	v_exp_f32_e32 v13, v5
	v_pk_add_f32 v[10:11], v[10:11], s[22:23] op_sel_hi:[1,0]
	v_rcp_f32_e32 v10, v10
	v_rcp_f32_e32 v11, v11
	v_pk_mul_f32 v[16:17], v[96:97], v[16:17]
	v_cvt_pk_bf16_f32 v21, v16, v17
	ds_write_b16 v75, v21 offset:4672
	ds_write_b16_d16_hi v75, v21 offset:4704
	v_pk_mul_f32 v[6:7], v[66:67], s[98:99] op_sel_hi:[1,0]
	v_pk_mul_f32 v[6:7], v[66:67], v[6:7]
	v_pk_fma_f32 v[6:7], v[66:67], v[6:7], v[66:67]
	v_pk_mul_f32 v[6:7], v[6:7], s[100:101] op_sel_hi:[1,0]
	v_pk_mul_f32 v[6:7], v[6:7], s[20:21] op_sel_hi:[1,0]
	v_exp_f32_e32 v14, v6
	v_exp_f32_e32 v15, v7
	v_pk_add_f32 v[12:13], v[12:13], s[22:23] op_sel_hi:[1,0]
	v_rcp_f32_e32 v12, v12
	v_rcp_f32_e32 v13, v13
	v_pk_mul_f32 v[10:11], v[78:79], v[10:11]
	v_cvt_pk_bf16_f32 v18, v10, v11
	ds_write_b16 v75, v18 offset:5120
	ds_write_b16_d16_hi v75, v18 offset:5152
	v_pk_mul_f32 v[8:9], v[68:69], s[98:99] op_sel_hi:[1,0]
	v_pk_mul_f32 v[8:9], v[68:69], v[8:9]
	v_pk_fma_f32 v[8:9], v[68:69], v[8:9], v[68:69]
	v_pk_mul_f32 v[8:9], v[8:9], s[100:101] op_sel_hi:[1,0]
	v_pk_mul_f32 v[8:9], v[8:9], s[20:21] op_sel_hi:[1,0]
	v_exp_f32_e32 v16, v8
	v_exp_f32_e32 v17, v9
	v_pk_add_f32 v[14:15], v[14:15], s[22:23] op_sel_hi:[1,0]
	v_rcp_f32_e32 v14, v14
	v_rcp_f32_e32 v15, v15
	v_pk_mul_f32 v[12:13], v[80:81], v[12:13]
	v_cvt_pk_bf16_f32 v19, v12, v13
	ds_write_b16 v75, v19 offset:5184
	ds_write_b16_d16_hi v75, v19 offset:5216
	v_pk_mul_f32 v[2:3], v[58:59], s[98:99] op_sel_hi:[1,0]
	v_pk_mul_f32 v[2:3], v[58:59], v[2:3]
	v_pk_fma_f32 v[2:3], v[58:59], v[2:3], v[58:59]
	v_pk_mul_f32 v[2:3], v[2:3], s[100:101] op_sel_hi:[1,0]
	v_pk_mul_f32 v[2:3], v[2:3], s[20:21] op_sel_hi:[1,0]
	v_exp_f32_e32 v10, v2
	v_exp_f32_e32 v11, v3
	v_pk_add_f32 v[16:17], v[16:17], s[22:23] op_sel_hi:[1,0]
	v_rcp_f32_e32 v16, v16
	v_rcp_f32_e32 v17, v17
	v_pk_mul_f32 v[14:15], v[66:67], v[14:15]
	v_cvt_pk_bf16_f32 v20, v14, v15
	ds_write_b16 v75, v20 offset:5632
	ds_write_b16_d16_hi v75, v20 offset:5664
	v_pk_mul_f32 v[4:5], v[60:61], s[98:99] op_sel_hi:[1,0]
	v_pk_mul_f32 v[4:5], v[60:61], v[4:5]
	v_pk_fma_f32 v[4:5], v[60:61], v[4:5], v[60:61]
	v_pk_mul_f32 v[4:5], v[4:5], s[100:101] op_sel_hi:[1,0]
	v_pk_mul_f32 v[4:5], v[4:5], s[20:21] op_sel_hi:[1,0]
	v_exp_f32_e32 v12, v4
	v_exp_f32_e32 v13, v5
	v_pk_add_f32 v[10:11], v[10:11], s[22:23] op_sel_hi:[1,0]
	v_rcp_f32_e32 v10, v10
	v_rcp_f32_e32 v11, v11
	v_pk_mul_f32 v[16:17], v[68:69], v[16:17]
	v_cvt_pk_bf16_f32 v21, v16, v17
	ds_write_b16 v75, v21 offset:5696
	ds_write_b16_d16_hi v75, v21 offset:5728
	v_pk_mul_f32 v[6:7], v[50:51], s[98:99] op_sel_hi:[1,0]
	v_pk_mul_f32 v[6:7], v[50:51], v[6:7]
	v_pk_fma_f32 v[6:7], v[50:51], v[6:7], v[50:51]
	v_pk_mul_f32 v[6:7], v[6:7], s[100:101] op_sel_hi:[1,0]
	v_pk_mul_f32 v[6:7], v[6:7], s[20:21] op_sel_hi:[1,0]
	v_exp_f32_e32 v14, v6
	v_exp_f32_e32 v15, v7
	v_pk_add_f32 v[12:13], v[12:13], s[22:23] op_sel_hi:[1,0]
	v_rcp_f32_e32 v12, v12
	v_rcp_f32_e32 v13, v13
	v_pk_mul_f32 v[10:11], v[58:59], v[10:11]
	v_cvt_pk_bf16_f32 v18, v10, v11
	ds_write_b16 v75, v18 offset:6144
	ds_write_b16_d16_hi v75, v18 offset:6176
	v_pk_mul_f32 v[8:9], v[52:53], s[98:99] op_sel_hi:[1,0]
	v_pk_mul_f32 v[8:9], v[52:53], v[8:9]
	v_pk_fma_f32 v[8:9], v[52:53], v[8:9], v[52:53]
	v_pk_mul_f32 v[8:9], v[8:9], s[100:101] op_sel_hi:[1,0]
	v_pk_mul_f32 v[8:9], v[8:9], s[20:21] op_sel_hi:[1,0]
	v_exp_f32_e32 v16, v8
	v_exp_f32_e32 v17, v9
	v_pk_add_f32 v[14:15], v[14:15], s[22:23] op_sel_hi:[1,0]
	v_rcp_f32_e32 v14, v14
	v_rcp_f32_e32 v15, v15
	v_pk_mul_f32 v[12:13], v[60:61], v[12:13]
	v_cvt_pk_bf16_f32 v19, v12, v13
	ds_write_b16 v75, v19 offset:6208
	ds_write_b16_d16_hi v75, v19 offset:6240
	v_pk_mul_f32 v[2:3], v[42:43], s[98:99] op_sel_hi:[1,0]
	v_pk_mul_f32 v[2:3], v[42:43], v[2:3]
	v_pk_fma_f32 v[2:3], v[42:43], v[2:3], v[42:43]
	v_pk_mul_f32 v[2:3], v[2:3], s[100:101] op_sel_hi:[1,0]
	v_pk_mul_f32 v[2:3], v[2:3], s[20:21] op_sel_hi:[1,0]
	v_exp_f32_e32 v10, v2
	v_exp_f32_e32 v11, v3
	v_pk_add_f32 v[16:17], v[16:17], s[22:23] op_sel_hi:[1,0]
	v_rcp_f32_e32 v16, v16
	v_rcp_f32_e32 v17, v17
	v_pk_mul_f32 v[14:15], v[50:51], v[14:15]
	v_cvt_pk_bf16_f32 v20, v14, v15
	ds_write_b16 v75, v20 offset:6656
	ds_write_b16_d16_hi v75, v20 offset:6688
	v_pk_mul_f32 v[4:5], v[44:45], s[98:99] op_sel_hi:[1,0]
	v_pk_mul_f32 v[4:5], v[44:45], v[4:5]
	v_pk_fma_f32 v[4:5], v[44:45], v[4:5], v[44:45]
	v_pk_mul_f32 v[4:5], v[4:5], s[100:101] op_sel_hi:[1,0]
	v_pk_mul_f32 v[4:5], v[4:5], s[20:21] op_sel_hi:[1,0]
	v_exp_f32_e32 v12, v4
	v_exp_f32_e32 v13, v5
	v_pk_add_f32 v[10:11], v[10:11], s[22:23] op_sel_hi:[1,0]
	v_rcp_f32_e32 v10, v10
	v_rcp_f32_e32 v11, v11
	v_pk_mul_f32 v[16:17], v[52:53], v[16:17]
	v_cvt_pk_bf16_f32 v21, v16, v17
	ds_write_b16 v75, v21 offset:6720
	ds_write_b16_d16_hi v75, v21 offset:6752
	v_pk_mul_f32 v[6:7], v[34:35], s[98:99] op_sel_hi:[1,0]
	v_pk_mul_f32 v[6:7], v[34:35], v[6:7]
	v_pk_fma_f32 v[6:7], v[34:35], v[6:7], v[34:35]
	v_pk_mul_f32 v[6:7], v[6:7], s[100:101] op_sel_hi:[1,0]
	v_pk_mul_f32 v[6:7], v[6:7], s[20:21] op_sel_hi:[1,0]
	v_exp_f32_e32 v14, v6
	v_exp_f32_e32 v15, v7
	v_pk_add_f32 v[12:13], v[12:13], s[22:23] op_sel_hi:[1,0]
	v_rcp_f32_e32 v12, v12
	v_rcp_f32_e32 v13, v13
	v_pk_mul_f32 v[10:11], v[42:43], v[10:11]
	v_cvt_pk_bf16_f32 v18, v10, v11
	ds_write_b16 v75, v18 offset:7168
	ds_write_b16_d16_hi v75, v18 offset:7200
	v_pk_mul_f32 v[8:9], v[36:37], s[98:99] op_sel_hi:[1,0]
	v_pk_mul_f32 v[8:9], v[36:37], v[8:9]
	v_pk_fma_f32 v[8:9], v[36:37], v[8:9], v[36:37]
	v_pk_mul_f32 v[8:9], v[8:9], s[100:101] op_sel_hi:[1,0]
	v_pk_mul_f32 v[8:9], v[8:9], s[20:21] op_sel_hi:[1,0]
	v_exp_f32_e32 v16, v8
	v_exp_f32_e32 v17, v9
	v_pk_add_f32 v[14:15], v[14:15], s[22:23] op_sel_hi:[1,0]
	v_rcp_f32_e32 v14, v14
	v_rcp_f32_e32 v15, v15
	v_pk_mul_f32 v[12:13], v[44:45], v[12:13]
	v_cvt_pk_bf16_f32 v19, v12, v13
	ds_write_b16 v75, v19 offset:7232
	ds_write_b16_d16_hi v75, v19 offset:7264
	v_pk_add_f32 v[16:17], v[16:17], s[22:23] op_sel_hi:[1,0]
	v_rcp_f32_e32 v16, v16
	v_rcp_f32_e32 v17, v17
	v_pk_mul_f32 v[14:15], v[34:35], v[14:15]
	v_cvt_pk_bf16_f32 v20, v14, v15
	ds_write_b16 v75, v20 offset:7680
	ds_write_b16_d16_hi v75, v20 offset:7712
	v_pk_mul_f32 v[16:17], v[36:37], v[16:17]
	v_cvt_pk_bf16_f32 v21, v16, v17
	ds_write_b16 v75, v21 offset:7744
	ds_write_b16_d16_hi v75, v21 offset:7776
	s_waitcnt lgkmcnt(0)
	ds_read_b128 v[34:37], v76
	ds_read_b128 v[38:41], v76 offset:1024
	ds_read_b128 v[42:45], v76 offset:2048
	ds_read_b128 v[46:49], v76 offset:3072
	ds_read_b128 v[50:53], v76 offset:4096
	ds_read_b128 v[54:57], v76 offset:5120
	ds_read_b128 v[58:61], v76 offset:6144
	ds_read_b128 v[62:65], v76 offset:7168
	s_lshl_b32 s24, s91, 4
	s_add_i32 s25, s24, s47
	s_lshl_b32 s25, s25, 10
	s_add_u32 s48, s18, s25
	s_addc_u32 s49, s19, 0
	s_add_i32 s25, s24, s47
	s_addk_i32 s25, 512
	s_lshl_b32 s25, s25, 10
	s_add_u32 s50, s18, s25
	s_addc_u32 s51, s19, 0
	s_add_i32 s25, s24, s47
	s_addk_i32 s25, 1024
	s_lshl_b32 s25, s25, 10
	s_add_u32 s52, s18, s25
	s_addc_u32 s53, s19, 0
	s_add_i32 s25, s24, s47
	s_addk_i32 s25, 1536
	s_lshl_b32 s25, s25, 10
	s_add_u32 s54, s18, s25
	s_addc_u32 s55, s19, 0
	s_add_i32 s25, s24, s14
	s_lshl_b32 s25, s25, 10
	s_add_u32 s56, s18, s25
	s_addc_u32 s57, s19, 0
	s_add_i32 s25, s24, s14
	s_addk_i32 s25, 512
	s_lshl_b32 s25, s25, 10
	s_add_u32 s58, s18, s25
	s_addc_u32 s59, s19, 0
	s_add_i32 s25, s24, s14
	s_addk_i32 s25, 1024
	s_lshl_b32 s25, s25, 10
	s_add_u32 s60, s18, s25
	s_addc_u32 s61, s19, 0
	s_add_i32 s25, s24, s14
	s_addk_i32 s25, 1536
	s_lshl_b32 s25, s25, 10
	s_add_u32 s62, s18, s25
	s_addc_u32 s63, s19, 0
	s_waitcnt lgkmcnt(7)
	global_store_dwordx4 v77, v[34:37], s[48:49] sc1
	s_waitcnt lgkmcnt(6)
	global_store_dwordx4 v77, v[38:41], s[50:51] sc1
	s_waitcnt lgkmcnt(5)
	global_store_dwordx4 v77, v[42:45], s[52:53] sc1
	s_waitcnt lgkmcnt(4)
	global_store_dwordx4 v77, v[46:49], s[54:55] sc1
	s_waitcnt lgkmcnt(3)
	global_store_dwordx4 v77, v[50:53], s[56:57] sc1
	s_waitcnt lgkmcnt(2)
	global_store_dwordx4 v77, v[54:57], s[58:59] sc1
	s_waitcnt lgkmcnt(1)
	global_store_dwordx4 v77, v[58:61], s[60:61] sc1
	s_waitcnt lgkmcnt(0)
	global_store_dwordx4 v77, v[62:65], s[62:63] sc1

.LBB0_789:
	s_waitcnt lgkmcnt(0)
	v_mul_f32_e32 v127, v127, v199
	v_mul_f32_e32 v127, 0xbfb8aa3b, v127
	v_mul_f32_e32 v128, v128, v199
	v_exp_f32_e32 v127, v127
	v_mul_f32_e32 v128, 0xbfb8aa3b, v128
	v_mul_f32_e32 v129, v129, v199
	v_mul_f32_e32 v126, v126, v199
	v_exp_f32_e32 v128, v128
	v_mul_f32_e32 v129, 0xbfb8aa3b, v129
	v_mul_f32_e32 v122, v122, v199
	v_mul_f32_e32 v126, 0xbfb8aa3b, v126
	v_exp_f32_e32 v129, v129
	v_mul_f32_e32 v122, 0xbfb8aa3b, v122
	v_exp_f32_e32 v126, v126
	v_exp_f32_e32 v122, v122
	v_add_f32_e32 v127, 1.0, v127
	v_rcp_f32_e32 v127, v127
	v_add_f32_e32 v128, 1.0, v128
	v_mul_f32_e32 v123, v123, v199
	v_rcp_f32_e32 v128, v128
	v_add_f32_e32 v129, 1.0, v129
	v_mul_f32_e32 v123, 0xbfb8aa3b, v123
	v_mul_f32_e32 v124, v124, v199
	v_add_f32_e32 v126, 1.0, v126
	v_exp_f32_e32 v123, v123
	v_rcp_f32_e32 v129, v129
	v_add_f32_e32 v122, 1.0, v122
	v_mul_f32_e32 v124, 0xbfb8aa3b, v124
	v_mul_f32_e32 v125, v125, v199
	s_waitcnt vmcnt(0)
	v_lshlrev_b32_e32 v202, 16, v158
	v_and_b32_e32 v158, 0xffff0000, v158
	v_rcp_f32_e32 v126, v126
	v_rcp_f32_e32 v122, v122
	v_exp_f32_e32 v124, v124
	v_mul_f32_e32 v125, 0xbfb8aa3b, v125
	v_lshlrev_b32_e32 v216, 16, v154
	v_and_b32_e32 v154, 0xffff0000, v154
	v_lshlrev_b32_e32 v203, 16, v159
	v_exp_f32_e32 v125, v125
	v_fmac_f32_e32 v154, v127, v158
	v_lshlrev_b32_e32 v158, 16, v155
	v_mul_f32_e32 v118, v118, v199
	v_and_b32_e32 v159, 0xffff0000, v159
	v_fmac_f32_e32 v158, v128, v203
	v_and_b32_e32 v128, 0xffff0000, v155
	v_mul_f32_e32 v118, 0xbfb8aa3b, v118
	v_mul_f32_e32 v119, v119, v199
	v_lshlrev_b32_e32 v214, 16, v160
	v_add_f32_e32 v123, 1.0, v123
	v_fmac_f32_e32 v128, v129, v159
	v_lshlrev_b32_e32 v129, 16, v156
	v_exp_f32_e32 v118, v118
	v_mul_f32_e32 v119, 0xbfb8aa3b, v119
	v_mul_f32_e32 v120, v120, v199
	v_rcp_f32_e32 v123, v123
	v_add_f32_e32 v124, 1.0, v124
	v_fmac_f32_e32 v216, v126, v202
	v_fmac_f32_e32 v129, v122, v214
	v_cvt_pk_bf16_f32 v122, v216, v154
	v_mul_f32_e32 v154, v154, v154
	v_exp_f32_e32 v119, v119
	v_mul_f32_e32 v120, 0xbfb8aa3b, v120
	v_mul_f32_e32 v121, v121, v199
	v_rcp_f32_e32 v124, v124
	v_add_f32_e32 v125, 1.0, v125
	v_fmac_f32_e32 v154, v216, v216
	v_exp_f32_e32 v120, v120
	v_mul_f32_e32 v121, 0xbfb8aa3b, v121
	v_mul_f32_e32 v114, v114, v199
	v_mul_f32_e32 v115, v115, v199
	v_rcp_f32_e32 v125, v125
	v_fmac_f32_e32 v154, v158, v158
	v_exp_f32_e32 v121, v121
	v_mul_f32_e32 v114, 0xbfb8aa3b, v114
	v_mul_f32_e32 v115, 0xbfb8aa3b, v115
	v_and_b32_e32 v160, 0xffff0000, v160
	v_and_b32_e32 v155, 0xffff0000, v156
	v_fmac_f32_e32 v154, v128, v128
	v_add_f32_e32 v118, 1.0, v118
	v_exp_f32_e32 v114, v114
	v_exp_f32_e32 v115, v115
	v_mul_f32_e32 v116, v116, v199
	v_lshlrev_b32_e32 v215, 16, v161
	v_fmac_f32_e32 v155, v123, v160
	v_lshlrev_b32_e32 v156, 16, v157
	v_fmac_f32_e32 v154, v129, v129
	v_rcp_f32_e32 v118, v118
	v_add_f32_e32 v119, 1.0, v119
	v_mul_f32_e32 v116, 0xbfb8aa3b, v116
	v_mul_f32_e32 v117, v117, v199
	v_and_b32_e32 v161, 0xffff0000, v161
	v_fmac_f32_e32 v156, v124, v215
	v_and_b32_e32 v157, 0xffff0000, v157
	v_fmac_f32_e32 v154, v155, v155
	v_rcp_f32_e32 v119, v119
	v_add_f32_e32 v120, 1.0, v120
	v_exp_f32_e32 v116, v116
	v_mul_f32_e32 v117, 0xbfb8aa3b, v117
	v_fmac_f32_e32 v157, v125, v161
	v_fmac_f32_e32 v154, v156, v156
	v_rcp_f32_e32 v120, v120
	v_add_f32_e32 v121, 1.0, v121
	v_exp_f32_e32 v117, v117
	v_cvt_pk_bf16_f32 v123, v158, v128
	v_cvt_pk_bf16_f32 v124, v129, v155
	v_cvt_pk_bf16_f32 v125, v156, v157
	v_fmac_f32_e32 v154, v157, v157
	v_lshlrev_b32_e32 v128, 16, v150
	v_rcp_f32_e32 v121, v121
	v_add_f32_e32 v114, 1.0, v114
	v_add_f32_e32 v115, 1.0, v115
	v_lshlrev_b32_e32 v157, 16, v146
	v_and_b32_e32 v129, 0xffff0000, v150
	v_rcp_f32_e32 v114, v114
	v_rcp_f32_e32 v115, v115
	v_fmac_f32_e32 v157, v118, v128
	v_and_b32_e32 v118, 0xffff0000, v146
	v_lshlrev_b32_e32 v150, 16, v151
	v_add_f32_e32 v116, 1.0, v116
	v_fmac_f32_e32 v118, v119, v129
	v_lshlrev_b32_e32 v119, 16, v147
	v_fmac_f32_e32 v154, v157, v157
	v_and_b32_e32 v151, 0xffff0000, v151
	v_rcp_f32_e32 v116, v116
	v_add_f32_e32 v117, 1.0, v117
	v_fmac_f32_e32 v119, v120, v150
	v_and_b32_e32 v128, 0xffff0000, v147
	v_fmac_f32_e32 v154, v118, v118
	v_lshlrev_b32_e32 v155, 16, v152
	v_and_b32_e32 v152, 0xffff0000, v152
	v_rcp_f32_e32 v117, v117
	v_fmac_f32_e32 v128, v121, v151
	v_lshlrev_b32_e32 v129, 16, v148
	v_and_b32_e32 v146, 0xffff0000, v148
	v_fmac_f32_e32 v154, v119, v119
	v_fmac_f32_e32 v129, v114, v155
	v_fmac_f32_e32 v146, v115, v152
	v_fmac_f32_e32 v154, v128, v128
	v_and_b32_e32 v115, 64, v206
	v_lshlrev_b32_e32 v156, 16, v153
	v_lshlrev_b32_e32 v147, 16, v149
	v_fmac_f32_e32 v154, v129, v129
	v_xor_b32_e32 v114, 16, v206
	v_add_u32_e32 v115, 64, v115
	v_and_b32_e32 v153, 0xffff0000, v153
	v_fmac_f32_e32 v147, v116, v156
	v_and_b32_e32 v150, 0xffff0000, v149
	v_fmac_f32_e32 v154, v146, v146
	v_cmp_lt_i32_e32 vcc, v114, v115
	v_fmac_f32_e32 v150, v117, v153
	v_fmac_f32_e32 v154, v147, v147
	v_cndmask_b32_e32 v114, v206, v114, vcc
	v_lshlrev_b64 v[200:201], 11, v[186:187]
	v_fmac_f32_e32 v154, v150, v150
	v_lshlrev_b32_e32 v148, 2, v114
	v_lshl_add_u64 v[126:127], s[4:5], 0, v[200:201]
	ds_bpermute_b32 v114, v148, v154
	v_lshl_add_u64 v[120:121], v[184:185], 1, v[126:127]
	global_store_dwordx4 v[120:121], v[122:125], off sc1
	v_cvt_pk_bf16_f32 v116, v157, v118
	v_xor_b32_e32 v118, 32, v206
	v_cmp_lt_i32_e32 vcc, v118, v115
	s_waitcnt lgkmcnt(0)
	v_add_f32_e32 v114, v154, v114
	v_cvt_pk_bf16_f32 v117, v119, v128
	v_cndmask_b32_e32 v115, v206, v118, vcc
	v_lshlrev_b32_e32 v149, 2, v115
	ds_bpermute_b32 v115, v149, v114
	v_cvt_pk_bf16_f32 v118, v129, v146
	v_cvt_pk_bf16_f32 v119, v147, v150
	v_lshl_add_u64 v[146:147], v[186:187], 3, s[0:1]
	global_store_dwordx4 v[120:121], v[116:119], off offset:256 sc1
	s_and_saveexec_b64 s[76:77], s[54:55]
	s_cbranch_execz .LBB0_791
	s_waitcnt lgkmcnt(0)
	v_add_f32_e32 v114, v114, v115
	v_mul_f32_e32 v114, 0x4d800000, v114
	v_trunc_f32_e32 v114, v114
	v_mul_f32_e32 v115, 0x2f800000, v114
	v_floor_f32_e32 v115, v115
	v_fmac_f32_e32 v114, 0xcf800000, v115
	v_cvt_u32_f32_e32 v114, v114
	v_cvt_u32_f32_e32 v115, v115
	global_atomic_add_x2 v[146:147], v[114:115], off
.LBB0_791:
	s_or_b64 exec, exec, s[76:77]
	v_mul_f32_e32 v110, v110, v198
	v_mul_f32_e32 v110, 0xbfb8aa3b, v110
	v_mul_f32_e32 v111, v111, v198
	v_exp_f32_e32 v110, v110
	v_mul_f32_e32 v111, 0xbfb8aa3b, v111
	v_mul_f32_e32 v112, v112, v198
	v_exp_f32_e32 v111, v111
	v_mul_f32_e32 v112, 0xbfb8aa3b, v112
	v_mul_f32_e32 v113, v113, v198
	v_exp_f32_e32 v112, v112
	v_mul_f32_e32 v113, 0xbfb8aa3b, v113
	v_mul_f32_e32 v106, v106, v198
	v_exp_f32_e32 v113, v113
	v_mul_f32_e32 v106, 0xbfb8aa3b, v106
	v_add_f32_e32 v110, 1.0, v110
	v_exp_f32_e32 v106, v106
	v_rcp_f32_e32 v110, v110
	v_add_f32_e32 v111, 1.0, v111
	v_rcp_f32_e32 v111, v111
	v_add_f32_e32 v112, 1.0, v112
	v_mul_f32_e32 v107, v107, v198
	v_rcp_f32_e32 v112, v112
	v_add_f32_e32 v113, 1.0, v113
	v_mul_f32_e32 v107, 0xbfb8aa3b, v107
	v_mul_f32_e32 v108, v108, v198
	v_lshlrev_b32_e32 v116, 16, v142
	v_exp_f32_e32 v107, v107
	v_rcp_f32_e32 v113, v113
	v_add_f32_e32 v106, 1.0, v106
	v_mul_f32_e32 v108, 0xbfb8aa3b, v108
	v_mul_f32_e32 v109, v109, v198
	v_lshlrev_b32_e32 v124, 16, v138
	v_and_b32_e32 v117, 0xffff0000, v142
	v_rcp_f32_e32 v106, v106
	v_exp_f32_e32 v108, v108
	v_mul_f32_e32 v109, 0xbfb8aa3b, v109
	v_fmac_f32_e32 v124, v110, v116
	v_and_b32_e32 v110, 0xffff0000, v138
	v_mul_f32_e32 v102, v102, v198
	v_lshlrev_b32_e32 v118, 16, v143
	v_exp_f32_e32 v109, v109
	v_fmac_f32_e32 v110, v111, v117
	v_lshlrev_b32_e32 v111, 16, v139
	v_mul_f32_e32 v102, 0xbfb8aa3b, v102
	v_mul_f32_e32 v103, v103, v198
	v_and_b32_e32 v119, 0xffff0000, v143
	v_fmac_f32_e32 v111, v112, v118
	v_and_b32_e32 v112, 0xffff0000, v139
	v_exp_f32_e32 v102, v102
	v_mul_f32_e32 v103, 0xbfb8aa3b, v103
	v_mul_f32_e32 v104, v104, v198
	v_lshlrev_b32_e32 v120, 16, v144
	v_add_f32_e32 v107, 1.0, v107
	v_fmac_f32_e32 v112, v113, v119
	v_lshlrev_b32_e32 v113, 16, v140
	v_exp_f32_e32 v103, v103
	v_mul_f32_e32 v104, 0xbfb8aa3b, v104
	v_mul_f32_e32 v105, v105, v198
	v_rcp_f32_e32 v107, v107
	v_add_f32_e32 v108, 1.0, v108
	v_fmac_f32_e32 v113, v106, v120
	v_cvt_pk_bf16_f32 v106, v124, v110
	v_mul_f32_e32 v110, v110, v110
	v_exp_f32_e32 v104, v104
	v_mul_f32_e32 v105, 0xbfb8aa3b, v105
	v_mul_f32_e32 v98, v98, v198
	v_rcp_f32_e32 v108, v108
	v_add_f32_e32 v109, 1.0, v109
	v_fmac_f32_e32 v110, v124, v124
	v_exp_f32_e32 v105, v105
	v_mul_f32_e32 v98, 0xbfb8aa3b, v98
	v_mul_f32_e32 v99, v99, v198
	v_rcp_f32_e32 v109, v109
	v_fmac_f32_e32 v110, v111, v111
	v_add_f32_e32 v102, 1.0, v102
	v_exp_f32_e32 v98, v98
	v_mul_f32_e32 v99, 0xbfb8aa3b, v99
	v_mul_f32_e32 v100, v100, v198
	v_and_b32_e32 v121, 0xffff0000, v144
	v_and_b32_e32 v116, 0xffff0000, v140
	v_fmac_f32_e32 v110, v112, v112
	v_rcp_f32_e32 v102, v102
	v_add_f32_e32 v103, 1.0, v103
	v_exp_f32_e32 v99, v99
	v_mul_f32_e32 v100, 0xbfb8aa3b, v100
	v_mul_f32_e32 v101, v101, v198
	v_lshlrev_b32_e32 v122, 16, v145
	v_fmac_f32_e32 v116, v107, v121
	v_lshlrev_b32_e32 v117, 16, v141
	v_fmac_f32_e32 v110, v113, v113
	v_rcp_f32_e32 v103, v103
	v_add_f32_e32 v104, 1.0, v104
	v_exp_f32_e32 v100, v100
	v_mul_f32_e32 v101, 0xbfb8aa3b, v101
	v_and_b32_e32 v123, 0xffff0000, v145
	v_fmac_f32_e32 v117, v108, v122
	v_and_b32_e32 v118, 0xffff0000, v141
	v_fmac_f32_e32 v110, v116, v116
	v_rcp_f32_e32 v104, v104
	v_add_f32_e32 v105, 1.0, v105
	v_exp_f32_e32 v101, v101
	v_fmac_f32_e32 v118, v109, v123
	v_cvt_pk_bf16_f32 v107, v111, v112
	v_fmac_f32_e32 v110, v117, v117
	v_lshlrev_b32_e32 v111, 16, v134
	v_rcp_f32_e32 v105, v105
	v_add_f32_e32 v98, 1.0, v98
	v_lshlrev_b32_e32 v121, 16, v130
	v_fmac_f32_e32 v110, v118, v118
	v_and_b32_e32 v112, 0xffff0000, v134
	v_rcp_f32_e32 v98, v98
	v_add_f32_e32 v99, 1.0, v99
	v_fmac_f32_e32 v121, v102, v111
	v_and_b32_e32 v102, 0xffff0000, v130
	v_cvt_pk_bf16_f32 v108, v113, v116
	v_lshlrev_b32_e32 v113, 16, v135
	v_rcp_f32_e32 v99, v99
	v_add_f32_e32 v100, 1.0, v100
	v_fmac_f32_e32 v102, v103, v112
	v_lshlrev_b32_e32 v103, 16, v131
	v_fmac_f32_e32 v110, v121, v121
	v_and_b32_e32 v116, 0xffff0000, v135
	v_rcp_f32_e32 v100, v100
	v_add_f32_e32 v101, 1.0, v101
	v_fmac_f32_e32 v103, v104, v113
	v_and_b32_e32 v111, 0xffff0000, v131
	v_fmac_f32_e32 v110, v102, v102
	v_cvt_pk_bf16_f32 v109, v117, v118
	v_lshlrev_b32_e32 v117, 16, v136
	v_rcp_f32_e32 v101, v101
	v_fmac_f32_e32 v111, v105, v116
	v_lshlrev_b32_e32 v112, 16, v132
	v_fmac_f32_e32 v110, v103, v103
	v_and_b32_e32 v118, 0xffff0000, v136
	v_fmac_f32_e32 v112, v98, v117
	v_and_b32_e32 v113, 0xffff0000, v132
	v_fmac_f32_e32 v110, v111, v111
	v_lshlrev_b32_e32 v119, 16, v137
	v_fmac_f32_e32 v113, v99, v118
	v_lshlrev_b32_e32 v116, 16, v133
	v_fmac_f32_e32 v110, v112, v112
	v_and_b32_e32 v120, 0xffff0000, v137
	v_fmac_f32_e32 v116, v100, v119
	v_and_b32_e32 v117, 0xffff0000, v133
	v_fmac_f32_e32 v110, v113, v113
	v_fmac_f32_e32 v117, v101, v120
	v_fmac_f32_e32 v110, v116, v116
	v_fmac_f32_e32 v110, v117, v117
	ds_bpermute_b32 v101, v148, v110
	s_waitcnt lgkmcnt(1)
	v_lshlrev_b64 v[114:115], 11, v[190:191]
	v_lshl_add_u64 v[98:99], s[4:5], 0, v[114:115]
	v_lshl_add_u64 v[104:105], v[184:185], 1, v[98:99]
	global_store_dwordx4 v[104:105], v[106:109], off sc1
	s_waitcnt lgkmcnt(0)
	v_add_f32_e32 v98, v110, v101
	ds_bpermute_b32 v99, v149, v98
	v_cvt_pk_bf16_f32 v100, v121, v102
	v_cvt_pk_bf16_f32 v101, v103, v111
	v_cvt_pk_bf16_f32 v102, v112, v113
	v_cvt_pk_bf16_f32 v103, v116, v117
	global_store_dwordx4 v[104:105], v[100:103], off offset:256 sc1
	s_and_saveexec_b64 s[76:77], s[54:55]
	s_cbranch_execz .LBB0_793
	s_waitcnt lgkmcnt(0)
	v_add_f32_e32 v98, v98, v99
	v_mul_f32_e32 v98, 0x4d800000, v98
	v_trunc_f32_e32 v98, v98
	v_mul_f32_e32 v99, 0x2f800000, v98
	v_floor_f32_e32 v99, v99
	v_fmac_f32_e32 v98, 0xcf800000, v99
	v_cvt_u32_f32_e32 v98, v98
	v_cvt_u32_f32_e32 v99, v99
	global_atomic_add_x2 v[146:147], v[98:99], off offset:128

.LBB0_801:
	s_waitcnt lgkmcnt(0)
	v_mul_f32_e32 v94, v94, v135
	v_mul_f32_e32 v94, 0xbfb8aa3b, v94
	v_mul_f32_e32 v95, v95, v135
	v_exp_f32_e32 v94, v94
	v_mul_f32_e32 v95, 0xbfb8aa3b, v95
	v_mul_f32_e32 v96, v96, v135
	v_exp_f32_e32 v95, v95
	v_mul_f32_e32 v96, 0xbfb8aa3b, v96
	v_mul_f32_e32 v97, v97, v135
	v_exp_f32_e32 v96, v96
	v_mul_f32_e32 v97, 0xbfb8aa3b, v97
	v_mul_f32_e32 v90, v90, v135
	v_exp_f32_e32 v97, v97
	v_mul_f32_e32 v90, 0xbfb8aa3b, v90
	v_add_f32_e32 v94, 1.0, v94
	v_exp_f32_e32 v90, v90
	v_rcp_f32_e32 v94, v94
	v_add_f32_e32 v95, 1.0, v95
	v_rcp_f32_e32 v95, v95
	v_add_f32_e32 v96, 1.0, v96
	v_mul_f32_e32 v91, v91, v135
	v_rcp_f32_e32 v96, v96
	v_add_f32_e32 v97, 1.0, v97
	v_mul_f32_e32 v91, 0xbfb8aa3b, v91
	v_mul_f32_e32 v92, v92, v135
	s_waitcnt vmcnt(5)
	v_lshlrev_b32_e32 v136, 16, v126
	v_exp_f32_e32 v91, v91
	v_rcp_f32_e32 v97, v97
	v_add_f32_e32 v90, 1.0, v90
	v_mul_f32_e32 v92, 0xbfb8aa3b, v92
	v_mul_f32_e32 v93, v93, v135
	v_lshlrev_b32_e32 v140, 16, v122
	v_and_b32_e32 v126, 0xffff0000, v126
	v_rcp_f32_e32 v90, v90
	v_exp_f32_e32 v92, v92
	v_mul_f32_e32 v93, 0xbfb8aa3b, v93
	v_fmac_f32_e32 v140, v94, v136
	v_and_b32_e32 v94, 0xffff0000, v122
	v_mul_f32_e32 v86, v86, v135
	v_lshlrev_b32_e32 v137, 16, v127
	v_exp_f32_e32 v93, v93
	v_fmac_f32_e32 v94, v95, v126
	v_lshlrev_b32_e32 v95, 16, v123
	v_mul_f32_e32 v86, 0xbfb8aa3b, v86
	v_mul_f32_e32 v87, v87, v135
	v_and_b32_e32 v127, 0xffff0000, v127
	v_fmac_f32_e32 v95, v96, v137
	v_and_b32_e32 v96, 0xffff0000, v123
	v_exp_f32_e32 v86, v86
	v_mul_f32_e32 v87, 0xbfb8aa3b, v87
	v_mul_f32_e32 v88, v88, v135
	v_lshlrev_b32_e32 v138, 16, v128
	v_add_f32_e32 v91, 1.0, v91
	v_fmac_f32_e32 v96, v97, v127
	v_lshlrev_b32_e32 v97, 16, v124
	v_exp_f32_e32 v87, v87
	v_mul_f32_e32 v88, 0xbfb8aa3b, v88
	v_mul_f32_e32 v89, v89, v135
	v_rcp_f32_e32 v91, v91
	v_add_f32_e32 v92, 1.0, v92
	v_fmac_f32_e32 v97, v90, v138
	v_cvt_pk_bf16_f32 v90, v140, v94
	v_mul_f32_e32 v94, v94, v94
	v_exp_f32_e32 v88, v88
	v_mul_f32_e32 v89, 0xbfb8aa3b, v89
	v_mul_f32_e32 v82, v82, v135
	v_rcp_f32_e32 v92, v92
	v_add_f32_e32 v93, 1.0, v93
	v_fmac_f32_e32 v94, v140, v140
	v_exp_f32_e32 v89, v89
	v_mul_f32_e32 v82, 0xbfb8aa3b, v82
	v_mul_f32_e32 v83, v83, v135
	v_rcp_f32_e32 v93, v93
	v_fmac_f32_e32 v94, v95, v95
	v_add_f32_e32 v86, 1.0, v86
	v_exp_f32_e32 v82, v82
	v_mul_f32_e32 v83, 0xbfb8aa3b, v83
	v_mul_f32_e32 v84, v84, v135
	v_and_b32_e32 v128, 0xffff0000, v128
	v_and_b32_e32 v122, 0xffff0000, v124
	v_fmac_f32_e32 v94, v96, v96
	v_rcp_f32_e32 v86, v86
	v_add_f32_e32 v87, 1.0, v87
	v_exp_f32_e32 v83, v83
	v_mul_f32_e32 v84, 0xbfb8aa3b, v84
	v_mul_f32_e32 v85, v85, v135
	v_lshlrev_b32_e32 v139, 16, v129
	v_fmac_f32_e32 v122, v91, v128
	v_lshlrev_b32_e32 v123, 16, v125
	v_fmac_f32_e32 v94, v97, v97
	v_rcp_f32_e32 v87, v87
	v_add_f32_e32 v88, 1.0, v88
	v_exp_f32_e32 v84, v84
	v_mul_f32_e32 v85, 0xbfb8aa3b, v85
	v_and_b32_e32 v129, 0xffff0000, v129
	v_fmac_f32_e32 v123, v92, v139
	v_and_b32_e32 v124, 0xffff0000, v125
	v_fmac_f32_e32 v94, v122, v122
	v_rcp_f32_e32 v88, v88
	v_add_f32_e32 v89, 1.0, v89
	v_exp_f32_e32 v85, v85
	v_fmac_f32_e32 v124, v93, v129
	v_cvt_pk_bf16_f32 v91, v95, v96
	v_cvt_pk_bf16_f32 v92, v97, v122
	v_cvt_pk_bf16_f32 v93, v123, v124
	v_fmac_f32_e32 v94, v123, v123
	s_waitcnt vmcnt(4)
	v_lshlrev_b32_e32 v95, 16, v118
	v_rcp_f32_e32 v89, v89
	v_add_f32_e32 v82, 1.0, v82
	v_lshlrev_b32_e32 v123, 16, v114
	v_fmac_f32_e32 v94, v124, v124
	v_and_b32_e32 v96, 0xffff0000, v118
	v_rcp_f32_e32 v82, v82
	v_add_f32_e32 v83, 1.0, v83
	v_fmac_f32_e32 v123, v86, v95
	v_and_b32_e32 v86, 0xffff0000, v114
	v_lshlrev_b32_e32 v97, 16, v119
	v_rcp_f32_e32 v83, v83
	v_add_f32_e32 v84, 1.0, v84
	v_fmac_f32_e32 v86, v87, v96
	v_lshlrev_b32_e32 v87, 16, v115
	v_fmac_f32_e32 v94, v123, v123
	v_and_b32_e32 v118, 0xffff0000, v119
	v_rcp_f32_e32 v84, v84
	v_add_f32_e32 v85, 1.0, v85
	v_fmac_f32_e32 v87, v88, v97
	v_and_b32_e32 v95, 0xffff0000, v115
	v_fmac_f32_e32 v94, v86, v86
	v_lshlrev_b32_e32 v119, 16, v120
	v_rcp_f32_e32 v85, v85
	v_fmac_f32_e32 v95, v89, v118
	v_lshlrev_b32_e32 v96, 16, v116
	v_fmac_f32_e32 v94, v87, v87
	v_and_b32_e32 v120, 0xffff0000, v120
	v_fmac_f32_e32 v96, v82, v119
	v_and_b32_e32 v97, 0xffff0000, v116
	v_fmac_f32_e32 v94, v95, v95
	v_lshlrev_b32_e32 v122, 16, v121
	v_fmac_f32_e32 v97, v83, v120
	v_lshlrev_b32_e32 v114, 16, v117
	v_fmac_f32_e32 v94, v96, v96
	v_and_b32_e32 v121, 0xffff0000, v121
	v_fmac_f32_e32 v114, v84, v122
	v_and_b32_e32 v115, 0xffff0000, v117
	v_fmac_f32_e32 v94, v97, v97
	v_fmac_f32_e32 v115, v85, v121
	v_fmac_f32_e32 v94, v114, v114
	v_fmac_f32_e32 v94, v115, v115
	ds_bpermute_b32 v85, v148, v94
	v_lshlrev_b64 v[132:133], 11, v[132:133]
	v_lshl_add_u64 v[82:83], s[4:5], 0, v[132:133]
	v_lshl_add_u64 v[88:89], v[184:185], 1, v[82:83]
	global_store_dwordx4 v[88:89], v[90:93], off sc1
	s_waitcnt lgkmcnt(0)
	v_add_f32_e32 v82, v94, v85
	ds_bpermute_b32 v83, v149, v82
	v_cvt_pk_bf16_f32 v84, v123, v86
	v_cvt_pk_bf16_f32 v85, v87, v95
	v_cvt_pk_bf16_f32 v86, v96, v97
	v_cvt_pk_bf16_f32 v87, v114, v115
	global_store_dwordx4 v[88:89], v[84:87], off offset:256 sc1
	s_and_saveexec_b64 s[76:77], s[54:55]
	s_cbranch_execz .LBB0_803
	s_waitcnt lgkmcnt(0)
	v_add_f32_e32 v82, v82, v83
	v_mul_f32_e32 v82, 0x4d800000, v82
	v_trunc_f32_e32 v82, v82
	v_mul_f32_e32 v83, 0x2f800000, v82
	v_floor_f32_e32 v83, v83
	v_fmac_f32_e32 v82, 0xcf800000, v83
	v_cvt_u32_f32_e32 v82, v82
	v_cvt_u32_f32_e32 v83, v83
	global_atomic_add_x2 v[146:147], v[82:83], off offset:256
.LBB0_803:
	s_or_b64 exec, exec, s[76:77]
	v_mul_f32_e32 v78, v78, v134
	v_mul_f32_e32 v78, 0xbfb8aa3b, v78
	v_mul_f32_e32 v79, v79, v134
	v_exp_f32_e32 v78, v78
	v_mul_f32_e32 v79, 0xbfb8aa3b, v79
	v_mul_f32_e32 v80, v80, v134
	v_exp_f32_e32 v79, v79
	v_mul_f32_e32 v80, 0xbfb8aa3b, v80
	v_mul_f32_e32 v81, v81, v134
	v_exp_f32_e32 v80, v80
	v_mul_f32_e32 v81, 0xbfb8aa3b, v81
	v_mul_f32_e32 v74, v74, v134
	v_exp_f32_e32 v81, v81
	v_mul_f32_e32 v74, 0xbfb8aa3b, v74
	v_add_f32_e32 v78, 1.0, v78
	v_exp_f32_e32 v74, v74
	v_rcp_f32_e32 v78, v78
	v_add_f32_e32 v79, 1.0, v79
	v_rcp_f32_e32 v79, v79
	v_add_f32_e32 v80, 1.0, v80
	v_mul_f32_e32 v75, v75, v134
	v_rcp_f32_e32 v80, v80
	v_add_f32_e32 v81, 1.0, v81
	v_mul_f32_e32 v75, 0xbfb8aa3b, v75
	v_mul_f32_e32 v76, v76, v134
	s_waitcnt vmcnt(3)
	v_lshlrev_b32_e32 v84, 16, v110
	v_exp_f32_e32 v75, v75
	v_rcp_f32_e32 v81, v81
	v_add_f32_e32 v74, 1.0, v74
	v_mul_f32_e32 v76, 0xbfb8aa3b, v76
	v_mul_f32_e32 v77, v77, v134
	v_lshlrev_b32_e32 v92, 16, v106
	v_and_b32_e32 v85, 0xffff0000, v110
	v_rcp_f32_e32 v74, v74
	v_exp_f32_e32 v76, v76
	v_mul_f32_e32 v77, 0xbfb8aa3b, v77
	v_fmac_f32_e32 v92, v78, v84
	v_and_b32_e32 v78, 0xffff0000, v106
	v_mul_f32_e32 v70, v70, v134
	v_lshlrev_b32_e32 v86, 16, v111
	v_exp_f32_e32 v77, v77
	v_fmac_f32_e32 v78, v79, v85
	v_lshlrev_b32_e32 v79, 16, v107
	v_mul_f32_e32 v70, 0xbfb8aa3b, v70
	v_mul_f32_e32 v71, v71, v134
	v_and_b32_e32 v87, 0xffff0000, v111
	v_fmac_f32_e32 v79, v80, v86
	v_and_b32_e32 v80, 0xffff0000, v107
	v_exp_f32_e32 v70, v70
	v_mul_f32_e32 v71, 0xbfb8aa3b, v71
	v_mul_f32_e32 v72, v72, v134
	v_lshlrev_b32_e32 v88, 16, v112
	v_add_f32_e32 v75, 1.0, v75
	v_fmac_f32_e32 v80, v81, v87
	v_lshlrev_b32_e32 v81, 16, v108
	v_exp_f32_e32 v71, v71
	v_mul_f32_e32 v72, 0xbfb8aa3b, v72
	v_mul_f32_e32 v73, v73, v134
	v_rcp_f32_e32 v75, v75
	v_add_f32_e32 v76, 1.0, v76
	v_fmac_f32_e32 v81, v74, v88
	v_cvt_pk_bf16_f32 v74, v92, v78
	v_mul_f32_e32 v78, v78, v78
	v_exp_f32_e32 v72, v72
	v_mul_f32_e32 v73, 0xbfb8aa3b, v73
	v_mul_f32_e32 v66, v66, v134
	v_rcp_f32_e32 v76, v76
	v_add_f32_e32 v77, 1.0, v77
	v_fmac_f32_e32 v78, v92, v92
	v_exp_f32_e32 v73, v73
	v_mul_f32_e32 v66, 0xbfb8aa3b, v66
	v_mul_f32_e32 v67, v67, v134
	v_rcp_f32_e32 v77, v77
	v_fmac_f32_e32 v78, v79, v79
	v_add_f32_e32 v70, 1.0, v70
	v_exp_f32_e32 v66, v66
	v_mul_f32_e32 v67, 0xbfb8aa3b, v67
	v_mul_f32_e32 v68, v68, v134
	v_and_b32_e32 v89, 0xffff0000, v112
	v_and_b32_e32 v84, 0xffff0000, v108
	v_fmac_f32_e32 v78, v80, v80
	v_rcp_f32_e32 v70, v70
	v_add_f32_e32 v71, 1.0, v71
	v_exp_f32_e32 v67, v67
	v_mul_f32_e32 v68, 0xbfb8aa3b, v68
	v_mul_f32_e32 v69, v69, v134
	v_lshlrev_b32_e32 v90, 16, v113
	v_fmac_f32_e32 v84, v75, v89
	v_lshlrev_b32_e32 v85, 16, v109
	v_fmac_f32_e32 v78, v81, v81
	v_rcp_f32_e32 v71, v71
	v_add_f32_e32 v72, 1.0, v72
	v_exp_f32_e32 v68, v68
	v_mul_f32_e32 v69, 0xbfb8aa3b, v69
	v_and_b32_e32 v91, 0xffff0000, v113
	v_fmac_f32_e32 v85, v76, v90
	v_and_b32_e32 v86, 0xffff0000, v109
	v_fmac_f32_e32 v78, v84, v84
	v_rcp_f32_e32 v72, v72
	v_add_f32_e32 v73, 1.0, v73
	v_exp_f32_e32 v69, v69
	v_fmac_f32_e32 v86, v77, v91
	v_cvt_pk_bf16_f32 v75, v79, v80
	v_fmac_f32_e32 v78, v85, v85
	s_waitcnt vmcnt(2)
	v_lshlrev_b32_e32 v79, 16, v102
	v_rcp_f32_e32 v73, v73
	v_add_f32_e32 v66, 1.0, v66
	v_lshlrev_b32_e32 v89, 16, v98
	v_fmac_f32_e32 v78, v86, v86
	v_and_b32_e32 v80, 0xffff0000, v102
	v_rcp_f32_e32 v66, v66
	v_add_f32_e32 v67, 1.0, v67
	v_fmac_f32_e32 v89, v70, v79
	v_and_b32_e32 v70, 0xffff0000, v98
	v_cvt_pk_bf16_f32 v76, v81, v84
	v_lshlrev_b32_e32 v81, 16, v103
	v_rcp_f32_e32 v67, v67
	v_add_f32_e32 v68, 1.0, v68
	v_fmac_f32_e32 v70, v71, v80
	v_lshlrev_b32_e32 v71, 16, v99
	v_fmac_f32_e32 v78, v89, v89
	v_and_b32_e32 v84, 0xffff0000, v103
	v_rcp_f32_e32 v68, v68
	v_add_f32_e32 v69, 1.0, v69
	v_fmac_f32_e32 v71, v72, v81
	v_and_b32_e32 v79, 0xffff0000, v99
	v_fmac_f32_e32 v78, v70, v70
	v_cvt_pk_bf16_f32 v77, v85, v86
	v_lshlrev_b32_e32 v85, 16, v104
	v_rcp_f32_e32 v69, v69
	v_fmac_f32_e32 v79, v73, v84
	v_lshlrev_b32_e32 v80, 16, v100
	v_fmac_f32_e32 v78, v71, v71
	v_and_b32_e32 v86, 0xffff0000, v104
	v_fmac_f32_e32 v80, v66, v85
	v_and_b32_e32 v81, 0xffff0000, v100
	v_fmac_f32_e32 v78, v79, v79
	v_lshlrev_b32_e32 v87, 16, v105
	v_fmac_f32_e32 v81, v67, v86
	v_lshlrev_b32_e32 v84, 16, v101
	v_fmac_f32_e32 v78, v80, v80
	v_and_b32_e32 v88, 0xffff0000, v105
	v_fmac_f32_e32 v84, v68, v87
	v_and_b32_e32 v85, 0xffff0000, v101
	v_fmac_f32_e32 v78, v81, v81
	v_fmac_f32_e32 v85, v69, v88
	v_fmac_f32_e32 v78, v84, v84
	v_fmac_f32_e32 v78, v85, v85
	ds_bpermute_b32 v69, v148, v78
	s_waitcnt lgkmcnt(1)
	v_lshlrev_b64 v[82:83], 11, v[130:131]
	v_lshl_add_u64 v[66:67], s[4:5], 0, v[82:83]
	v_lshl_add_u64 v[72:73], v[184:185], 1, v[66:67]
	global_store_dwordx4 v[72:73], v[74:77], off sc1
	s_waitcnt lgkmcnt(0)
	v_add_f32_e32 v66, v78, v69
	ds_bpermute_b32 v67, v149, v66
	v_cvt_pk_bf16_f32 v68, v89, v70
	v_cvt_pk_bf16_f32 v69, v71, v79
	v_cvt_pk_bf16_f32 v70, v80, v81
	v_cvt_pk_bf16_f32 v71, v84, v85
	global_store_dwordx4 v[72:73], v[68:71], off offset:256 sc1
	s_and_saveexec_b64 s[76:77], s[54:55]
	s_cbranch_execz .LBB0_805
	s_waitcnt lgkmcnt(0)
	v_add_f32_e32 v66, v66, v67
	v_mul_f32_e32 v66, 0x4d800000, v66
	v_trunc_f32_e32 v66, v66
	v_mul_f32_e32 v67, 0x2f800000, v66
	v_floor_f32_e32 v67, v67
	v_fmac_f32_e32 v66, 0xcf800000, v67
	v_cvt_u32_f32_e32 v66, v66
	v_cvt_u32_f32_e32 v67, v67
	global_atomic_add_x2 v[146:147], v[66:67], off offset:384

.LBB0_813:
	s_waitcnt lgkmcnt(0)
	v_mul_f32_e32 v62, v62, v103
	v_mul_f32_e32 v62, 0xbfb8aa3b, v62
	v_mul_f32_e32 v63, v63, v103
	v_exp_f32_e32 v62, v62
	v_mul_f32_e32 v63, 0xbfb8aa3b, v63
	v_mul_f32_e32 v64, v64, v103
	v_exp_f32_e32 v63, v63
	v_mul_f32_e32 v64, 0xbfb8aa3b, v64
	v_mul_f32_e32 v65, v65, v103
	v_exp_f32_e32 v64, v64
	v_mul_f32_e32 v65, 0xbfb8aa3b, v65
	v_mul_f32_e32 v58, v58, v103
	v_exp_f32_e32 v65, v65
	v_mul_f32_e32 v58, 0xbfb8aa3b, v58
	v_add_f32_e32 v62, 1.0, v62
	v_exp_f32_e32 v58, v58
	v_rcp_f32_e32 v62, v62
	v_add_f32_e32 v63, 1.0, v63
	v_rcp_f32_e32 v63, v63
	v_add_f32_e32 v64, 1.0, v64
	v_mul_f32_e32 v59, v59, v103
	v_rcp_f32_e32 v64, v64
	v_add_f32_e32 v65, 1.0, v65
	v_mul_f32_e32 v59, 0xbfb8aa3b, v59
	v_mul_f32_e32 v60, v60, v103
	s_waitcnt vmcnt(5)
	v_lshlrev_b32_e32 v104, 16, v94
	v_exp_f32_e32 v59, v59
	v_rcp_f32_e32 v65, v65
	v_add_f32_e32 v58, 1.0, v58
	v_mul_f32_e32 v60, 0xbfb8aa3b, v60
	v_mul_f32_e32 v61, v61, v103
	v_lshlrev_b32_e32 v108, 16, v90
	v_and_b32_e32 v94, 0xffff0000, v94
	v_rcp_f32_e32 v58, v58
	v_exp_f32_e32 v60, v60
	v_mul_f32_e32 v61, 0xbfb8aa3b, v61
	v_fmac_f32_e32 v108, v62, v104
	v_and_b32_e32 v62, 0xffff0000, v90
	v_mul_f32_e32 v54, v54, v103
	v_lshlrev_b32_e32 v105, 16, v95
	v_exp_f32_e32 v61, v61
	v_fmac_f32_e32 v62, v63, v94
	v_lshlrev_b32_e32 v63, 16, v91
	v_mul_f32_e32 v54, 0xbfb8aa3b, v54
	v_mul_f32_e32 v55, v55, v103
	v_and_b32_e32 v95, 0xffff0000, v95
	v_fmac_f32_e32 v63, v64, v105
	v_and_b32_e32 v64, 0xffff0000, v91
	v_exp_f32_e32 v54, v54
	v_mul_f32_e32 v55, 0xbfb8aa3b, v55
	v_mul_f32_e32 v56, v56, v103
	v_lshlrev_b32_e32 v106, 16, v96
	v_add_f32_e32 v59, 1.0, v59
	v_fmac_f32_e32 v64, v65, v95
	v_lshlrev_b32_e32 v65, 16, v92
	v_exp_f32_e32 v55, v55
	v_mul_f32_e32 v56, 0xbfb8aa3b, v56
	v_mul_f32_e32 v57, v57, v103
	v_rcp_f32_e32 v59, v59
	v_add_f32_e32 v60, 1.0, v60
	v_fmac_f32_e32 v65, v58, v106
	v_cvt_pk_bf16_f32 v58, v108, v62
	v_mul_f32_e32 v62, v62, v62
	v_exp_f32_e32 v56, v56
	v_mul_f32_e32 v57, 0xbfb8aa3b, v57
	v_mul_f32_e32 v50, v50, v103
	v_rcp_f32_e32 v60, v60
	v_add_f32_e32 v61, 1.0, v61
	v_fmac_f32_e32 v62, v108, v108
	v_exp_f32_e32 v57, v57
	v_mul_f32_e32 v50, 0xbfb8aa3b, v50
	v_mul_f32_e32 v51, v51, v103
	v_rcp_f32_e32 v61, v61
	v_fmac_f32_e32 v62, v63, v63
	v_add_f32_e32 v54, 1.0, v54
	v_exp_f32_e32 v50, v50
	v_mul_f32_e32 v51, 0xbfb8aa3b, v51
	v_mul_f32_e32 v52, v52, v103
	v_and_b32_e32 v96, 0xffff0000, v96
	v_and_b32_e32 v90, 0xffff0000, v92
	v_fmac_f32_e32 v62, v64, v64
	v_rcp_f32_e32 v54, v54
	v_add_f32_e32 v55, 1.0, v55
	v_exp_f32_e32 v51, v51
	v_mul_f32_e32 v52, 0xbfb8aa3b, v52
	v_mul_f32_e32 v53, v53, v103
	v_lshlrev_b32_e32 v107, 16, v97
	v_fmac_f32_e32 v90, v59, v96
	v_lshlrev_b32_e32 v91, 16, v93
	v_fmac_f32_e32 v62, v65, v65
	v_rcp_f32_e32 v55, v55
	v_add_f32_e32 v56, 1.0, v56
	v_exp_f32_e32 v52, v52
	v_mul_f32_e32 v53, 0xbfb8aa3b, v53
	v_and_b32_e32 v97, 0xffff0000, v97
	v_fmac_f32_e32 v91, v60, v107
	v_and_b32_e32 v92, 0xffff0000, v93
	v_fmac_f32_e32 v62, v90, v90
	v_rcp_f32_e32 v56, v56
	v_add_f32_e32 v57, 1.0, v57
	v_exp_f32_e32 v53, v53
	v_fmac_f32_e32 v92, v61, v97
	v_cvt_pk_bf16_f32 v59, v63, v64
	v_cvt_pk_bf16_f32 v60, v65, v90
	v_cvt_pk_bf16_f32 v61, v91, v92
	v_fmac_f32_e32 v62, v91, v91
	s_waitcnt vmcnt(4)
	v_lshlrev_b32_e32 v63, 16, v86
	v_rcp_f32_e32 v57, v57
	v_add_f32_e32 v50, 1.0, v50
	v_lshlrev_b32_e32 v91, 16, v82
	v_fmac_f32_e32 v62, v92, v92
	v_and_b32_e32 v64, 0xffff0000, v86
	v_rcp_f32_e32 v50, v50
	v_add_f32_e32 v51, 1.0, v51
	v_fmac_f32_e32 v91, v54, v63
	v_and_b32_e32 v54, 0xffff0000, v82
	v_lshlrev_b32_e32 v65, 16, v87
	v_rcp_f32_e32 v51, v51
	v_add_f32_e32 v52, 1.0, v52
	v_fmac_f32_e32 v54, v55, v64
	v_lshlrev_b32_e32 v55, 16, v83
	v_fmac_f32_e32 v62, v91, v91
	v_and_b32_e32 v86, 0xffff0000, v87
	v_rcp_f32_e32 v52, v52
	v_add_f32_e32 v53, 1.0, v53
	v_fmac_f32_e32 v55, v56, v65
	v_and_b32_e32 v63, 0xffff0000, v83
	v_fmac_f32_e32 v62, v54, v54
	v_lshlrev_b32_e32 v87, 16, v88
	v_rcp_f32_e32 v53, v53
	v_fmac_f32_e32 v63, v57, v86
	v_lshlrev_b32_e32 v64, 16, v84
	v_fmac_f32_e32 v62, v55, v55
	v_and_b32_e32 v88, 0xffff0000, v88
	v_fmac_f32_e32 v64, v50, v87
	v_and_b32_e32 v65, 0xffff0000, v84
	v_fmac_f32_e32 v62, v63, v63
	v_lshlrev_b32_e32 v90, 16, v89
	v_fmac_f32_e32 v65, v51, v88
	v_lshlrev_b32_e32 v82, 16, v85
	v_fmac_f32_e32 v62, v64, v64
	v_and_b32_e32 v89, 0xffff0000, v89
	v_fmac_f32_e32 v82, v52, v90
	v_and_b32_e32 v83, 0xffff0000, v85
	v_fmac_f32_e32 v62, v65, v65
	v_fmac_f32_e32 v83, v53, v89
	v_fmac_f32_e32 v62, v82, v82
	v_fmac_f32_e32 v62, v83, v83
	ds_bpermute_b32 v53, v148, v62
	v_lshlrev_b64 v[100:101], 11, v[100:101]
	v_lshl_add_u64 v[50:51], s[4:5], 0, v[100:101]
	v_lshl_add_u64 v[56:57], v[184:185], 1, v[50:51]
	global_store_dwordx4 v[56:57], v[58:61], off sc1
	s_waitcnt lgkmcnt(0)
	v_add_f32_e32 v50, v62, v53
	ds_bpermute_b32 v51, v149, v50
	v_cvt_pk_bf16_f32 v52, v91, v54
	v_cvt_pk_bf16_f32 v53, v55, v63
	v_cvt_pk_bf16_f32 v54, v64, v65
	v_cvt_pk_bf16_f32 v55, v82, v83
	global_store_dwordx4 v[56:57], v[52:55], off offset:256 sc1
	s_and_saveexec_b64 s[76:77], s[54:55]
	s_cbranch_execz .LBB0_815
	s_waitcnt lgkmcnt(0)
	v_add_f32_e32 v50, v50, v51
	v_mul_f32_e32 v50, 0x4d800000, v50
	v_trunc_f32_e32 v50, v50
	v_mul_f32_e32 v51, 0x2f800000, v50
	v_floor_f32_e32 v51, v51
	v_fmac_f32_e32 v50, 0xcf800000, v51
	v_cvt_u32_f32_e32 v50, v50
	v_cvt_u32_f32_e32 v51, v51
	global_atomic_add_x2 v[146:147], v[50:51], off offset:1024
.LBB0_815:
	s_or_b64 exec, exec, s[76:77]
	v_mul_f32_e32 v46, v46, v102
	v_mul_f32_e32 v46, 0xbfb8aa3b, v46
	v_mul_f32_e32 v47, v47, v102
	v_exp_f32_e32 v46, v46
	v_mul_f32_e32 v47, 0xbfb8aa3b, v47
	v_mul_f32_e32 v48, v48, v102
	v_exp_f32_e32 v47, v47
	v_mul_f32_e32 v48, 0xbfb8aa3b, v48
	v_mul_f32_e32 v49, v49, v102
	v_exp_f32_e32 v48, v48
	v_mul_f32_e32 v49, 0xbfb8aa3b, v49
	v_mul_f32_e32 v42, v42, v102
	v_exp_f32_e32 v49, v49
	v_mul_f32_e32 v42, 0xbfb8aa3b, v42
	v_add_f32_e32 v46, 1.0, v46
	v_exp_f32_e32 v42, v42
	v_rcp_f32_e32 v46, v46
	v_add_f32_e32 v47, 1.0, v47
	v_rcp_f32_e32 v47, v47
	v_add_f32_e32 v48, 1.0, v48
	v_mul_f32_e32 v43, v43, v102
	v_rcp_f32_e32 v48, v48
	v_add_f32_e32 v49, 1.0, v49
	v_mul_f32_e32 v43, 0xbfb8aa3b, v43
	v_mul_f32_e32 v44, v44, v102
	s_waitcnt vmcnt(3)
	v_lshlrev_b32_e32 v52, 16, v78
	v_exp_f32_e32 v43, v43
	v_rcp_f32_e32 v49, v49
	v_add_f32_e32 v42, 1.0, v42
	v_mul_f32_e32 v44, 0xbfb8aa3b, v44
	v_mul_f32_e32 v45, v45, v102
	v_lshlrev_b32_e32 v60, 16, v74
	v_and_b32_e32 v53, 0xffff0000, v78
	v_rcp_f32_e32 v42, v42
	v_exp_f32_e32 v44, v44
	v_mul_f32_e32 v45, 0xbfb8aa3b, v45
	v_fmac_f32_e32 v60, v46, v52
	v_and_b32_e32 v46, 0xffff0000, v74
	v_mul_f32_e32 v38, v38, v102
	v_lshlrev_b32_e32 v54, 16, v79
	v_exp_f32_e32 v45, v45
	v_fmac_f32_e32 v46, v47, v53
	v_lshlrev_b32_e32 v47, 16, v75
	v_mul_f32_e32 v38, 0xbfb8aa3b, v38
	v_mul_f32_e32 v39, v39, v102
	v_and_b32_e32 v55, 0xffff0000, v79
	v_fmac_f32_e32 v47, v48, v54
	v_and_b32_e32 v48, 0xffff0000, v75
	v_exp_f32_e32 v38, v38
	v_mul_f32_e32 v39, 0xbfb8aa3b, v39
	v_mul_f32_e32 v40, v40, v102
	v_lshlrev_b32_e32 v56, 16, v80
	v_add_f32_e32 v43, 1.0, v43
	v_fmac_f32_e32 v48, v49, v55
	v_lshlrev_b32_e32 v49, 16, v76
	v_exp_f32_e32 v39, v39
	v_mul_f32_e32 v40, 0xbfb8aa3b, v40
	v_mul_f32_e32 v41, v41, v102
	v_rcp_f32_e32 v43, v43
	v_add_f32_e32 v44, 1.0, v44
	v_fmac_f32_e32 v49, v42, v56
	v_cvt_pk_bf16_f32 v42, v60, v46
	v_mul_f32_e32 v46, v46, v46
	v_exp_f32_e32 v40, v40
	v_mul_f32_e32 v41, 0xbfb8aa3b, v41
	v_mul_f32_e32 v34, v34, v102
	v_rcp_f32_e32 v44, v44
	v_add_f32_e32 v45, 1.0, v45
	v_fmac_f32_e32 v46, v60, v60
	v_exp_f32_e32 v41, v41
	v_mul_f32_e32 v34, 0xbfb8aa3b, v34
	v_mul_f32_e32 v35, v35, v102
	v_rcp_f32_e32 v45, v45
	v_fmac_f32_e32 v46, v47, v47
	v_add_f32_e32 v38, 1.0, v38
	v_exp_f32_e32 v34, v34
	v_mul_f32_e32 v35, 0xbfb8aa3b, v35
	v_mul_f32_e32 v36, v36, v102
	v_and_b32_e32 v57, 0xffff0000, v80
	v_and_b32_e32 v52, 0xffff0000, v76
	v_fmac_f32_e32 v46, v48, v48
	v_rcp_f32_e32 v38, v38
	v_add_f32_e32 v39, 1.0, v39
	v_exp_f32_e32 v35, v35
	v_mul_f32_e32 v36, 0xbfb8aa3b, v36
	v_mul_f32_e32 v37, v37, v102
	v_lshlrev_b32_e32 v58, 16, v81
	v_fmac_f32_e32 v52, v43, v57
	v_lshlrev_b32_e32 v53, 16, v77
	v_fmac_f32_e32 v46, v49, v49
	v_rcp_f32_e32 v39, v39
	v_add_f32_e32 v40, 1.0, v40
	v_exp_f32_e32 v36, v36
	v_mul_f32_e32 v37, 0xbfb8aa3b, v37
	v_and_b32_e32 v59, 0xffff0000, v81
	v_fmac_f32_e32 v53, v44, v58
	v_and_b32_e32 v54, 0xffff0000, v77
	v_fmac_f32_e32 v46, v52, v52
	v_rcp_f32_e32 v40, v40
	v_add_f32_e32 v41, 1.0, v41
	v_exp_f32_e32 v37, v37
	v_fmac_f32_e32 v54, v45, v59
	v_cvt_pk_bf16_f32 v43, v47, v48
	v_fmac_f32_e32 v46, v53, v53
	s_waitcnt vmcnt(2)
	v_lshlrev_b32_e32 v47, 16, v70
	v_rcp_f32_e32 v41, v41
	v_add_f32_e32 v34, 1.0, v34
	v_lshlrev_b32_e32 v57, 16, v66
	v_fmac_f32_e32 v46, v54, v54
	v_and_b32_e32 v48, 0xffff0000, v70
	v_rcp_f32_e32 v34, v34
	v_add_f32_e32 v35, 1.0, v35
	v_fmac_f32_e32 v57, v38, v47
	v_and_b32_e32 v38, 0xffff0000, v66
	v_cvt_pk_bf16_f32 v44, v49, v52
	v_lshlrev_b32_e32 v49, 16, v71
	v_rcp_f32_e32 v35, v35
	v_add_f32_e32 v36, 1.0, v36
	v_fmac_f32_e32 v38, v39, v48
	v_lshlrev_b32_e32 v39, 16, v67
	v_fmac_f32_e32 v46, v57, v57
	v_and_b32_e32 v52, 0xffff0000, v71
	v_rcp_f32_e32 v36, v36
	v_add_f32_e32 v37, 1.0, v37
	v_fmac_f32_e32 v39, v40, v49
	v_and_b32_e32 v47, 0xffff0000, v67
	v_fmac_f32_e32 v46, v38, v38
	v_cvt_pk_bf16_f32 v45, v53, v54
	v_lshlrev_b32_e32 v53, 16, v72
	v_rcp_f32_e32 v37, v37
	v_fmac_f32_e32 v47, v41, v52
	v_lshlrev_b32_e32 v48, 16, v68
	v_fmac_f32_e32 v46, v39, v39
	v_and_b32_e32 v54, 0xffff0000, v72
	v_fmac_f32_e32 v48, v34, v53
	v_and_b32_e32 v49, 0xffff0000, v68
	v_fmac_f32_e32 v46, v47, v47
	v_lshlrev_b32_e32 v55, 16, v73
	v_fmac_f32_e32 v49, v35, v54
	v_lshlrev_b32_e32 v52, 16, v69
	v_fmac_f32_e32 v46, v48, v48
	v_and_b32_e32 v56, 0xffff0000, v73
	v_fmac_f32_e32 v52, v36, v55
	v_and_b32_e32 v53, 0xffff0000, v69
	v_fmac_f32_e32 v46, v49, v49
	v_fmac_f32_e32 v53, v37, v56
	v_fmac_f32_e32 v46, v52, v52
	v_fmac_f32_e32 v46, v53, v53
	ds_bpermute_b32 v37, v148, v46
	s_waitcnt lgkmcnt(1)
	v_lshlrev_b64 v[50:51], 11, v[98:99]
	v_lshl_add_u64 v[34:35], s[4:5], 0, v[50:51]
	v_lshl_add_u64 v[40:41], v[184:185], 1, v[34:35]
	global_store_dwordx4 v[40:41], v[42:45], off sc1
	s_waitcnt lgkmcnt(0)
	v_add_f32_e32 v34, v46, v37
	ds_bpermute_b32 v35, v149, v34
	v_cvt_pk_bf16_f32 v36, v57, v38
	v_cvt_pk_bf16_f32 v37, v39, v47
	v_cvt_pk_bf16_f32 v38, v48, v49
	v_cvt_pk_bf16_f32 v39, v52, v53
	global_store_dwordx4 v[40:41], v[36:39], off offset:256 sc1
	s_and_saveexec_b64 s[76:77], s[54:55]
	s_cbranch_execz .LBB0_817
	s_waitcnt lgkmcnt(0)
	v_add_f32_e32 v34, v34, v35
	v_mul_f32_e32 v34, 0x4d800000, v34
	v_trunc_f32_e32 v34, v34
	v_mul_f32_e32 v35, 0x2f800000, v34
	v_floor_f32_e32 v35, v35
	v_fmac_f32_e32 v34, 0xcf800000, v35
	v_cvt_u32_f32_e32 v34, v34
	v_cvt_u32_f32_e32 v35, v35
	global_atomic_add_x2 v[146:147], v[34:35], off offset:1152

.LBB0_825:
	s_waitcnt lgkmcnt(0)
	v_mul_f32_e32 v30, v30, v71
	v_mul_f32_e32 v30, 0xbfb8aa3b, v30
	v_mul_f32_e32 v31, v31, v71
	v_exp_f32_e32 v30, v30
	v_mul_f32_e32 v31, 0xbfb8aa3b, v31
	v_mul_f32_e32 v32, v32, v71
	v_exp_f32_e32 v31, v31
	v_mul_f32_e32 v32, 0xbfb8aa3b, v32
	v_mul_f32_e32 v33, v33, v71
	v_exp_f32_e32 v32, v32
	v_mul_f32_e32 v33, 0xbfb8aa3b, v33
	v_mul_f32_e32 v26, v26, v71
	v_exp_f32_e32 v33, v33
	v_mul_f32_e32 v26, 0xbfb8aa3b, v26
	v_add_f32_e32 v30, 1.0, v30
	v_exp_f32_e32 v26, v26
	v_rcp_f32_e32 v30, v30
	v_add_f32_e32 v31, 1.0, v31
	v_rcp_f32_e32 v31, v31
	v_add_f32_e32 v32, 1.0, v32
	v_mul_f32_e32 v27, v27, v71
	v_rcp_f32_e32 v32, v32
	v_add_f32_e32 v33, 1.0, v33
	v_mul_f32_e32 v27, 0xbfb8aa3b, v27
	v_mul_f32_e32 v28, v28, v71
	s_waitcnt vmcnt(5)
	v_lshlrev_b32_e32 v72, 16, v62
	v_exp_f32_e32 v27, v27
	v_rcp_f32_e32 v33, v33
	v_add_f32_e32 v26, 1.0, v26
	v_mul_f32_e32 v28, 0xbfb8aa3b, v28
	v_mul_f32_e32 v29, v29, v71
	v_lshlrev_b32_e32 v76, 16, v58
	v_and_b32_e32 v62, 0xffff0000, v62
	v_rcp_f32_e32 v26, v26
	v_exp_f32_e32 v28, v28
	v_mul_f32_e32 v29, 0xbfb8aa3b, v29
	v_fmac_f32_e32 v76, v30, v72
	v_and_b32_e32 v30, 0xffff0000, v58
	v_mul_f32_e32 v22, v22, v71
	v_lshlrev_b32_e32 v73, 16, v63
	v_exp_f32_e32 v29, v29
	v_fmac_f32_e32 v30, v31, v62
	v_lshlrev_b32_e32 v31, 16, v59
	v_mul_f32_e32 v22, 0xbfb8aa3b, v22
	v_mul_f32_e32 v23, v23, v71
	v_and_b32_e32 v63, 0xffff0000, v63
	v_fmac_f32_e32 v31, v32, v73
	v_and_b32_e32 v32, 0xffff0000, v59
	v_exp_f32_e32 v22, v22
	v_mul_f32_e32 v23, 0xbfb8aa3b, v23
	v_mul_f32_e32 v24, v24, v71
	v_lshlrev_b32_e32 v74, 16, v64
	v_add_f32_e32 v27, 1.0, v27
	v_fmac_f32_e32 v32, v33, v63
	v_lshlrev_b32_e32 v33, 16, v60
	v_exp_f32_e32 v23, v23
	v_mul_f32_e32 v24, 0xbfb8aa3b, v24
	v_mul_f32_e32 v25, v25, v71
	v_rcp_f32_e32 v27, v27
	v_add_f32_e32 v28, 1.0, v28
	v_fmac_f32_e32 v33, v26, v74
	v_cvt_pk_bf16_f32 v26, v76, v30
	v_mul_f32_e32 v30, v30, v30
	v_exp_f32_e32 v24, v24
	v_mul_f32_e32 v25, 0xbfb8aa3b, v25
	v_mul_f32_e32 v18, v18, v71
	v_rcp_f32_e32 v28, v28
	v_add_f32_e32 v29, 1.0, v29
	v_fmac_f32_e32 v30, v76, v76
	v_exp_f32_e32 v25, v25
	v_mul_f32_e32 v18, 0xbfb8aa3b, v18
	v_mul_f32_e32 v19, v19, v71
	v_rcp_f32_e32 v29, v29
	v_fmac_f32_e32 v30, v31, v31
	v_add_f32_e32 v22, 1.0, v22
	v_exp_f32_e32 v18, v18
	v_mul_f32_e32 v19, 0xbfb8aa3b, v19
	v_mul_f32_e32 v20, v20, v71
	v_and_b32_e32 v64, 0xffff0000, v64
	v_and_b32_e32 v58, 0xffff0000, v60
	v_fmac_f32_e32 v30, v32, v32
	v_rcp_f32_e32 v22, v22
	v_add_f32_e32 v23, 1.0, v23
	v_exp_f32_e32 v19, v19
	v_mul_f32_e32 v20, 0xbfb8aa3b, v20
	v_mul_f32_e32 v21, v21, v71
	v_lshlrev_b32_e32 v75, 16, v65
	v_fmac_f32_e32 v58, v27, v64
	v_lshlrev_b32_e32 v59, 16, v61
	v_fmac_f32_e32 v30, v33, v33
	v_rcp_f32_e32 v23, v23
	v_add_f32_e32 v24, 1.0, v24
	v_exp_f32_e32 v20, v20
	v_mul_f32_e32 v21, 0xbfb8aa3b, v21
	v_and_b32_e32 v65, 0xffff0000, v65
	v_fmac_f32_e32 v59, v28, v75
	v_and_b32_e32 v60, 0xffff0000, v61
	v_fmac_f32_e32 v30, v58, v58
	v_rcp_f32_e32 v24, v24
	v_add_f32_e32 v25, 1.0, v25
	v_exp_f32_e32 v21, v21
	v_fmac_f32_e32 v60, v29, v65
	v_cvt_pk_bf16_f32 v27, v31, v32
	v_cvt_pk_bf16_f32 v28, v33, v58
	v_cvt_pk_bf16_f32 v29, v59, v60
	v_fmac_f32_e32 v30, v59, v59
	s_waitcnt vmcnt(4)
	v_lshlrev_b32_e32 v31, 16, v54
	v_rcp_f32_e32 v25, v25
	v_add_f32_e32 v18, 1.0, v18
	v_lshlrev_b32_e32 v59, 16, v50
	v_fmac_f32_e32 v30, v60, v60
	v_and_b32_e32 v32, 0xffff0000, v54
	v_rcp_f32_e32 v18, v18
	v_add_f32_e32 v19, 1.0, v19
	v_fmac_f32_e32 v59, v22, v31
	v_and_b32_e32 v22, 0xffff0000, v50
	v_lshlrev_b32_e32 v33, 16, v55
	v_rcp_f32_e32 v19, v19
	v_add_f32_e32 v20, 1.0, v20
	v_fmac_f32_e32 v22, v23, v32
	v_lshlrev_b32_e32 v23, 16, v51
	v_fmac_f32_e32 v30, v59, v59
	v_and_b32_e32 v54, 0xffff0000, v55
	v_rcp_f32_e32 v20, v20
	v_add_f32_e32 v21, 1.0, v21
	v_fmac_f32_e32 v23, v24, v33
	v_and_b32_e32 v31, 0xffff0000, v51
	v_fmac_f32_e32 v30, v22, v22
	v_lshlrev_b32_e32 v55, 16, v56
	v_rcp_f32_e32 v21, v21
	v_fmac_f32_e32 v31, v25, v54
	v_lshlrev_b32_e32 v32, 16, v52
	v_fmac_f32_e32 v30, v23, v23
	v_and_b32_e32 v56, 0xffff0000, v56
	v_fmac_f32_e32 v32, v18, v55
	v_and_b32_e32 v33, 0xffff0000, v52
	v_fmac_f32_e32 v30, v31, v31
	v_lshlrev_b32_e32 v58, 16, v57
	v_fmac_f32_e32 v33, v19, v56
	v_lshlrev_b32_e32 v50, 16, v53
	v_fmac_f32_e32 v30, v32, v32
	v_and_b32_e32 v57, 0xffff0000, v57
	v_fmac_f32_e32 v50, v20, v58
	v_and_b32_e32 v51, 0xffff0000, v53
	v_fmac_f32_e32 v30, v33, v33
	v_fmac_f32_e32 v51, v21, v57
	v_fmac_f32_e32 v30, v50, v50
	v_fmac_f32_e32 v30, v51, v51
	ds_bpermute_b32 v21, v148, v30
	v_lshlrev_b64 v[68:69], 11, v[68:69]
	v_lshl_add_u64 v[18:19], s[4:5], 0, v[68:69]
	v_lshl_add_u64 v[24:25], v[184:185], 1, v[18:19]
	global_store_dwordx4 v[24:25], v[26:29], off sc1
	s_waitcnt lgkmcnt(0)
	v_add_f32_e32 v18, v30, v21
	ds_bpermute_b32 v19, v149, v18
	v_cvt_pk_bf16_f32 v20, v59, v22
	v_cvt_pk_bf16_f32 v21, v23, v31
	v_cvt_pk_bf16_f32 v22, v32, v33
	v_cvt_pk_bf16_f32 v23, v50, v51
	global_store_dwordx4 v[24:25], v[20:23], off offset:256 sc1
	s_and_saveexec_b64 s[76:77], s[54:55]
	s_cbranch_execz .LBB0_827
	s_waitcnt lgkmcnt(0)
	v_add_f32_e32 v18, v18, v19
	v_mul_f32_e32 v18, 0x4d800000, v18
	v_trunc_f32_e32 v18, v18
	v_mul_f32_e32 v19, 0x2f800000, v18
	v_floor_f32_e32 v19, v19
	v_fmac_f32_e32 v18, 0xcf800000, v19
	v_cvt_u32_f32_e32 v18, v18
	v_cvt_u32_f32_e32 v19, v19
	global_atomic_add_x2 v[146:147], v[18:19], off offset:1280
.LBB0_827:
	s_or_b64 exec, exec, s[76:77]
	v_mul_f32_e32 v14, v14, v70
	v_mul_f32_e32 v14, 0xbfb8aa3b, v14
	v_mul_f32_e32 v15, v15, v70
	v_exp_f32_e32 v14, v14
	v_mul_f32_e32 v15, 0xbfb8aa3b, v15
	v_mul_f32_e32 v16, v16, v70
	v_exp_f32_e32 v15, v15
	v_mul_f32_e32 v16, 0xbfb8aa3b, v16
	v_mul_f32_e32 v17, v17, v70
	v_exp_f32_e32 v16, v16
	v_mul_f32_e32 v17, 0xbfb8aa3b, v17
	v_mul_f32_e32 v10, v10, v70
	v_exp_f32_e32 v17, v17
	v_mul_f32_e32 v10, 0xbfb8aa3b, v10
	v_add_f32_e32 v14, 1.0, v14
	v_exp_f32_e32 v10, v10
	v_rcp_f32_e32 v14, v14
	v_add_f32_e32 v15, 1.0, v15
	v_rcp_f32_e32 v15, v15
	v_add_f32_e32 v16, 1.0, v16
	v_mul_f32_e32 v11, v11, v70
	v_rcp_f32_e32 v16, v16
	v_add_f32_e32 v17, 1.0, v17
	v_mul_f32_e32 v11, 0xbfb8aa3b, v11
	v_mul_f32_e32 v12, v12, v70
	s_waitcnt vmcnt(3)
	v_lshlrev_b32_e32 v20, 16, v46
	v_exp_f32_e32 v11, v11
	v_rcp_f32_e32 v17, v17
	v_add_f32_e32 v10, 1.0, v10
	v_mul_f32_e32 v12, 0xbfb8aa3b, v12
	v_mul_f32_e32 v13, v13, v70
	v_lshlrev_b32_e32 v28, 16, v42
	v_and_b32_e32 v21, 0xffff0000, v46
	v_rcp_f32_e32 v10, v10
	v_exp_f32_e32 v12, v12
	v_mul_f32_e32 v13, 0xbfb8aa3b, v13
	v_fmac_f32_e32 v28, v14, v20
	v_and_b32_e32 v14, 0xffff0000, v42
	v_mul_f32_e32 v6, v6, v70
	v_lshlrev_b32_e32 v22, 16, v47
	v_exp_f32_e32 v13, v13
	v_fmac_f32_e32 v14, v15, v21
	v_lshlrev_b32_e32 v15, 16, v43
	v_mul_f32_e32 v6, 0xbfb8aa3b, v6
	v_mul_f32_e32 v7, v7, v70
	v_and_b32_e32 v23, 0xffff0000, v47
	v_fmac_f32_e32 v15, v16, v22
	v_and_b32_e32 v16, 0xffff0000, v43
	v_exp_f32_e32 v6, v6
	v_mul_f32_e32 v7, 0xbfb8aa3b, v7
	v_mul_f32_e32 v8, v8, v70
	v_lshlrev_b32_e32 v24, 16, v48
	v_add_f32_e32 v11, 1.0, v11
	v_fmac_f32_e32 v16, v17, v23
	v_lshlrev_b32_e32 v17, 16, v44
	v_exp_f32_e32 v7, v7
	v_mul_f32_e32 v8, 0xbfb8aa3b, v8
	v_mul_f32_e32 v9, v9, v70
	v_rcp_f32_e32 v11, v11
	v_add_f32_e32 v12, 1.0, v12
	v_fmac_f32_e32 v17, v10, v24
	v_cvt_pk_bf16_f32 v10, v28, v14
	v_mul_f32_e32 v14, v14, v14
	v_exp_f32_e32 v8, v8
	v_mul_f32_e32 v9, 0xbfb8aa3b, v9
	v_mul_f32_e32 v2, v2, v70
	v_rcp_f32_e32 v12, v12
	v_add_f32_e32 v13, 1.0, v13
	v_fmac_f32_e32 v14, v28, v28
	v_exp_f32_e32 v9, v9
	v_mul_f32_e32 v2, 0xbfb8aa3b, v2
	v_mul_f32_e32 v3, v3, v70
	v_rcp_f32_e32 v13, v13
	v_fmac_f32_e32 v14, v15, v15
	v_add_f32_e32 v6, 1.0, v6
	v_exp_f32_e32 v2, v2
	v_mul_f32_e32 v3, 0xbfb8aa3b, v3
	v_mul_f32_e32 v4, v4, v70
	v_and_b32_e32 v25, 0xffff0000, v48
	v_and_b32_e32 v20, 0xffff0000, v44
	v_fmac_f32_e32 v14, v16, v16
	v_rcp_f32_e32 v6, v6
	v_add_f32_e32 v7, 1.0, v7
	v_exp_f32_e32 v3, v3
	v_mul_f32_e32 v4, 0xbfb8aa3b, v4
	v_mul_f32_e32 v5, v5, v70
	v_lshlrev_b32_e32 v26, 16, v49
	v_fmac_f32_e32 v20, v11, v25
	v_lshlrev_b32_e32 v21, 16, v45
	v_fmac_f32_e32 v14, v17, v17
	v_rcp_f32_e32 v7, v7
	v_add_f32_e32 v8, 1.0, v8
	v_exp_f32_e32 v4, v4
	v_mul_f32_e32 v5, 0xbfb8aa3b, v5
	v_and_b32_e32 v27, 0xffff0000, v49
	v_fmac_f32_e32 v21, v12, v26
	v_and_b32_e32 v22, 0xffff0000, v45
	v_fmac_f32_e32 v14, v20, v20
	v_rcp_f32_e32 v8, v8
	v_add_f32_e32 v9, 1.0, v9
	v_exp_f32_e32 v5, v5
	v_fmac_f32_e32 v22, v13, v27
	v_cvt_pk_bf16_f32 v11, v15, v16
	v_fmac_f32_e32 v14, v21, v21
	s_waitcnt vmcnt(2)
	v_lshlrev_b32_e32 v15, 16, v38
	v_rcp_f32_e32 v9, v9
	v_add_f32_e32 v2, 1.0, v2
	v_lshlrev_b32_e32 v25, 16, v34
	v_fmac_f32_e32 v14, v22, v22
	v_and_b32_e32 v16, 0xffff0000, v38
	v_rcp_f32_e32 v2, v2
	v_add_f32_e32 v3, 1.0, v3
	v_fmac_f32_e32 v25, v6, v15
	v_and_b32_e32 v6, 0xffff0000, v34
	v_cvt_pk_bf16_f32 v12, v17, v20
	v_lshlrev_b32_e32 v17, 16, v39
	v_rcp_f32_e32 v3, v3
	v_add_f32_e32 v4, 1.0, v4
	v_fmac_f32_e32 v6, v7, v16
	v_lshlrev_b32_e32 v7, 16, v35
	v_fmac_f32_e32 v14, v25, v25
	v_and_b32_e32 v20, 0xffff0000, v39
	v_rcp_f32_e32 v4, v4
	v_add_f32_e32 v5, 1.0, v5
	v_fmac_f32_e32 v7, v8, v17
	v_and_b32_e32 v15, 0xffff0000, v35
	v_fmac_f32_e32 v14, v6, v6
	v_cvt_pk_bf16_f32 v13, v21, v22
	v_lshlrev_b32_e32 v21, 16, v40
	v_rcp_f32_e32 v5, v5
	v_fmac_f32_e32 v15, v9, v20
	v_lshlrev_b32_e32 v16, 16, v36
	v_fmac_f32_e32 v14, v7, v7
	v_and_b32_e32 v22, 0xffff0000, v40
	v_fmac_f32_e32 v16, v2, v21
	v_and_b32_e32 v17, 0xffff0000, v36
	v_fmac_f32_e32 v14, v15, v15
	v_lshlrev_b32_e32 v23, 16, v41
	v_fmac_f32_e32 v17, v3, v22
	v_lshlrev_b32_e32 v20, 16, v37
	v_fmac_f32_e32 v14, v16, v16
	v_and_b32_e32 v24, 0xffff0000, v41
	v_fmac_f32_e32 v20, v4, v23
	v_and_b32_e32 v21, 0xffff0000, v37
	v_fmac_f32_e32 v14, v17, v17
	v_fmac_f32_e32 v21, v5, v24
	v_fmac_f32_e32 v14, v20, v20
	v_fmac_f32_e32 v14, v21, v21
	ds_bpermute_b32 v5, v148, v14
	s_waitcnt lgkmcnt(1)
	v_lshlrev_b64 v[18:19], 11, v[66:67]
	v_lshl_add_u64 v[2:3], s[4:5], 0, v[18:19]
	v_lshl_add_u64 v[8:9], v[184:185], 1, v[2:3]
	global_store_dwordx4 v[8:9], v[10:13], off sc1
	s_waitcnt lgkmcnt(0)
	v_add_f32_e32 v2, v14, v5
	ds_bpermute_b32 v3, v149, v2
	v_cvt_pk_bf16_f32 v4, v25, v6
	v_cvt_pk_bf16_f32 v5, v7, v15
	v_cvt_pk_bf16_f32 v6, v16, v17
	v_cvt_pk_bf16_f32 v7, v20, v21
	global_store_dwordx4 v[8:9], v[4:7], off offset:256 sc1
	s_and_saveexec_b64 s[76:77], s[54:55]
	s_cbranch_execz .LBB0_829
	s_waitcnt lgkmcnt(0)
	v_add_f32_e32 v2, v2, v3
	v_mul_f32_e32 v2, 0x4d800000, v2
	v_trunc_f32_e32 v2, v2
	v_mul_f32_e32 v3, 0x2f800000, v2
	v_floor_f32_e32 v3, v3
	v_fmac_f32_e32 v2, 0xcf800000, v3
	v_cvt_u32_f32_e32 v2, v2
	v_cvt_u32_f32_e32 v3, v3
	global_atomic_add_x2 v[146:147], v[2:3], off offset:1408

.LBB0_866:
	s_or_saveexec_b64 s[56:57], s[56:57]
	v_ashrrev_i32_e32 v142, 4, v0
	v_lshlrev_b64 v[152:153], 5, v[140:141]
	v_ashrrev_i32_e32 v143, 31, v142
	v_lshlrev_b32_e32 v138, 1, v134
	s_xor_b64 exec, exec, s[56:57]
	v_lshlrev_b64 v[150:151], 20, v[142:143]
	v_lshl_add_u64 v[150:151], s[40:41], 0, v[150:151]
	v_lshl_add_u64 v[150:151], v[150:151], 0, v[152:153]
	v_mov_b32_e32 v139, v1
	v_lshl_add_u64 v[150:151], v[150:151], 0, v[138:139]
	v_mov_b32_e32 v154, v144
	s_or_b64 exec, exec, s[56:57]
	v_pk_mul_f32 v[126:127], v[126:127], v[154:155] op_sel_hi:[1,0]
	v_pk_mul_f32 v[160:161], v[124:125], v[154:155] op_sel_hi:[1,0]
	v_pk_mul_f32 v[124:125], v[122:123], v[154:155] op_sel_hi:[1,0]
	v_cvt_pk_bf16_f32 v122, v126, v127
	v_pk_mul_f32 v[128:129], v[128:129], v[154:155] op_sel_hi:[1,0]
	s_movk_i32 s12, 0x1ff
	v_cvt_pk_bf16_f32 v123, v128, v129
	v_cvt_pk_bf16_f32 v124, v124, v125
	v_cvt_pk_bf16_f32 v125, v160, v161
	global_store_dwordx4 v[150:151], v[122:125], off sc1
	s_nop 1
	v_or_b32_e32 v122, 0x80, v0
	v_cmp_lt_i32_e64 s[56:57], s12, v122
	s_and_saveexec_b64 s[20:21], s[56:57]
	s_xor_b64 s[76:77], exec, s[20:21]
	s_cbranch_execz .LBB0_874
	s_cmpk_lt_u32 s69, 0x400
	s_mov_b64 s[90:91], -1
	s_cbranch_scc1 .LBB0_871
	v_lshl_add_u64 v[124:125], s[60:61], 0, v[148:149]
	s_movk_i32 s12, 0xf800
	v_lshl_add_u64 v[124:125], v[0:1], 1, v[124:125]
	s_mov_b32 s13, -1
	v_lshl_add_u64 v[124:125], v[124:125], 0, s[12:13]
	s_mov_b64 s[90:91], 0

.LBB0_873:
.LBB0_874:
	s_or_saveexec_b64 s[76:77], s[76:77]
	v_ashrrev_i32_e32 v122, 4, v122
	v_ashrrev_i32_e32 v123, 31, v122
	s_xor_b64 exec, exec, s[76:77]
	v_lshlrev_b64 v[124:125], 20, v[122:123]
	v_lshl_add_u64 v[124:125], s[40:41], 0, v[124:125]
	v_lshl_add_u64 v[124:125], v[124:125], 0, v[152:153]
	v_mov_b32_e32 v139, v1
	v_lshl_add_u64 v[124:125], v[124:125], 0, v[138:139]
	s_or_b64 exec, exec, s[76:77]
	v_pk_mul_f32 v[120:121], v[120:121], v[144:145] op_sel_hi:[1,0]
	v_pk_mul_f32 v[118:119], v[118:119], v[144:145] op_sel_hi:[1,0]
	v_pk_mul_f32 v[126:127], v[116:117], v[144:145] op_sel_hi:[1,0]
	v_pk_mul_f32 v[116:117], v[114:115], v[144:145] op_sel_hi:[1,0]
	v_cvt_pk_bf16_f32 v114, v118, v119
	v_cvt_pk_bf16_f32 v115, v120, v121
	v_or_b32_e32 v120, 16, v140
	s_mov_b64 s[76:77], -1
	s_and_b64 vcc, exec, s[52:53]
	v_ashrrev_i32_e32 v121, 31, v120
	v_cvt_pk_bf16_f32 v116, v116, v117
	v_cvt_pk_bf16_f32 v117, v126, v127
	global_store_dwordx4 v[124:125], v[114:117], off sc1
	s_cbranch_vccnz .LBB0_878
	ds_read_b32 v114, v158 offset:64
	s_mov_b64 s[76:77], 0

.LBB0_889:
	s_or_saveexec_b64 s[76:77], s[76:77]
	v_lshlrev_b64 v[120:121], 5, v[120:121]
	s_xor_b64 exec, exec, s[76:77]
	v_lshlrev_b64 v[124:125], 20, v[142:143]
	v_lshl_add_u64 v[124:125], s[40:41], 0, v[124:125]
	v_lshl_add_u64 v[124:125], v[124:125], 0, v[120:121]
	v_mov_b32_e32 v139, v1
	v_lshl_add_u64 v[124:125], v[124:125], 0, v[138:139]
	v_mov_b32_e32 v126, v114
	s_or_b64 exec, exec, s[76:77]
	v_pk_mul_f32 v[112:113], v[112:113], v[126:127] op_sel_hi:[1,0]
	v_pk_mul_f32 v[110:111], v[110:111], v[126:127] op_sel_hi:[1,0]
	v_pk_mul_f32 v[128:129], v[108:109], v[126:127] op_sel_hi:[1,0]
	v_pk_mul_f32 v[108:109], v[106:107], v[126:127] op_sel_hi:[1,0]
	v_cvt_pk_bf16_f32 v106, v110, v111
	v_cvt_pk_bf16_f32 v107, v112, v113
	s_nop 0
	v_cvt_pk_bf16_f32 v108, v108, v109
	v_cvt_pk_bf16_f32 v109, v128, v129
	global_store_dwordx4 v[124:125], v[106:109], off sc1
	s_and_saveexec_b64 s[20:21], s[56:57]
	s_xor_b64 s[76:77], exec, s[20:21]
	s_cbranch_execz .LBB0_897
	s_cmpk_lt_u32 s69, 0x400
	s_mov_b64 s[90:91], -1
	s_cbranch_scc1 .LBB0_894
	v_lshl_add_u64 v[106:107], s[60:61], 0, v[118:119]
	s_movk_i32 s12, 0xf800
	v_lshl_add_u64 v[106:107], v[0:1], 1, v[106:107]
	s_mov_b32 s13, -1
	v_lshl_add_u64 v[106:107], v[106:107], 0, s[12:13]
	s_mov_b64 s[90:91], 0

.LBB0_896:
.LBB0_897:
	s_andn2_saveexec_b64 s[76:77], s[76:77]
	v_lshlrev_b64 v[106:107], 20, v[122:123]
	v_lshl_add_u64 v[106:107], s[40:41], 0, v[106:107]
	v_lshl_add_u64 v[106:107], v[106:107], 0, v[120:121]
	v_mov_b32_e32 v139, v1
	v_lshl_add_u64 v[106:107], v[106:107], 0, v[138:139]
	s_or_b64 exec, exec, s[76:77]
	v_pk_mul_f32 v[104:105], v[104:105], v[114:115] op_sel_hi:[1,0]
	v_pk_mul_f32 v[102:103], v[102:103], v[114:115] op_sel_hi:[1,0]
	v_pk_mul_f32 v[108:109], v[100:101], v[114:115] op_sel_hi:[1,0]
	v_pk_mul_f32 v[100:101], v[98:99], v[114:115] op_sel_hi:[1,0]
	v_cvt_pk_bf16_f32 v98, v102, v103
	v_cvt_pk_bf16_f32 v99, v104, v105
	v_or_b32_e32 v104, 32, v140
	s_mov_b64 s[76:77], -1
	s_and_b64 vcc, exec, s[52:53]
	v_ashrrev_i32_e32 v105, 31, v104
	v_cvt_pk_bf16_f32 v100, v100, v101
	v_cvt_pk_bf16_f32 v101, v108, v109
	global_store_dwordx4 v[106:107], v[98:101], off sc1
	s_cbranch_vccnz .LBB0_901
	ds_read_b32 v98, v158 offset:128
	s_mov_b64 s[76:77], 0

.LBB0_912:
	s_or_saveexec_b64 s[76:77], s[76:77]
	v_lshlrev_b64 v[104:105], 5, v[104:105]
	s_xor_b64 exec, exec, s[76:77]
	v_lshlrev_b64 v[106:107], 20, v[142:143]
	v_lshl_add_u64 v[106:107], s[40:41], 0, v[106:107]
	v_lshl_add_u64 v[106:107], v[106:107], 0, v[104:105]
	v_mov_b32_e32 v139, v1
	v_lshl_add_u64 v[106:107], v[106:107], 0, v[138:139]
	v_mov_b32_e32 v108, v98
	s_or_b64 exec, exec, s[76:77]
	v_pk_mul_f32 v[96:97], v[96:97], v[108:109] op_sel_hi:[1,0]
	v_pk_mul_f32 v[94:95], v[94:95], v[108:109] op_sel_hi:[1,0]
	v_pk_mul_f32 v[110:111], v[92:93], v[108:109] op_sel_hi:[1,0]
	v_pk_mul_f32 v[92:93], v[90:91], v[108:109] op_sel_hi:[1,0]
	v_cvt_pk_bf16_f32 v90, v94, v95
	v_cvt_pk_bf16_f32 v91, v96, v97
	s_nop 0
	v_cvt_pk_bf16_f32 v92, v92, v93
	v_cvt_pk_bf16_f32 v93, v110, v111
	global_store_dwordx4 v[106:107], v[90:93], off sc1
	s_and_saveexec_b64 s[20:21], s[56:57]
	s_xor_b64 s[76:77], exec, s[20:21]
	s_cbranch_execz .LBB0_920
	s_cmpk_lt_u32 s69, 0x400
	s_mov_b64 s[90:91], -1
	s_cbranch_scc1 .LBB0_917
	v_lshl_add_u64 v[90:91], s[60:61], 0, v[102:103]
	s_movk_i32 s12, 0xf800
	v_lshl_add_u64 v[90:91], v[0:1], 1, v[90:91]
	s_mov_b32 s13, -1
	v_lshl_add_u64 v[90:91], v[90:91], 0, s[12:13]
	s_mov_b64 s[90:91], 0

.LBB0_919:
.LBB0_920:
	s_andn2_saveexec_b64 s[76:77], s[76:77]
	v_lshlrev_b64 v[90:91], 20, v[122:123]
	v_lshl_add_u64 v[90:91], s[40:41], 0, v[90:91]
	v_lshl_add_u64 v[90:91], v[90:91], 0, v[104:105]
	v_mov_b32_e32 v139, v1
	v_lshl_add_u64 v[90:91], v[90:91], 0, v[138:139]
	s_or_b64 exec, exec, s[76:77]
	v_pk_mul_f32 v[88:89], v[88:89], v[98:99] op_sel_hi:[1,0]
	v_pk_mul_f32 v[86:87], v[86:87], v[98:99] op_sel_hi:[1,0]
	v_pk_mul_f32 v[92:93], v[84:85], v[98:99] op_sel_hi:[1,0]
	v_pk_mul_f32 v[84:85], v[82:83], v[98:99] op_sel_hi:[1,0]
	v_cvt_pk_bf16_f32 v82, v86, v87
	v_cvt_pk_bf16_f32 v83, v88, v89
	v_or_b32_e32 v88, 48, v140
	s_mov_b64 s[76:77], -1
	s_and_b64 vcc, exec, s[52:53]
	v_ashrrev_i32_e32 v89, 31, v88
	v_cvt_pk_bf16_f32 v84, v84, v85
	v_cvt_pk_bf16_f32 v85, v92, v93
	global_store_dwordx4 v[90:91], v[82:85], off sc1
	s_cbranch_vccnz .LBB0_924
	ds_read_b32 v82, v158 offset:192
	s_mov_b64 s[76:77], 0

.LBB0_935:
	s_or_saveexec_b64 s[76:77], s[76:77]
	v_lshlrev_b64 v[88:89], 5, v[88:89]
	s_xor_b64 exec, exec, s[76:77]
	v_lshlrev_b64 v[90:91], 20, v[142:143]
	v_lshl_add_u64 v[90:91], s[40:41], 0, v[90:91]
	v_lshl_add_u64 v[90:91], v[90:91], 0, v[88:89]
	v_mov_b32_e32 v139, v1
	v_lshl_add_u64 v[90:91], v[90:91], 0, v[138:139]
	v_mov_b32_e32 v92, v82
	s_or_b64 exec, exec, s[76:77]
	v_pk_mul_f32 v[80:81], v[80:81], v[92:93] op_sel_hi:[1,0]
	v_pk_mul_f32 v[78:79], v[78:79], v[92:93] op_sel_hi:[1,0]
	v_pk_mul_f32 v[94:95], v[76:77], v[92:93] op_sel_hi:[1,0]
	v_pk_mul_f32 v[76:77], v[74:75], v[92:93] op_sel_hi:[1,0]
	v_cvt_pk_bf16_f32 v74, v78, v79
	v_cvt_pk_bf16_f32 v75, v80, v81
	s_nop 0
	v_cvt_pk_bf16_f32 v76, v76, v77
	v_cvt_pk_bf16_f32 v77, v94, v95
	global_store_dwordx4 v[90:91], v[74:77], off sc1
	s_and_saveexec_b64 s[20:21], s[56:57]
	s_xor_b64 s[76:77], exec, s[20:21]
	s_cbranch_execz .LBB0_943
	s_cmpk_lt_u32 s69, 0x400
	s_mov_b64 s[90:91], -1
	s_cbranch_scc1 .LBB0_940
	v_lshl_add_u64 v[74:75], s[60:61], 0, v[86:87]
	s_movk_i32 s12, 0xf800
	v_lshl_add_u64 v[74:75], v[0:1], 1, v[74:75]
	s_mov_b32 s13, -1
	v_lshl_add_u64 v[74:75], v[74:75], 0, s[12:13]
	s_mov_b64 s[90:91], 0

.LBB0_942:
.LBB0_943:
	s_andn2_saveexec_b64 s[76:77], s[76:77]
	v_lshlrev_b64 v[74:75], 20, v[122:123]
	v_lshl_add_u64 v[74:75], s[40:41], 0, v[74:75]
	v_lshl_add_u64 v[74:75], v[74:75], 0, v[88:89]
	v_mov_b32_e32 v139, v1
	v_lshl_add_u64 v[74:75], v[74:75], 0, v[138:139]
	s_or_b64 exec, exec, s[76:77]
	v_pk_mul_f32 v[72:73], v[72:73], v[82:83] op_sel_hi:[1,0]
	v_pk_mul_f32 v[70:71], v[70:71], v[82:83] op_sel_hi:[1,0]
	v_pk_mul_f32 v[76:77], v[68:69], v[82:83] op_sel_hi:[1,0]
	v_pk_mul_f32 v[68:69], v[66:67], v[82:83] op_sel_hi:[1,0]
	v_cvt_pk_bf16_f32 v66, v70, v71
	v_cvt_pk_bf16_f32 v67, v72, v73
	v_add_u32_e32 v72, 0x80, v140
	s_mov_b64 s[76:77], -1
	s_and_b64 vcc, exec, s[52:53]
	v_ashrrev_i32_e32 v73, 31, v72
	v_cvt_pk_bf16_f32 v68, v68, v69
	v_cvt_pk_bf16_f32 v69, v76, v77
	global_store_dwordx4 v[74:75], v[66:69], off sc1
	s_cbranch_vccnz .LBB0_947
	ds_read_b32 v66, v158 offset:512
	s_mov_b64 s[76:77], 0

.LBB0_958:
	s_or_saveexec_b64 s[76:77], s[76:77]
	v_lshlrev_b64 v[72:73], 5, v[72:73]
	s_xor_b64 exec, exec, s[76:77]
	v_lshlrev_b64 v[74:75], 20, v[142:143]
	v_lshl_add_u64 v[74:75], s[40:41], 0, v[74:75]
	v_lshl_add_u64 v[74:75], v[74:75], 0, v[72:73]
	v_mov_b32_e32 v139, v1
	v_lshl_add_u64 v[74:75], v[74:75], 0, v[138:139]
	v_mov_b32_e32 v76, v66
	s_or_b64 exec, exec, s[76:77]
	v_pk_mul_f32 v[64:65], v[64:65], v[76:77] op_sel_hi:[1,0]
	v_pk_mul_f32 v[62:63], v[62:63], v[76:77] op_sel_hi:[1,0]
	v_pk_mul_f32 v[78:79], v[60:61], v[76:77] op_sel_hi:[1,0]
	v_pk_mul_f32 v[60:61], v[58:59], v[76:77] op_sel_hi:[1,0]
	v_cvt_pk_bf16_f32 v58, v62, v63
	v_cvt_pk_bf16_f32 v59, v64, v65
	s_nop 0
	v_cvt_pk_bf16_f32 v60, v60, v61
	v_cvt_pk_bf16_f32 v61, v78, v79
	global_store_dwordx4 v[74:75], v[58:61], off sc1
	s_and_saveexec_b64 s[20:21], s[56:57]
	s_xor_b64 s[76:77], exec, s[20:21]
	s_cbranch_execz .LBB0_966
	s_cmpk_lt_u32 s69, 0x400
	s_mov_b64 s[90:91], -1
	s_cbranch_scc1 .LBB0_963
	v_lshl_add_u64 v[58:59], s[60:61], 0, v[70:71]
	s_movk_i32 s12, 0xf800
	v_lshl_add_u64 v[58:59], v[0:1], 1, v[58:59]
	s_mov_b32 s13, -1
	v_lshl_add_u64 v[58:59], v[58:59], 0, s[12:13]
	s_mov_b64 s[90:91], 0

.LBB0_965:
.LBB0_966:
	s_andn2_saveexec_b64 s[76:77], s[76:77]
	v_lshlrev_b64 v[58:59], 20, v[122:123]
	v_lshl_add_u64 v[58:59], s[40:41], 0, v[58:59]
	v_lshl_add_u64 v[58:59], v[58:59], 0, v[72:73]
	v_mov_b32_e32 v139, v1
	v_lshl_add_u64 v[58:59], v[58:59], 0, v[138:139]
	s_or_b64 exec, exec, s[76:77]
	v_pk_mul_f32 v[56:57], v[56:57], v[66:67] op_sel_hi:[1,0]
	v_pk_mul_f32 v[54:55], v[54:55], v[66:67] op_sel_hi:[1,0]
	v_pk_mul_f32 v[60:61], v[52:53], v[66:67] op_sel_hi:[1,0]
	v_pk_mul_f32 v[52:53], v[50:51], v[66:67] op_sel_hi:[1,0]
	v_cvt_pk_bf16_f32 v50, v54, v55
	v_cvt_pk_bf16_f32 v51, v56, v57
	v_add_u32_e32 v56, 0x90, v140
	s_mov_b64 s[76:77], -1
	s_and_b64 vcc, exec, s[52:53]
	v_ashrrev_i32_e32 v57, 31, v56
	v_cvt_pk_bf16_f32 v52, v52, v53
	v_cvt_pk_bf16_f32 v53, v60, v61
	global_store_dwordx4 v[58:59], v[50:53], off sc1
	s_cbranch_vccnz .LBB0_970
	ds_read_b32 v50, v158 offset:576
	s_mov_b64 s[76:77], 0

.LBB0_981:
	s_or_saveexec_b64 s[76:77], s[76:77]
	v_lshlrev_b64 v[56:57], 5, v[56:57]
	s_xor_b64 exec, exec, s[76:77]
	v_lshlrev_b64 v[58:59], 20, v[142:143]
	v_lshl_add_u64 v[58:59], s[40:41], 0, v[58:59]
	v_lshl_add_u64 v[58:59], v[58:59], 0, v[56:57]
	v_mov_b32_e32 v139, v1
	v_lshl_add_u64 v[58:59], v[58:59], 0, v[138:139]
	v_mov_b32_e32 v60, v50
	s_or_b64 exec, exec, s[76:77]
	v_pk_mul_f32 v[48:49], v[48:49], v[60:61] op_sel_hi:[1,0]
	v_pk_mul_f32 v[46:47], v[46:47], v[60:61] op_sel_hi:[1,0]
	v_pk_mul_f32 v[62:63], v[44:45], v[60:61] op_sel_hi:[1,0]
	v_pk_mul_f32 v[44:45], v[42:43], v[60:61] op_sel_hi:[1,0]
	v_cvt_pk_bf16_f32 v42, v46, v47
	v_cvt_pk_bf16_f32 v43, v48, v49
	s_nop 0
	v_cvt_pk_bf16_f32 v44, v44, v45
	v_cvt_pk_bf16_f32 v45, v62, v63
	global_store_dwordx4 v[58:59], v[42:45], off sc1
	s_and_saveexec_b64 s[20:21], s[56:57]
	s_xor_b64 s[76:77], exec, s[20:21]
	s_cbranch_execz .LBB0_989
	s_cmpk_lt_u32 s69, 0x400
	s_mov_b64 s[90:91], -1
	s_cbranch_scc1 .LBB0_986
	v_lshl_add_u64 v[42:43], s[60:61], 0, v[54:55]
	s_movk_i32 s12, 0xf800
	v_lshl_add_u64 v[42:43], v[0:1], 1, v[42:43]
	s_mov_b32 s13, -1
	v_lshl_add_u64 v[42:43], v[42:43], 0, s[12:13]
	s_mov_b64 s[90:91], 0

.LBB0_988:
.LBB0_989:
	s_andn2_saveexec_b64 s[76:77], s[76:77]
	v_lshlrev_b64 v[42:43], 20, v[122:123]
	v_lshl_add_u64 v[42:43], s[40:41], 0, v[42:43]
	v_lshl_add_u64 v[42:43], v[42:43], 0, v[56:57]
	v_mov_b32_e32 v139, v1
	v_lshl_add_u64 v[42:43], v[42:43], 0, v[138:139]
	s_or_b64 exec, exec, s[76:77]
	v_pk_mul_f32 v[40:41], v[40:41], v[50:51] op_sel_hi:[1,0]
	v_pk_mul_f32 v[38:39], v[38:39], v[50:51] op_sel_hi:[1,0]
	v_pk_mul_f32 v[44:45], v[36:37], v[50:51] op_sel_hi:[1,0]
	v_pk_mul_f32 v[36:37], v[34:35], v[50:51] op_sel_hi:[1,0]
	v_cvt_pk_bf16_f32 v34, v38, v39
	v_cvt_pk_bf16_f32 v35, v40, v41
	v_add_u32_e32 v40, 0xa0, v140
	s_mov_b64 s[76:77], -1
	s_and_b64 vcc, exec, s[52:53]
	v_ashrrev_i32_e32 v41, 31, v40
	v_cvt_pk_bf16_f32 v36, v36, v37
	v_cvt_pk_bf16_f32 v37, v44, v45
	global_store_dwordx4 v[42:43], v[34:37], off sc1
	s_cbranch_vccnz .LBB0_993
	ds_read_b32 v34, v158 offset:640
	s_mov_b64 s[76:77], 0

.LBB0_1004:
	s_or_saveexec_b64 s[76:77], s[76:77]
	v_lshlrev_b64 v[40:41], 5, v[40:41]
	s_xor_b64 exec, exec, s[76:77]
	v_lshlrev_b64 v[42:43], 20, v[142:143]
	v_lshl_add_u64 v[42:43], s[40:41], 0, v[42:43]
	v_lshl_add_u64 v[42:43], v[42:43], 0, v[40:41]
	v_mov_b32_e32 v139, v1
	v_lshl_add_u64 v[42:43], v[42:43], 0, v[138:139]
	v_mov_b32_e32 v44, v34
	s_or_b64 exec, exec, s[76:77]
	v_pk_mul_f32 v[32:33], v[32:33], v[44:45] op_sel_hi:[1,0]
	v_pk_mul_f32 v[30:31], v[30:31], v[44:45] op_sel_hi:[1,0]
	v_pk_mul_f32 v[46:47], v[28:29], v[44:45] op_sel_hi:[1,0]
	v_pk_mul_f32 v[28:29], v[26:27], v[44:45] op_sel_hi:[1,0]
	v_cvt_pk_bf16_f32 v26, v30, v31
	v_cvt_pk_bf16_f32 v27, v32, v33
	s_nop 0
	v_cvt_pk_bf16_f32 v28, v28, v29
	v_cvt_pk_bf16_f32 v29, v46, v47
	global_store_dwordx4 v[42:43], v[26:29], off sc1
	s_and_saveexec_b64 s[20:21], s[56:57]
	s_xor_b64 s[76:77], exec, s[20:21]
	s_cbranch_execz .LBB0_1012
	s_cmpk_lt_u32 s69, 0x400
	s_mov_b64 s[90:91], -1
	s_cbranch_scc1 .LBB0_1009
	v_lshl_add_u64 v[26:27], s[60:61], 0, v[38:39]
	s_movk_i32 s12, 0xf800
	v_lshl_add_u64 v[26:27], v[0:1], 1, v[26:27]
	s_mov_b32 s13, -1
	v_lshl_add_u64 v[26:27], v[26:27], 0, s[12:13]
	s_mov_b64 s[90:91], 0

.LBB0_1011:
.LBB0_1012:
	s_andn2_saveexec_b64 s[76:77], s[76:77]
	v_lshlrev_b64 v[26:27], 20, v[122:123]
	v_lshl_add_u64 v[26:27], s[40:41], 0, v[26:27]
	v_lshl_add_u64 v[26:27], v[26:27], 0, v[40:41]
	v_mov_b32_e32 v139, v1
	v_lshl_add_u64 v[26:27], v[26:27], 0, v[138:139]
	s_or_b64 exec, exec, s[76:77]
	v_pk_mul_f32 v[24:25], v[24:25], v[34:35] op_sel_hi:[1,0]
	v_pk_mul_f32 v[22:23], v[22:23], v[34:35] op_sel_hi:[1,0]
	v_pk_mul_f32 v[28:29], v[20:21], v[34:35] op_sel_hi:[1,0]
	v_pk_mul_f32 v[20:21], v[18:19], v[34:35] op_sel_hi:[1,0]
	v_cvt_pk_bf16_f32 v18, v22, v23
	v_cvt_pk_bf16_f32 v19, v24, v25
	v_add_u32_e32 v24, 0xb0, v140
	s_mov_b64 s[76:77], -1
	s_and_b64 vcc, exec, s[52:53]
	v_ashrrev_i32_e32 v25, 31, v24
	v_cvt_pk_bf16_f32 v20, v20, v21
	v_cvt_pk_bf16_f32 v21, v28, v29
	global_store_dwordx4 v[26:27], v[18:21], off sc1
	s_cbranch_vccnz .LBB0_1016
	ds_read_b32 v18, v158 offset:704
	s_mov_b64 s[76:77], 0

.LBB0_1027:
.LBB0_1028:
	s_or_saveexec_b64 s[58:59], s[58:59]
	v_lshlrev_b64 v[24:25], 5, v[24:25]
	s_xor_b64 exec, exec, s[58:59]
	v_lshlrev_b64 v[26:27], 20, v[142:143]
	v_lshl_add_u64 v[26:27], s[40:41], 0, v[26:27]
	v_lshl_add_u64 v[26:27], v[26:27], 0, v[24:25]
	v_mov_b32_e32 v139, v1
	v_lshl_add_u64 v[26:27], v[26:27], 0, v[138:139]
	v_mov_b32_e32 v28, v18
	s_or_b64 exec, exec, s[58:59]
	v_pk_mul_f32 v[16:17], v[16:17], v[28:29] op_sel_hi:[1,0]
	v_pk_mul_f32 v[14:15], v[14:15], v[28:29] op_sel_hi:[1,0]
	v_pk_mul_f32 v[30:31], v[12:13], v[28:29] op_sel_hi:[1,0]
	v_pk_mul_f32 v[12:13], v[10:11], v[28:29] op_sel_hi:[1,0]
	v_cvt_pk_bf16_f32 v10, v14, v15
	v_cvt_pk_bf16_f32 v11, v16, v17
	s_nop 0
	v_cvt_pk_bf16_f32 v12, v12, v13
	v_cvt_pk_bf16_f32 v13, v30, v31
	global_store_dwordx4 v[26:27], v[10:13], off sc1
	s_and_saveexec_b64 s[20:21], s[56:57]
	s_xor_b64 s[56:57], exec, s[20:21]
	s_cbranch_execz .LBB0_1036
	s_cmpk_lt_u32 s69, 0x400
	s_mov_b64 s[58:59], -1
	s_cbranch_scc1 .LBB0_1033
	v_lshl_add_u64 v[10:11], s[60:61], 0, v[22:23]
	s_movk_i32 s12, 0xf800
	v_lshl_add_u64 v[10:11], v[0:1], 1, v[10:11]
	s_mov_b32 s13, -1
	v_lshl_add_u64 v[10:11], v[10:11], 0, s[12:13]
	s_mov_b64 s[58:59], 0

.LBB0_1035:
.LBB0_1036:
	s_andn2_saveexec_b64 s[56:57], s[56:57]
	v_lshlrev_b64 v[10:11], 20, v[122:123]
	v_lshl_add_u64 v[10:11], s[40:41], 0, v[10:11]
	v_lshl_add_u64 v[10:11], v[10:11], 0, v[24:25]
	v_mov_b32_e32 v139, v1
	v_lshl_add_u64 v[10:11], v[10:11], 0, v[138:139]
	s_or_b64 exec, exec, s[56:57]
	v_pk_mul_f32 v[12:13], v[4:5], v[18:19] op_sel_hi:[1,0]
	v_pk_mul_f32 v[4:5], v[2:3], v[18:19] op_sel_hi:[1,0]
	s_andn2_b64 vcc, exec, s[54:55]
	s_mov_b64 s[54:55], -1
	v_pk_mul_f32 v[8:9], v[8:9], v[18:19] op_sel_hi:[1,0]
	v_pk_mul_f32 v[6:7], v[6:7], v[18:19] op_sel_hi:[1,0]
	s_nop 0
	v_cvt_pk_bf16_f32 v2, v6, v7
	v_cvt_pk_bf16_f32 v3, v8, v9
	v_cvt_pk_bf16_f32 v4, v4, v5
	v_cvt_pk_bf16_f32 v5, v12, v13
	global_store_dwordx4 v[10:11], v[2:5], off sc1
	s_cbranch_vccnz .LBB0_846
	s_andn2_b64 vcc, exec, s[6:7]
	s_cbranch_vccnz .LBB0_845
	s_barrier
	s_branch .LBB0_845
